# GEMM K-loops: LDS fragment-read base addresses formed once before each K-loop instead of a VALU add per iteration
# speedup vs baseline: 1.0145x; 1.0021x over previous
; #define PG8_STAGE(bufoff, gbase, voff) do { _Pragma("unroll") for (int _i = 0; _i < 2; ++_i) \
;         __builtin_amdgcn_global_load_lds((const unsigned*)((const char*)(gbase) + (voff)[_i]), (LAS unsigned*)(lds + (bufoff) + ldsw + _i * 8192), 16, 0, 0); } while (0)
; #define PG8_LDA(dst, b, h) do { _Pragma("unroll") for (int m = 0; m < 4; ++m) _Pragma("unroll") for (int k = 0; k < 2; ++k) dst[m][k] = *(const LAS bf16x8*)(lds + PG8_SA(b, h) + aoff + m * 2048 + k * 1024); } while (0)
; #define PG8_LDB(dst, b, h) do { _Pragma("unroll") for (int n = 0; n < 2; ++n) _Pragma("unroll") for (int k = 0; k < 2; ++k) dst[n][k] = *(const LAS bf16x8*)(lds + PG8_SB(b, h) + boff + n * 2048 + k * 1024); } while (0)
; #define PG8_MMA(ai, bj, At, Bt) do { __builtin_amdgcn_s_setprio(1); _Pragma("unroll") for (int m = 0; m < 4; ++m) _Pragma("unroll") for (int n = 0; n < 2; ++n) _Pragma("unroll") for (int k = 0; k < 2; ++k) \
;         acc[ai][bj][m][n] = __builtin_amdgcn_mfma_f32_16x16x32_bf16(Bt[n][k], At[m][k], acc[ai][bj][m][n], 0, 0, 0); __builtin_amdgcn_s_setprio(0); } while (0)
; template <class EpiT, class Sched>
; __device__ __forceinline__ void gemm_phase(LAS unsigned char* lds, const Gemm g, const Sched& S, const EpiT& E, int wv) {
;     ...
;         const bool has_next = S.next(ui + 1, nxt);
;         const char* nA = has_next ? (const char*)g.A + (size_t)nxt.pm * tstepA + (size_t)(nxt.pn >> g.zshift) * g.zA : cA; const char* nB = has_next ? (const char*)g.Bt + (size_t)nxt.pn * tstepB : cB;
;         for (int t = 0; t < nt; t += 2) {
;             const bool last = (t == nt - 2);
;             const char* a1 = cA + (size_t)(t + 1) * kstep;
;             const char* a2 = last ? nA : cA + (size_t)(t + 2) * kstep; const char* b2 = last ? nB : cB + (size_t)(t + 2) * kstep;
;             const char* a3 = a2 + kstep; const char* b3 = b2 + kstep;
;             PG8_LDB(B0, 0, 0); PG8_LDB(B1, 0, 1); PG8_SCHED; PG8_LDA(At, 0, 0); PG8_STAGE(PG8_SA(1, 1), a1 + hstepA, voffA);
;             PG8_WAIT_V(8); PG8_WAIT_L(0); PG8_BAR; PG8_MMA(0, 0, At, B0); PG8_MMA(0, 1, At, B1); PG8_BAR; PG8_SCHED;
;     ...
; #pragma unroll
;         for (int a = 0; a < 2; ++a)
; #pragma unroll
;             for (int b = 0; b < 2; ++b)
; #pragma unroll
;                 for (int m = 0; m < 4; ++m)
; #pragma unroll
;                     for (int n = 0; n < 2; ++n) acc[a][b][m][n] = (f32x4){0.f, 0.f, 0.f, 0.f};
.LBB0_245:
	s_ashr_i32 s19, s18, 31
	s_lshl_b64 s[20:21], s[18:19], 19
	s_add_u32 s20, s33, s20
	s_addc_u32 s21, s34, s21
	s_and_b64 s[22:23], s[2:3], exec
	s_cselect_b32 s19, s21, s27
	s_cselect_b32 s25, s20, s26
	s_ashr_i32 s17, s16, 31
	s_lshl_b64 s[22:23], s[16:17], 19
	s_add_u32 s22, s0, s22
	s_addc_u32 s23, s1, s23
	s_and_b64 s[30:31], s[2:3], exec
	s_cselect_b32 s17, s23, s29
	s_cselect_b32 s46, s22, s28
	s_add_u32 s26, s26, 0x40080
	s_addc_u32 s27, s27, 0
	s_add_u32 s47, s28, 0x100
	v_mov_b32_e32 v0, 0
	s_addc_u32 s48, s29, 0
	s_mov_b32 s49, -2
	v_mov_b32_e32 v1, v0
	v_mov_b32_e32 v2, v0
	v_mov_b32_e32 v3, v0
	v_mov_b32_e32 v4, v0
	v_mov_b32_e32 v5, v0
	v_mov_b32_e32 v6, v0
	v_mov_b32_e32 v7, v0
	v_mov_b32_e32 v8, v0
	v_mov_b32_e32 v9, v0
	v_mov_b32_e32 v10, v0
	v_mov_b32_e32 v11, v0
	v_mov_b32_e32 v12, v0
	v_mov_b32_e32 v13, v0
	v_mov_b32_e32 v14, v0
	v_mov_b32_e32 v15, v0
	v_mov_b32_e32 v16, v0
	v_mov_b32_e32 v17, v0
	v_mov_b32_e32 v18, v0
	v_mov_b32_e32 v19, v0
	v_mov_b32_e32 v20, v0
	v_mov_b32_e32 v21, v0
	v_mov_b32_e32 v22, v0
	v_mov_b32_e32 v23, v0
	v_mov_b32_e32 v24, v0
	v_mov_b32_e32 v25, v0
	v_mov_b32_e32 v26, v0
	v_mov_b32_e32 v27, v0
	v_mov_b32_e32 v28, v0
	v_mov_b32_e32 v29, v0
	v_mov_b32_e32 v30, v0
	v_mov_b32_e32 v31, v0
	v_mov_b32_e32 v60, v0
	v_mov_b32_e32 v61, v0
	v_mov_b32_e32 v62, v0
	v_mov_b32_e32 v63, v0
	v_mov_b32_e32 v68, v0
	v_mov_b32_e32 v69, v0
	v_mov_b32_e32 v70, v0
	v_mov_b32_e32 v71, v0
	v_mov_b32_e32 v72, v0
	v_mov_b32_e32 v73, v0
	v_mov_b32_e32 v74, v0
	v_mov_b32_e32 v75, v0
	v_mov_b32_e32 v76, v0
	v_mov_b32_e32 v77, v0
	v_mov_b32_e32 v78, v0
	v_mov_b32_e32 v79, v0
	v_mov_b32_e32 v80, v0
	v_mov_b32_e32 v81, v0
	v_mov_b32_e32 v82, v0
	v_mov_b32_e32 v83, v0
	v_mov_b32_e32 v84, v0
	v_mov_b32_e32 v85, v0
	v_mov_b32_e32 v86, v0
	v_mov_b32_e32 v87, v0
	v_mov_b32_e32 v88, v0
	v_mov_b32_e32 v89, v0
	v_mov_b32_e32 v90, v0
	v_mov_b32_e32 v91, v0
	v_mov_b32_e32 v92, v0
	v_mov_b32_e32 v93, v0
	v_mov_b32_e32 v94, v0
	v_mov_b32_e32 v95, v0
	v_mov_b32_e32 v32, v0
	v_mov_b32_e32 v33, v0
	v_mov_b32_e32 v34, v0
	v_mov_b32_e32 v35, v0
	v_mov_b32_e32 v36, v0
	v_mov_b32_e32 v37, v0
	v_mov_b32_e32 v38, v0
	v_mov_b32_e32 v39, v0
	v_mov_b32_e32 v40, v0
	v_mov_b32_e32 v41, v0
	v_mov_b32_e32 v42, v0
	v_mov_b32_e32 v43, v0
	v_mov_b32_e32 v44, v0
	v_mov_b32_e32 v45, v0
	v_mov_b32_e32 v46, v0
	v_mov_b32_e32 v47, v0
	v_mov_b32_e32 v48, v0
	v_mov_b32_e32 v49, v0
	v_mov_b32_e32 v50, v0
	v_mov_b32_e32 v51, v0
	v_mov_b32_e32 v52, v0
	v_mov_b32_e32 v53, v0
	v_mov_b32_e32 v54, v0
	v_mov_b32_e32 v55, v0
	v_mov_b32_e32 v56, v0
	v_mov_b32_e32 v57, v0
	v_mov_b32_e32 v58, v0
	v_mov_b32_e32 v59, v0
	v_mov_b32_e32 v64, v0
	v_mov_b32_e32 v65, v0
	v_mov_b32_e32 v66, v0
	v_mov_b32_e32 v67, v0
	v_mov_b32_e32 v96, v0
	v_mov_b32_e32 v97, v0
	v_mov_b32_e32 v98, v0
	v_mov_b32_e32 v99, v0
	v_mov_b32_e32 v100, v0
	v_mov_b32_e32 v101, v0
	v_mov_b32_e32 v102, v0
	v_mov_b32_e32 v103, v0
	v_mov_b32_e32 v104, v0
	v_mov_b32_e32 v105, v0
	v_mov_b32_e32 v106, v0
	v_mov_b32_e32 v107, v0
	v_mov_b32_e32 v108, v0
	v_mov_b32_e32 v109, v0
	v_mov_b32_e32 v110, v0
	v_mov_b32_e32 v111, v0
	v_mov_b32_e32 v112, v0
	v_mov_b32_e32 v113, v0
	v_mov_b32_e32 v114, v0
	v_mov_b32_e32 v115, v0
	v_mov_b32_e32 v116, v0
	v_mov_b32_e32 v117, v0
	v_mov_b32_e32 v118, v0
	v_mov_b32_e32 v119, v0
	v_mov_b32_e32 v120, v0
	v_mov_b32_e32 v121, v0
	v_mov_b32_e32 v122, v0
	v_mov_b32_e32 v123, v0
	v_mov_b32_e32 v124, v0
	v_mov_b32_e32 v125, v0
	v_mov_b32_e32 v126, v0
	v_mov_b32_e32 v127, v0
	v_add_u32_e32 v250, 0x10000, v164
	v_add_u32_e32 v251, 0x14000, v164
	v_add_u32_e32 v252, 0x18000, v164
	v_add_u32_e32 v253, 0x1c000, v164
.LBB0_246:
	s_add_u32 s28, s26, 0xfffc0080
	s_addc_u32 s29, s27, -1
	s_add_i32 s50, 0, 0x10000
	s_cmp_eq_u32 s49, 12
	s_cselect_b32 s31, s19, s29
	s_cselect_b32 s30, s25, s28
	s_cselect_b32 s29, s17, s48
	s_cselect_b32 s28, s46, s47
	s_add_i32 s52, 0, 0x14000
	ds_read_b128 v[128:131], v250
	ds_read_b128 v[132:135], v250 offset:1024
	ds_read_b128 v[146:149], v250 offset:2048
	ds_read_b128 v[150:153], v250 offset:3072
	ds_read_b128 v[154:157], v251
	ds_read_b128 v[158:161], v251 offset:1024
	ds_read_b128 v[166:169], v251 offset:2048
	ds_read_b128 v[170:173], v251 offset:3072
	s_add_i32 m0, s36, 0xc000
	ds_read_b128 v[174:177], v165
	ds_read_b128 v[178:181], v165 offset:1024
	ds_read_b128 v[182:185], v165 offset:2048
	ds_read_b128 v[186:189], v165 offset:3072
	ds_read_b128 v[204:207], v165 offset:4096
	ds_read_b128 v[208:211], v165 offset:5120
	ds_read_b128 v[212:215], v165 offset:6144
	ds_read_b128 v[216:219], v165 offset:7168
	global_load_lds_dwordx4 v142, s[26:27]
	s_add_i32 m0, s36, 0xe000
	s_nop 0
	global_load_lds_dwordx4 v144, s[26:27]
	s_waitcnt vmcnt(8)
	s_waitcnt lgkmcnt(0)
	s_barrier
; #define PG8_STAGE(bufoff, gbase, voff) do { _Pragma("unroll") for (int _i = 0; _i < 2; ++_i) \
;         __builtin_amdgcn_global_load_lds((const unsigned*)((const char*)(gbase) + (voff)[_i]), (LAS unsigned*)(lds + (bufoff) + ldsw + _i * 8192), 16, 0, 0); } while (0)
; #define PG8_LDA(dst, b, h) do { _Pragma("unroll") for (int m = 0; m < 4; ++m) _Pragma("unroll") for (int k = 0; k < 2; ++k) dst[m][k] = *(const LAS bf16x8*)(lds + PG8_SA(b, h) + aoff + m * 2048 + k * 1024); } while (0)
; #define PG8_LDB(dst, b, h) do { _Pragma("unroll") for (int n = 0; n < 2; ++n) _Pragma("unroll") for (int k = 0; k < 2; ++k) dst[n][k] = *(const LAS bf16x8*)(lds + PG8_SB(b, h) + boff + n * 2048 + k * 1024); } while (0)
; #define PG8_MMA(ai, bj, At, Bt) do { __builtin_amdgcn_s_setprio(1); _Pragma("unroll") for (int m = 0; m < 4; ++m) _Pragma("unroll") for (int n = 0; n < 2; ++n) _Pragma("unroll") for (int k = 0; k < 2; ++k) \
;         acc[ai][bj][m][n] = __builtin_amdgcn_mfma_f32_16x16x32_bf16(Bt[n][k], At[m][k], acc[ai][bj][m][n], 0, 0, 0); __builtin_amdgcn_s_setprio(0); } while (0)
; #define PG8_WAIT_V(n) asm volatile("s_waitcnt vmcnt(" #n ")" ::: "memory")
; #define PG8_WAIT_L(n) asm volatile("s_waitcnt lgkmcnt(" #n ")" ::: "memory")
; #define PG8_BAR __builtin_amdgcn_s_barrier()
; #define PG8_SCHED __builtin_amdgcn_sched_barrier(0)
; template <class EpiT, class Sched>
; __device__ __forceinline__ void gemm_phase(LAS unsigned char* lds, const Gemm g, const Sched& S, const EpiT& E, int wv) {
;     ...
;             PG8_LDB(B0, 0, 0); PG8_LDB(B1, 0, 1); PG8_SCHED; PG8_LDA(At, 0, 0); PG8_STAGE(PG8_SA(1, 1), a1 + hstepA, voffA);
;             PG8_WAIT_V(8); PG8_WAIT_L(0); PG8_BAR; PG8_MMA(0, 0, At, B0); PG8_MMA(0, 1, At, B1); PG8_BAR; PG8_SCHED;
;             PG8_LDA(At, 0, 1); PG8_STAGE(PG8_SB(0, 0), b2, voffB); PG8_STAGE(PG8_SB(0, 1), b2 + hstepB, voffB); PG8_STAGE(PG8_SA(0, 0), a2, voffA);
;             PG8_WAIT_V(8); PG8_WAIT_L(0); PG8_BAR; PG8_MMA(1, 0, At, B0); PG8_MMA(1, 1, At, B1); PG8_BAR; PG8_SCHED;
	s_setprio 1
	s_waitcnt lgkmcnt(0)
	v_mfma_f32_16x16x32_bf16 v[124:127], v[128:131], v[174:177], v[124:127]
	v_mfma_f32_16x16x32_bf16 v[120:123], v[146:149], v[174:177], v[120:123]
	v_mfma_f32_16x16x32_bf16 v[116:119], v[128:131], v[182:185], v[116:119]
	v_mfma_f32_16x16x32_bf16 v[112:115], v[146:149], v[182:185], v[112:115]
	v_mfma_f32_16x16x32_bf16 v[108:111], v[128:131], v[204:207], v[108:111]
	v_mfma_f32_16x16x32_bf16 v[104:107], v[146:149], v[204:207], v[104:107]
	v_mfma_f32_16x16x32_bf16 v[100:103], v[128:131], v[212:215], v[100:103]
	v_mfma_f32_16x16x32_bf16 v[96:99], v[146:149], v[212:215], v[96:99]
	v_mfma_f32_16x16x32_bf16 v[124:127], v[132:135], v[178:181], v[124:127]
	v_mfma_f32_16x16x32_bf16 v[120:123], v[150:153], v[178:181], v[120:123]
	v_mfma_f32_16x16x32_bf16 v[116:119], v[132:135], v[186:189], v[116:119]
	v_mfma_f32_16x16x32_bf16 v[112:115], v[150:153], v[186:189], v[112:115]
	v_mfma_f32_16x16x32_bf16 v[108:111], v[132:135], v[208:211], v[108:111]
	v_mfma_f32_16x16x32_bf16 v[104:107], v[150:153], v[208:211], v[104:107]
	v_mfma_f32_16x16x32_bf16 v[100:103], v[132:135], v[216:219], v[100:103]
	v_mfma_f32_16x16x32_bf16 v[96:99], v[150:153], v[216:219], v[96:99]
	s_setprio 0
	s_setprio 1
	v_mfma_f32_16x16x32_bf16 v[64:67], v[154:157], v[174:177], v[64:67]
	v_mfma_f32_16x16x32_bf16 v[56:59], v[166:169], v[174:177], v[56:59]
	v_mfma_f32_16x16x32_bf16 v[52:55], v[154:157], v[182:185], v[52:55]
	v_mfma_f32_16x16x32_bf16 v[48:51], v[166:169], v[182:185], v[48:51]
	v_mfma_f32_16x16x32_bf16 v[44:47], v[154:157], v[204:207], v[44:47]
	v_mfma_f32_16x16x32_bf16 v[40:43], v[166:169], v[204:207], v[40:43]
	v_mfma_f32_16x16x32_bf16 v[36:39], v[154:157], v[212:215], v[36:39]
	v_mfma_f32_16x16x32_bf16 v[32:35], v[166:169], v[212:215], v[32:35]
	v_mfma_f32_16x16x32_bf16 v[64:67], v[158:161], v[178:181], v[64:67]
	v_mfma_f32_16x16x32_bf16 v[56:59], v[170:173], v[178:181], v[56:59]
	v_mfma_f32_16x16x32_bf16 v[52:55], v[158:161], v[186:189], v[52:55]
	v_mfma_f32_16x16x32_bf16 v[48:51], v[170:173], v[186:189], v[48:51]
	v_mfma_f32_16x16x32_bf16 v[44:47], v[158:161], v[208:211], v[44:47]
	v_mfma_f32_16x16x32_bf16 v[40:43], v[170:173], v[208:211], v[40:43]
	v_mfma_f32_16x16x32_bf16 v[36:39], v[158:161], v[216:219], v[36:39]
	v_mfma_f32_16x16x32_bf16 v[32:35], v[170:173], v[216:219], v[32:35]
	s_setprio 0
	s_barrier
	s_add_i32 s50, s50, s35
	s_add_u32 s54, s28, s92
	s_addc_u32 s55, s29, s93
	s_mov_b32 m0, s50
	ds_read_b128 v[174:177], v165 offset:16384
	ds_read_b128 v[178:181], v165 offset:17408
	ds_read_b128 v[182:185], v165 offset:18432
	ds_read_b128 v[186:189], v165 offset:19456
	ds_read_b128 v[204:207], v165 offset:20480
	ds_read_b128 v[208:211], v165 offset:21504
	ds_read_b128 v[212:215], v165 offset:22528
	ds_read_b128 v[216:219], v165 offset:23552
	global_load_lds_dwordx4 v192, s[28:29]
	s_add_i32 m0, s50, 0x2000
	s_add_u32 s50, s28, 0x40000
	s_addc_u32 s51, s29, 0
	s_add_i32 s52, s52, s35
	global_load_lds_dwordx4 v140, s[28:29]
	s_mov_b32 m0, s52
	s_nop 0
	global_load_lds_dwordx4 v192, s[50:51]
	s_add_i32 m0, s52, 0x2000
	s_nop 0
	global_load_lds_dwordx4 v140, s[50:51]
	s_add_u32 s56, s30, s92
	s_addc_u32 s57, s31, s93
	s_mov_b32 m0, s36
	s_nop 0
	global_load_lds_dwordx4 v136, s[30:31]
	s_mov_b32 m0, s37
	s_nop 0
	global_load_lds_dwordx4 v138, s[30:31]
	s_waitcnt vmcnt(8)
	s_waitcnt lgkmcnt(0)
	s_barrier
	s_setprio 1
	s_waitcnt lgkmcnt(0)
	v_mfma_f32_16x16x32_bf16 v[92:95], v[128:131], v[174:177], v[92:95]
	v_mfma_f32_16x16x32_bf16 v[88:91], v[146:149], v[174:177], v[88:91]
	v_mfma_f32_16x16x32_bf16 v[84:87], v[128:131], v[182:185], v[84:87]
	v_mfma_f32_16x16x32_bf16 v[80:83], v[146:149], v[182:185], v[80:83]
	v_mfma_f32_16x16x32_bf16 v[76:79], v[128:131], v[204:207], v[76:79]
	v_mfma_f32_16x16x32_bf16 v[72:75], v[146:149], v[204:207], v[72:75]
	v_mfma_f32_16x16x32_bf16 v[68:71], v[128:131], v[212:215], v[68:71]
	v_mfma_f32_16x16x32_bf16 v[60:63], v[146:149], v[212:215], v[60:63]
	v_mfma_f32_16x16x32_bf16 v[92:95], v[132:135], v[178:181], v[92:95]
	v_mfma_f32_16x16x32_bf16 v[88:91], v[150:153], v[178:181], v[88:91]
	v_mfma_f32_16x16x32_bf16 v[84:87], v[132:135], v[186:189], v[84:87]
	v_mfma_f32_16x16x32_bf16 v[80:83], v[150:153], v[186:189], v[80:83]
	v_mfma_f32_16x16x32_bf16 v[76:79], v[132:135], v[208:211], v[76:79]
	v_mfma_f32_16x16x32_bf16 v[72:75], v[150:153], v[208:211], v[72:75]
	v_mfma_f32_16x16x32_bf16 v[68:71], v[132:135], v[216:219], v[68:71]
	v_mfma_f32_16x16x32_bf16 v[60:63], v[150:153], v[216:219], v[60:63]
	s_setprio 0
	s_setprio 1
	v_mfma_f32_16x16x32_bf16 v[28:31], v[154:157], v[174:177], v[28:31]
	v_mfma_f32_16x16x32_bf16 v[24:27], v[166:169], v[174:177], v[24:27]
	v_mfma_f32_16x16x32_bf16 v[20:23], v[154:157], v[182:185], v[20:23]
	v_mfma_f32_16x16x32_bf16 v[16:19], v[166:169], v[182:185], v[16:19]
	v_mfma_f32_16x16x32_bf16 v[12:15], v[154:157], v[204:207], v[12:15]
	v_mfma_f32_16x16x32_bf16 v[8:11], v[166:169], v[204:207], v[8:11]
	v_mfma_f32_16x16x32_bf16 v[4:7], v[154:157], v[212:215], v[4:7]
	v_mfma_f32_16x16x32_bf16 v[0:3], v[166:169], v[212:215], v[0:3]
	v_mfma_f32_16x16x32_bf16 v[28:31], v[158:161], v[178:181], v[28:31]
	v_mfma_f32_16x16x32_bf16 v[24:27], v[170:173], v[178:181], v[24:27]
	v_mfma_f32_16x16x32_bf16 v[20:23], v[158:161], v[186:189], v[20:23]
	v_mfma_f32_16x16x32_bf16 v[16:19], v[170:173], v[186:189], v[16:19]
	v_mfma_f32_16x16x32_bf16 v[12:15], v[158:161], v[208:211], v[12:15]
	v_mfma_f32_16x16x32_bf16 v[8:11], v[170:173], v[208:211], v[8:11]
	v_mfma_f32_16x16x32_bf16 v[4:7], v[158:161], v[216:219], v[4:7]
	v_mfma_f32_16x16x32_bf16 v[0:3], v[170:173], v[216:219], v[0:3]
	s_setprio 0
	s_barrier
; #define PG8_STAGE(bufoff, gbase, voff) do { _Pragma("unroll") for (int _i = 0; _i < 2; ++_i) \
;         __builtin_amdgcn_global_load_lds((const unsigned*)((const char*)(gbase) + (voff)[_i]), (LAS unsigned*)(lds + (bufoff) + ldsw + _i * 8192), 16, 0, 0); } while (0)
; #define PG8_LDA(dst, b, h) do { _Pragma("unroll") for (int m = 0; m < 4; ++m) _Pragma("unroll") for (int k = 0; k < 2; ++k) dst[m][k] = *(const LAS bf16x8*)(lds + PG8_SA(b, h) + aoff + m * 2048 + k * 1024); } while (0)
; #define PG8_LDB(dst, b, h) do { _Pragma("unroll") for (int n = 0; n < 2; ++n) _Pragma("unroll") for (int k = 0; k < 2; ++k) dst[n][k] = *(const LAS bf16x8*)(lds + PG8_SB(b, h) + boff + n * 2048 + k * 1024); } while (0)
; #define PG8_MMA(ai, bj, At, Bt) do { __builtin_amdgcn_s_setprio(1); _Pragma("unroll") for (int m = 0; m < 4; ++m) _Pragma("unroll") for (int n = 0; n < 2; ++n) _Pragma("unroll") for (int k = 0; k < 2; ++k) \
;         acc[ai][bj][m][n] = __builtin_amdgcn_mfma_f32_16x16x32_bf16(Bt[n][k], At[m][k], acc[ai][bj][m][n], 0, 0, 0); __builtin_amdgcn_s_setprio(0); } while (0)
; #define PG8_WAIT_V(n) asm volatile("s_waitcnt vmcnt(" #n ")" ::: "memory")
; #define PG8_WAIT_L(n) asm volatile("s_waitcnt lgkmcnt(" #n ")" ::: "memory")
; #define PG8_BAR __builtin_amdgcn_s_barrier()
; #define PG8_SCHED __builtin_amdgcn_sched_barrier(0)
; template <class EpiT, class Sched>
; __device__ __forceinline__ void gemm_phase(LAS unsigned char* lds, const Gemm g, const Sched& S, const EpiT& E, int wv) {
;     ...
;             PG8_LDB(B0, 1, 0); PG8_LDB(B1, 1, 1); PG8_SCHED; PG8_LDA(At, 1, 0); PG8_STAGE(PG8_SA(0, 1), a2 + hstepA, voffA);
;             PG8_WAIT_V(8); PG8_WAIT_L(0); PG8_BAR; PG8_MMA(0, 0, At, B0); PG8_MMA(0, 1, At, B1); PG8_BAR; PG8_SCHED;
;             PG8_LDA(At, 1, 1); PG8_STAGE(PG8_SB(1, 0), b3, voffB); PG8_STAGE(PG8_SB(1, 1), b3 + hstepB, voffB); PG8_STAGE(PG8_SA(1, 0), a3, voffA);
;             PG8_WAIT_V(8); PG8_WAIT_L(0); PG8_BAR; PG8_MMA(1, 0, At, B0); PG8_MMA(1, 1, At, B1); PG8_BAR; PG8_SCHED;
;         }
	s_add_i32 s50, 0, 0x18000
	s_add_i32 s51, 0, 0x1c000
	ds_read_b128 v[128:131], v252
	ds_read_b128 v[132:135], v252 offset:1024
	ds_read_b128 v[146:149], v252 offset:2048
	ds_read_b128 v[150:153], v252 offset:3072
	ds_read_b128 v[154:157], v253
	ds_read_b128 v[158:161], v253 offset:1024
	ds_read_b128 v[166:169], v253 offset:2048
	ds_read_b128 v[170:173], v253 offset:3072
	s_add_u32 s30, s30, 0x40000
	s_addc_u32 s31, s31, 0
	s_mov_b32 m0, s38
	ds_read_b128 v[174:177], v165 offset:32768
	ds_read_b128 v[178:181], v165 offset:33792
	ds_read_b128 v[182:185], v165 offset:34816
	ds_read_b128 v[186:189], v165 offset:35840
	ds_read_b128 v[204:207], v165 offset:36864
	ds_read_b128 v[208:211], v165 offset:37888
	ds_read_b128 v[212:215], v165 offset:38912
	ds_read_b128 v[216:219], v165 offset:39936
	global_load_lds_dwordx4 v136, s[30:31]
	s_mov_b32 m0, s39
	s_nop 0
	global_load_lds_dwordx4 v138, s[30:31]
	s_waitcnt vmcnt(8)
	s_waitcnt lgkmcnt(0)
	s_barrier
	s_setprio 1
	s_waitcnt lgkmcnt(0)
	v_mfma_f32_16x16x32_bf16 v[124:127], v[128:131], v[174:177], v[124:127]
	v_mfma_f32_16x16x32_bf16 v[120:123], v[146:149], v[174:177], v[120:123]
	v_mfma_f32_16x16x32_bf16 v[116:119], v[128:131], v[182:185], v[116:119]
	v_mfma_f32_16x16x32_bf16 v[112:115], v[146:149], v[182:185], v[112:115]
	v_mfma_f32_16x16x32_bf16 v[108:111], v[128:131], v[204:207], v[108:111]
	v_mfma_f32_16x16x32_bf16 v[104:107], v[146:149], v[204:207], v[104:107]
	v_mfma_f32_16x16x32_bf16 v[100:103], v[128:131], v[212:215], v[100:103]
	v_mfma_f32_16x16x32_bf16 v[96:99], v[146:149], v[212:215], v[96:99]
	v_mfma_f32_16x16x32_bf16 v[124:127], v[132:135], v[178:181], v[124:127]
	v_mfma_f32_16x16x32_bf16 v[120:123], v[150:153], v[178:181], v[120:123]
	v_mfma_f32_16x16x32_bf16 v[116:119], v[132:135], v[186:189], v[116:119]
	v_mfma_f32_16x16x32_bf16 v[112:115], v[150:153], v[186:189], v[112:115]
	v_mfma_f32_16x16x32_bf16 v[108:111], v[132:135], v[208:211], v[108:111]
	v_mfma_f32_16x16x32_bf16 v[104:107], v[150:153], v[208:211], v[104:107]
	v_mfma_f32_16x16x32_bf16 v[100:103], v[132:135], v[216:219], v[100:103]
	v_mfma_f32_16x16x32_bf16 v[96:99], v[150:153], v[216:219], v[96:99]
	s_setprio 0
	s_setprio 1
	v_mfma_f32_16x16x32_bf16 v[64:67], v[154:157], v[174:177], v[64:67]
	v_mfma_f32_16x16x32_bf16 v[56:59], v[166:169], v[174:177], v[56:59]
	v_mfma_f32_16x16x32_bf16 v[52:55], v[154:157], v[182:185], v[52:55]
	v_mfma_f32_16x16x32_bf16 v[48:51], v[166:169], v[182:185], v[48:51]
	v_mfma_f32_16x16x32_bf16 v[44:47], v[154:157], v[204:207], v[44:47]
	v_mfma_f32_16x16x32_bf16 v[40:43], v[166:169], v[204:207], v[40:43]
	v_mfma_f32_16x16x32_bf16 v[36:39], v[154:157], v[212:215], v[36:39]
	v_mfma_f32_16x16x32_bf16 v[32:35], v[166:169], v[212:215], v[32:35]
	v_mfma_f32_16x16x32_bf16 v[64:67], v[158:161], v[178:181], v[64:67]
	v_mfma_f32_16x16x32_bf16 v[56:59], v[170:173], v[178:181], v[56:59]
	v_mfma_f32_16x16x32_bf16 v[52:55], v[158:161], v[186:189], v[52:55]
	v_mfma_f32_16x16x32_bf16 v[48:51], v[170:173], v[186:189], v[48:51]
	v_mfma_f32_16x16x32_bf16 v[44:47], v[158:161], v[208:211], v[44:47]
	v_mfma_f32_16x16x32_bf16 v[40:43], v[170:173], v[208:211], v[40:43]
	v_mfma_f32_16x16x32_bf16 v[36:39], v[158:161], v[216:219], v[36:39]
	v_mfma_f32_16x16x32_bf16 v[32:35], v[170:173], v[216:219], v[32:35]
	s_setprio 0
	s_barrier
	s_add_i32 s30, s50, s35
	s_mov_b32 m0, s30
	ds_read_b128 v[174:177], v165 offset:49152
	ds_read_b128 v[178:181], v165 offset:50176
	ds_read_b128 v[182:185], v165 offset:51200
	ds_read_b128 v[186:189], v165 offset:52224
	ds_read_b128 v[204:207], v165 offset:53248
	ds_read_b128 v[208:211], v165 offset:54272
	ds_read_b128 v[212:215], v165 offset:55296
	ds_read_b128 v[216:219], v165 offset:56320
	global_load_lds_dwordx4 v192, s[54:55]
	s_add_i32 m0, s30, 0x2000
	s_add_u32 s28, s28, 0x40080
	s_addc_u32 s29, s29, 0
	s_add_i32 s30, s51, s35
	global_load_lds_dwordx4 v140, s[54:55]
	s_mov_b32 m0, s30
	s_nop 0
	global_load_lds_dwordx4 v192, s[28:29]
	s_add_i32 m0, s30, 0x2000
	s_nop 0
	global_load_lds_dwordx4 v140, s[28:29]
	s_mov_b32 m0, s40
	s_nop 0
	global_load_lds_dwordx4 v136, s[56:57]
	s_mov_b32 m0, s41
	s_nop 0
	global_load_lds_dwordx4 v138, s[56:57]
	s_waitcnt vmcnt(8)
	s_waitcnt lgkmcnt(0)
	s_barrier
	s_setprio 1
	s_waitcnt lgkmcnt(0)
	v_mfma_f32_16x16x32_bf16 v[92:95], v[128:131], v[174:177], v[92:95]
	v_mfma_f32_16x16x32_bf16 v[88:91], v[146:149], v[174:177], v[88:91]
	v_mfma_f32_16x16x32_bf16 v[84:87], v[128:131], v[182:185], v[84:87]
	v_mfma_f32_16x16x32_bf16 v[80:83], v[146:149], v[182:185], v[80:83]
	v_mfma_f32_16x16x32_bf16 v[76:79], v[128:131], v[204:207], v[76:79]
	v_mfma_f32_16x16x32_bf16 v[72:75], v[146:149], v[204:207], v[72:75]
	v_mfma_f32_16x16x32_bf16 v[68:71], v[128:131], v[212:215], v[68:71]
	v_mfma_f32_16x16x32_bf16 v[60:63], v[146:149], v[212:215], v[60:63]
	v_mfma_f32_16x16x32_bf16 v[92:95], v[132:135], v[178:181], v[92:95]
	v_mfma_f32_16x16x32_bf16 v[88:91], v[150:153], v[178:181], v[88:91]
	v_mfma_f32_16x16x32_bf16 v[84:87], v[132:135], v[186:189], v[84:87]
	v_mfma_f32_16x16x32_bf16 v[80:83], v[150:153], v[186:189], v[80:83]
	v_mfma_f32_16x16x32_bf16 v[76:79], v[132:135], v[208:211], v[76:79]
	v_mfma_f32_16x16x32_bf16 v[72:75], v[150:153], v[208:211], v[72:75]
	v_mfma_f32_16x16x32_bf16 v[68:71], v[132:135], v[216:219], v[68:71]
	v_mfma_f32_16x16x32_bf16 v[60:63], v[150:153], v[216:219], v[60:63]
	s_setprio 0
	s_setprio 1
	v_mfma_f32_16x16x32_bf16 v[28:31], v[154:157], v[174:177], v[28:31]
	v_mfma_f32_16x16x32_bf16 v[24:27], v[166:169], v[174:177], v[24:27]
	v_mfma_f32_16x16x32_bf16 v[20:23], v[154:157], v[182:185], v[20:23]
	v_mfma_f32_16x16x32_bf16 v[16:19], v[166:169], v[182:185], v[16:19]
	v_mfma_f32_16x16x32_bf16 v[12:15], v[154:157], v[204:207], v[12:15]
	v_mfma_f32_16x16x32_bf16 v[8:11], v[166:169], v[204:207], v[8:11]
	v_mfma_f32_16x16x32_bf16 v[4:7], v[154:157], v[212:215], v[4:7]
	v_mfma_f32_16x16x32_bf16 v[0:3], v[166:169], v[212:215], v[0:3]
	v_mfma_f32_16x16x32_bf16 v[28:31], v[158:161], v[178:181], v[28:31]
	v_mfma_f32_16x16x32_bf16 v[24:27], v[170:173], v[178:181], v[24:27]
	v_mfma_f32_16x16x32_bf16 v[20:23], v[158:161], v[186:189], v[20:23]
	v_mfma_f32_16x16x32_bf16 v[16:19], v[170:173], v[186:189], v[16:19]
	v_mfma_f32_16x16x32_bf16 v[12:15], v[158:161], v[208:211], v[12:15]
	v_mfma_f32_16x16x32_bf16 v[8:11], v[170:173], v[208:211], v[8:11]
	v_mfma_f32_16x16x32_bf16 v[4:7], v[158:161], v[216:219], v[4:7]
	v_mfma_f32_16x16x32_bf16 v[0:3], v[170:173], v[216:219], v[0:3]
	s_setprio 0
	s_barrier
	s_add_i32 s49, s49, 2
	s_add_u32 s26, s26, 0x100
	s_addc_u32 s27, s27, 0
	s_add_u32 s47, s47, 0x100
	s_addc_u32 s48, s48, 0
	s_cmp_gt_u32 s49, 13
	s_cbranch_scc0 .LBB0_246
	s_and_b64 vcc, exec, s[12:13]
	s_cbranch_vccz .LBB0_249
	s_barrier

; template <class EpiT, class Sched>
; __device__ __forceinline__ void gemm_phase(LAS unsigned char* lds, const Gemm g, const Sched& S, const EpiT& E, int wv) {
;     ...
;     f32x4 acc[2][2][4][2];
; #pragma unroll
;     for (int a = 0; a < 2; ++a)
; #pragma unroll
;         for (int b = 0; b < 2; ++b)
; #pragma unroll
;             for (int m = 0; m < 4; ++m)
; #pragma unroll
;                 for (int n = 0; n < 2; ++n) acc[a][b][m][n] = (f32x4){0.f, 0.f, 0.f, 0.f};
;     ...
; #pragma unroll
;         for (int a = 0; a < 2; ++a)
; #pragma unroll
;             for (int b = 0; b < 2; ++b)
; #pragma unroll
;                 for (int m = 0; m < 4; ++m)
; #pragma unroll
;                     for (int n = 0; n < 2; ++n) acc[a][b][m][n] = (f32x4){0.f, 0.f, 0.f, 0.f};
.LBB0_470:
	v_mov_b32_e32 v123, 0
	s_andn2_b64 vcc, exec, s[26:27]
	v_mov_b32_e32 v122, v123
	v_mov_b32_e32 v121, v123
	v_mov_b32_e32 v120, v123
	v_mov_b32_e32 v127, v123
	v_mov_b32_e32 v126, v123
	v_mov_b32_e32 v125, v123
	v_mov_b32_e32 v124, v123
	v_mov_b32_e32 v119, v123
	v_mov_b32_e32 v118, v123
	v_mov_b32_e32 v117, v123
	v_mov_b32_e32 v116, v123
	v_mov_b32_e32 v115, v123
	v_mov_b32_e32 v114, v123
	v_mov_b32_e32 v113, v123
	v_mov_b32_e32 v112, v123
	v_mov_b32_e32 v111, v123
	v_mov_b32_e32 v110, v123
	v_mov_b32_e32 v109, v123
	v_mov_b32_e32 v108, v123
	v_mov_b32_e32 v107, v123
	v_mov_b32_e32 v106, v123
	v_mov_b32_e32 v105, v123
	v_mov_b32_e32 v104, v123
	v_mov_b32_e32 v103, v123
	v_mov_b32_e32 v102, v123
	v_mov_b32_e32 v101, v123
	v_mov_b32_e32 v100, v123
	v_mov_b32_e32 v99, v123
	v_mov_b32_e32 v98, v123
	v_mov_b32_e32 v97, v123
	v_mov_b32_e32 v96, v123
	v_mov_b32_e32 v63, v123
	v_mov_b32_e32 v62, v123
	v_mov_b32_e32 v61, v123
	v_mov_b32_e32 v60, v123
	v_mov_b32_e32 v59, v123
	v_mov_b32_e32 v58, v123
	v_mov_b32_e32 v57, v123
	v_mov_b32_e32 v56, v123
	v_mov_b32_e32 v55, v123
	v_mov_b32_e32 v54, v123
	v_mov_b32_e32 v53, v123
	v_mov_b32_e32 v52, v123
	v_mov_b32_e32 v51, v123
	v_mov_b32_e32 v50, v123
	v_mov_b32_e32 v49, v123
	v_mov_b32_e32 v48, v123
	v_mov_b32_e32 v47, v123
	v_mov_b32_e32 v46, v123
	v_mov_b32_e32 v45, v123
	v_mov_b32_e32 v44, v123
	v_mov_b32_e32 v43, v123
	v_mov_b32_e32 v42, v123
	v_mov_b32_e32 v41, v123
	v_mov_b32_e32 v40, v123
	v_mov_b32_e32 v39, v123
	v_mov_b32_e32 v38, v123
	v_mov_b32_e32 v37, v123
	v_mov_b32_e32 v36, v123
	v_mov_b32_e32 v35, v123
	v_mov_b32_e32 v34, v123
	v_mov_b32_e32 v33, v123
	v_mov_b32_e32 v32, v123
	v_mov_b32_e32 v95, v123
	v_mov_b32_e32 v94, v123
	v_mov_b32_e32 v93, v123
	v_mov_b32_e32 v92, v123
	v_mov_b32_e32 v91, v123
	v_mov_b32_e32 v90, v123
	v_mov_b32_e32 v89, v123
	v_mov_b32_e32 v88, v123
	v_mov_b32_e32 v87, v123
	v_mov_b32_e32 v86, v123
	v_mov_b32_e32 v85, v123
	v_mov_b32_e32 v84, v123
	v_mov_b32_e32 v83, v123
	v_mov_b32_e32 v82, v123
	v_mov_b32_e32 v81, v123
	v_mov_b32_e32 v80, v123
	v_mov_b32_e32 v79, v123
	v_mov_b32_e32 v78, v123
	v_mov_b32_e32 v77, v123
	v_mov_b32_e32 v76, v123
	v_mov_b32_e32 v75, v123
	v_mov_b32_e32 v74, v123
	v_mov_b32_e32 v73, v123
	v_mov_b32_e32 v72, v123
	v_mov_b32_e32 v71, v123
	v_mov_b32_e32 v70, v123
	v_mov_b32_e32 v69, v123
	v_mov_b32_e32 v68, v123
	v_mov_b32_e32 v67, v123
	v_mov_b32_e32 v66, v123
	v_mov_b32_e32 v65, v123
	v_mov_b32_e32 v64, v123
	v_mov_b32_e32 v31, v123
	v_mov_b32_e32 v30, v123
	v_mov_b32_e32 v29, v123
	v_mov_b32_e32 v28, v123
	v_mov_b32_e32 v27, v123
	v_mov_b32_e32 v26, v123
	v_mov_b32_e32 v25, v123
	v_mov_b32_e32 v24, v123
	v_mov_b32_e32 v23, v123
	v_mov_b32_e32 v22, v123
	v_mov_b32_e32 v21, v123
	v_mov_b32_e32 v20, v123
	v_mov_b32_e32 v19, v123
	v_mov_b32_e32 v18, v123
	v_mov_b32_e32 v17, v123
	v_mov_b32_e32 v16, v123
	v_mov_b32_e32 v15, v123
	v_mov_b32_e32 v14, v123
	v_mov_b32_e32 v13, v123
	v_mov_b32_e32 v12, v123
	v_mov_b32_e32 v11, v123
	v_mov_b32_e32 v10, v123
	v_mov_b32_e32 v9, v123
	v_mov_b32_e32 v8, v123
	v_mov_b32_e32 v7, v123
	v_mov_b32_e32 v6, v123
	v_mov_b32_e32 v5, v123
	v_mov_b32_e32 v4, v123
	v_mov_b32_e32 v3, v123
	v_mov_b32_e32 v2, v123
	v_mov_b32_e32 v1, v123
	v_mov_b32_e32 v0, v123
	s_cbranch_vccnz .LBB0_473
	s_add_u32 s0, s0, 0x80
	s_addc_u32 s1, s1, 0
	s_add_u32 s6, s6, 0x100
	v_mov_b32_e32 v0, 0
	v_mov_b32_e32 v254, 0xc00
	s_addc_u32 s7, s7, 0
	s_mov_b32 s4, 0
	v_mov_b32_e32 v1, v0
	v_mov_b32_e32 v2, v0
	v_mov_b32_e32 v3, v0
	v_mov_b32_e32 v4, v0
	v_mov_b32_e32 v5, v0
	v_mov_b32_e32 v6, v0
	v_mov_b32_e32 v7, v0
	v_mov_b32_e32 v8, v0
	v_mov_b32_e32 v9, v0
	v_mov_b32_e32 v10, v0
	v_mov_b32_e32 v11, v0
	v_mov_b32_e32 v12, v0
	v_mov_b32_e32 v13, v0
	v_mov_b32_e32 v14, v0
	v_mov_b32_e32 v15, v0
	v_mov_b32_e32 v16, v0
	v_mov_b32_e32 v17, v0
	v_mov_b32_e32 v18, v0
	v_mov_b32_e32 v19, v0
	v_mov_b32_e32 v20, v0
	v_mov_b32_e32 v21, v0
	v_mov_b32_e32 v22, v0
	v_mov_b32_e32 v23, v0
	v_mov_b32_e32 v24, v0
	v_mov_b32_e32 v25, v0
	v_mov_b32_e32 v26, v0
	v_mov_b32_e32 v27, v0
	v_mov_b32_e32 v28, v0
	v_mov_b32_e32 v29, v0
	v_mov_b32_e32 v30, v0
	v_mov_b32_e32 v31, v0
	v_mov_b32_e32 v64, v0
	v_mov_b32_e32 v65, v0
	v_mov_b32_e32 v66, v0
	v_mov_b32_e32 v67, v0
	v_mov_b32_e32 v68, v0
	v_mov_b32_e32 v69, v0
	v_mov_b32_e32 v70, v0
	v_mov_b32_e32 v71, v0
	v_mov_b32_e32 v72, v0
	v_mov_b32_e32 v73, v0
	v_mov_b32_e32 v74, v0
	v_mov_b32_e32 v75, v0
	v_mov_b32_e32 v76, v0
	v_mov_b32_e32 v77, v0
	v_mov_b32_e32 v78, v0
	v_mov_b32_e32 v79, v0
	v_mov_b32_e32 v80, v0
	v_mov_b32_e32 v81, v0
	v_mov_b32_e32 v82, v0
	v_mov_b32_e32 v83, v0
	v_mov_b32_e32 v84, v0
	v_mov_b32_e32 v85, v0
	v_mov_b32_e32 v86, v0
	v_mov_b32_e32 v87, v0
	v_mov_b32_e32 v88, v0
	v_mov_b32_e32 v89, v0
	v_mov_b32_e32 v90, v0
	v_mov_b32_e32 v91, v0
	v_mov_b32_e32 v92, v0
	v_mov_b32_e32 v93, v0
	v_mov_b32_e32 v94, v0
	v_mov_b32_e32 v95, v0
	v_mov_b32_e32 v32, v0
	v_mov_b32_e32 v33, v0
	v_mov_b32_e32 v34, v0
	v_mov_b32_e32 v35, v0
	v_mov_b32_e32 v36, v0
	v_mov_b32_e32 v37, v0
	v_mov_b32_e32 v38, v0
	v_mov_b32_e32 v39, v0
	v_mov_b32_e32 v40, v0
	v_mov_b32_e32 v41, v0
	v_mov_b32_e32 v42, v0
	v_mov_b32_e32 v43, v0
	v_mov_b32_e32 v44, v0
	v_mov_b32_e32 v45, v0
	v_mov_b32_e32 v46, v0
	v_mov_b32_e32 v47, v0
	v_mov_b32_e32 v48, v0
	v_mov_b32_e32 v49, v0
	v_mov_b32_e32 v50, v0
	v_mov_b32_e32 v51, v0
	v_mov_b32_e32 v52, v0
	v_mov_b32_e32 v53, v0
	v_mov_b32_e32 v54, v0
	v_mov_b32_e32 v55, v0
	v_mov_b32_e32 v56, v0
	v_mov_b32_e32 v57, v0
	v_mov_b32_e32 v58, v0
	v_mov_b32_e32 v59, v0
	v_mov_b32_e32 v60, v0
	v_mov_b32_e32 v61, v0
	v_mov_b32_e32 v62, v0
	v_mov_b32_e32 v63, v0
	v_mov_b32_e32 v96, v0
	v_mov_b32_e32 v97, v0
	v_mov_b32_e32 v98, v0
	v_mov_b32_e32 v99, v0
	v_mov_b32_e32 v100, v0
	v_mov_b32_e32 v101, v0
	v_mov_b32_e32 v102, v0
	v_mov_b32_e32 v103, v0
	v_mov_b32_e32 v104, v0
	v_mov_b32_e32 v105, v0
	v_mov_b32_e32 v106, v0
	v_mov_b32_e32 v107, v0
	v_mov_b32_e32 v108, v0
	v_mov_b32_e32 v109, v0
	v_mov_b32_e32 v110, v0
	v_mov_b32_e32 v111, v0
	v_mov_b32_e32 v112, v0
	v_mov_b32_e32 v113, v0
	v_mov_b32_e32 v114, v0
	v_mov_b32_e32 v115, v0
	v_mov_b32_e32 v116, v0
	v_mov_b32_e32 v117, v0
	v_mov_b32_e32 v118, v0
	v_mov_b32_e32 v119, v0
	v_mov_b32_e32 v124, v0
	v_mov_b32_e32 v125, v0
	v_mov_b32_e32 v126, v0
	v_mov_b32_e32 v127, v0
	v_mov_b32_e32 v120, v0
	v_mov_b32_e32 v121, v0
	v_mov_b32_e32 v122, v0
	v_mov_b32_e32 v123, v0
	v_add_u32_e32 v250, 0x10000, v158
	v_add_u32_e32 v251, 0x14000, v158
	v_add_u32_e32 v252, 0x18000, v158
	v_add_u32_e32 v253, 0x1c000, v158
; #define PG8_STAGE(bufoff, gbase, voff) do { _Pragma("unroll") for (int _i = 0; _i < 2; ++_i) \
;         __builtin_amdgcn_global_load_lds((const unsigned*)((const char*)(gbase) + (voff)[_i]), (LAS unsigned*)(lds + (bufoff) + ldsw + _i * 8192), 16, 0, 0); } while (0)
; #define PG8_LDA(dst, b, h) do { _Pragma("unroll") for (int m = 0; m < 4; ++m) _Pragma("unroll") for (int k = 0; k < 2; ++k) dst[m][k] = *(const LAS bf16x8*)(lds + PG8_SA(b, h) + aoff + m * 2048 + k * 1024); } while (0)
; #define PG8_LDB(dst, b, h) do { _Pragma("unroll") for (int n = 0; n < 2; ++n) _Pragma("unroll") for (int k = 0; k < 2; ++k) dst[n][k] = *(const LAS bf16x8*)(lds + PG8_SB(b, h) + boff + n * 2048 + k * 1024); } while (0)
; #define PG8_MMA(ai, bj, At, Bt) do { __builtin_amdgcn_s_setprio(1); _Pragma("unroll") for (int m = 0; m < 4; ++m) _Pragma("unroll") for (int n = 0; n < 2; ++n) _Pragma("unroll") for (int k = 0; k < 2; ++k) \
;         acc[ai][bj][m][n] = __builtin_amdgcn_mfma_f32_16x16x32_bf16(Bt[n][k], At[m][k], acc[ai][bj][m][n], 0, 0, 0); __builtin_amdgcn_s_setprio(0); } while (0)
; #define PG8_WAIT_V(n) asm volatile("s_waitcnt vmcnt(" #n ")" ::: "memory")
; #define PG8_WAIT_L(n) asm volatile("s_waitcnt lgkmcnt(" #n ")" ::: "memory")
; #define PG8_BAR __builtin_amdgcn_s_barrier()
; #define PG8_SCHED __builtin_amdgcn_sched_barrier(0)
; template <class EpiT, class Sched>
; __device__ __forceinline__ void gemm_phase(LAS unsigned char* lds, const Gemm g, const Sched& S, const EpiT& E, int wv) {
;     ...
;             PG8_LDB(B0, 0, 0); PG8_LDB(B1, 0, 1); PG8_SCHED; PG8_LDA(At, 0, 0); PG8_STAGE(PG8_SA(1, 1), a1 + hstepA, voffA);
;             PG8_WAIT_V(8); PG8_WAIT_L(0); PG8_BAR; PG8_MMA(0, 0, At, B0); PG8_MMA(0, 1, At, B1); PG8_BAR; PG8_SCHED;
;             PG8_LDA(At, 0, 1); PG8_STAGE(PG8_SB(0, 0), b2, voffB); PG8_STAGE(PG8_SB(0, 1), b2 + hstepB, voffB); PG8_STAGE(PG8_SA(0, 0), a2, voffA);
;             PG8_WAIT_V(8); PG8_WAIT_L(0); PG8_BAR; PG8_MMA(1, 0, At, B0); PG8_MMA(1, 1, At, B1); PG8_BAR; PG8_SCHED;
.LBB0_472:
	s_add_i32 s9, s4, 2
	s_add_u32 s11, s0, 0x80
	s_addc_u32 s5, s1, 0
	s_add_i32 s33, 0, 0x10000
	s_cmp_eq_u32 s58, s4
	s_cselect_b32 s5, s35, s5
	s_cselect_b32 s4, s34, s11
	s_cselect_b32 s39, s37, s7
	s_cselect_b32 s38, s36, s6
	s_add_i32 s11, 0, 0x14000
	ds_read_b128 v[128:131], v250
	ds_read_b128 v[142:145], v250 offset:1024
	ds_read_b128 v[146:149], v250 offset:2048
	ds_read_b128 v[150:153], v250 offset:3072
	ds_read_b128 v[154:157], v251
	ds_read_b128 v[160:163], v251 offset:1024
	ds_read_b128 v[164:167], v251 offset:2048
	ds_read_b128 v[168:171], v251 offset:3072
	v_lshl_add_u64 v[216:217], s[0:1], 0, v[138:139]
	s_add_i32 m0, s50, 0xc000
	ds_read_b128 v[172:175], v159
	ds_read_b128 v[176:179], v159 offset:1024
	ds_read_b128 v[180:183], v159 offset:2048
	ds_read_b128 v[184:187], v159 offset:3072
	ds_read_b128 v[188:191], v159 offset:4096
	ds_read_b128 v[204:207], v159 offset:5120
	ds_read_b128 v[208:211], v159 offset:6144
	ds_read_b128 v[212:215], v159 offset:7168
	global_load_lds_dwordx4 v[216:217], off
	v_lshl_add_u64 v[216:217], s[0:1], 0, v[140:141]
	s_add_i32 m0, s50, 0xe000
	s_nop 0
	global_load_lds_dwordx4 v[216:217], off
	s_waitcnt vmcnt(8)
	s_waitcnt lgkmcnt(0)
	s_barrier
	s_setprio 1
	s_waitcnt lgkmcnt(0)
	v_mfma_f32_16x16x32_bf16 v[120:123], v[128:131], v[172:175], v[120:123]
	v_mfma_f32_16x16x32_bf16 v[124:127], v[146:149], v[172:175], v[124:127]
	v_mfma_f32_16x16x32_bf16 v[116:119], v[128:131], v[180:183], v[116:119]
	v_mfma_f32_16x16x32_bf16 v[112:115], v[146:149], v[180:183], v[112:115]
	v_mfma_f32_16x16x32_bf16 v[108:111], v[128:131], v[188:191], v[108:111]
	v_mfma_f32_16x16x32_bf16 v[104:107], v[146:149], v[188:191], v[104:107]
	v_mfma_f32_16x16x32_bf16 v[100:103], v[128:131], v[208:211], v[100:103]
	v_mfma_f32_16x16x32_bf16 v[96:99], v[146:149], v[208:211], v[96:99]
	v_mfma_f32_16x16x32_bf16 v[120:123], v[142:145], v[176:179], v[120:123]
	v_mfma_f32_16x16x32_bf16 v[124:127], v[150:153], v[176:179], v[124:127]
	v_mfma_f32_16x16x32_bf16 v[116:119], v[142:145], v[184:187], v[116:119]
	v_mfma_f32_16x16x32_bf16 v[112:115], v[150:153], v[184:187], v[112:115]
	v_mfma_f32_16x16x32_bf16 v[108:111], v[142:145], v[204:207], v[108:111]
	v_mfma_f32_16x16x32_bf16 v[104:107], v[150:153], v[204:207], v[104:107]
	v_mfma_f32_16x16x32_bf16 v[100:103], v[142:145], v[212:215], v[100:103]
	v_mfma_f32_16x16x32_bf16 v[96:99], v[150:153], v[212:215], v[96:99]
	s_setprio 0
	s_setprio 1
	v_mfma_f32_16x16x32_bf16 v[60:63], v[154:157], v[172:175], v[60:63]
	v_mfma_f32_16x16x32_bf16 v[56:59], v[164:167], v[172:175], v[56:59]
	v_mfma_f32_16x16x32_bf16 v[52:55], v[154:157], v[180:183], v[52:55]
	v_mfma_f32_16x16x32_bf16 v[48:51], v[164:167], v[180:183], v[48:51]
	v_mfma_f32_16x16x32_bf16 v[44:47], v[154:157], v[188:191], v[44:47]
	v_mfma_f32_16x16x32_bf16 v[40:43], v[164:167], v[188:191], v[40:43]
	v_mfma_f32_16x16x32_bf16 v[36:39], v[154:157], v[208:211], v[36:39]
	v_mfma_f32_16x16x32_bf16 v[32:35], v[164:167], v[208:211], v[32:35]
	v_mfma_f32_16x16x32_bf16 v[60:63], v[160:163], v[176:179], v[60:63]
	v_mfma_f32_16x16x32_bf16 v[56:59], v[168:171], v[176:179], v[56:59]
	v_mfma_f32_16x16x32_bf16 v[52:55], v[160:163], v[184:187], v[52:55]
	v_mfma_f32_16x16x32_bf16 v[48:51], v[168:171], v[184:187], v[48:51]
	v_mfma_f32_16x16x32_bf16 v[44:47], v[160:163], v[204:207], v[44:47]
	v_mfma_f32_16x16x32_bf16 v[40:43], v[168:171], v[204:207], v[40:43]
	v_mfma_f32_16x16x32_bf16 v[36:39], v[160:163], v[212:215], v[36:39]
	v_mfma_f32_16x16x32_bf16 v[32:35], v[168:171], v[212:215], v[32:35]
	s_setprio 0
	s_barrier
	s_add_i32 s33, s33, s49
	v_lshl_add_u64 v[216:217], s[38:39], 0, v[192:193]
	s_mov_b32 m0, s33
	ds_read_b128 v[172:175], v159 offset:16384
	ds_read_b128 v[176:179], v159 offset:17408
	ds_read_b128 v[180:183], v159 offset:18432
	ds_read_b128 v[184:187], v159 offset:19456
	ds_read_b128 v[188:191], v159 offset:20480
	ds_read_b128 v[204:207], v159 offset:21504
	ds_read_b128 v[208:211], v159 offset:22528
	ds_read_b128 v[212:215], v159 offset:23552
	global_load_lds_dwordx4 v[216:217], off
	s_add_i32 m0, s33, 0x2000
	v_lshl_add_u64 v[218:219], s[38:39], 0, v[136:137]
	s_add_u32 s38, s38, s16
	s_addc_u32 s39, s39, s17
	s_add_i32 s11, s11, s49
	global_load_lds_dwordx4 v[218:219], off
	v_lshl_add_u64 v[220:221], s[38:39], 0, v[192:193]
	s_mov_b32 m0, s11
	v_lshl_add_u64 v[222:223], s[38:39], 0, v[136:137]
	global_load_lds_dwordx4 v[220:221], off
	s_add_i32 m0, s11, 0x2000
	v_lshl_add_u64 v[232:233], s[4:5], 0, v[132:133]
	global_load_lds_dwordx4 v[222:223], off
	s_mov_b32 m0, s50
	v_lshl_add_u64 v[234:235], s[4:5], 0, v[134:135]
	global_load_lds_dwordx4 v[232:233], off
	s_mov_b32 m0, s51
	s_nop 0
	global_load_lds_dwordx4 v[234:235], off
	s_waitcnt vmcnt(8)
	s_waitcnt lgkmcnt(0)
	s_barrier
; #define PG8_STAGE(bufoff, gbase, voff) do { _Pragma("unroll") for (int _i = 0; _i < 2; ++_i) \
;         __builtin_amdgcn_global_load_lds((const unsigned*)((const char*)(gbase) + (voff)[_i]), (LAS unsigned*)(lds + (bufoff) + ldsw + _i * 8192), 16, 0, 0); } while (0)
; #define PG8_LDA(dst, b, h) do { _Pragma("unroll") for (int m = 0; m < 4; ++m) _Pragma("unroll") for (int k = 0; k < 2; ++k) dst[m][k] = *(const LAS bf16x8*)(lds + PG8_SA(b, h) + aoff + m * 2048 + k * 1024); } while (0)
; #define PG8_LDB(dst, b, h) do { _Pragma("unroll") for (int n = 0; n < 2; ++n) _Pragma("unroll") for (int k = 0; k < 2; ++k) dst[n][k] = *(const LAS bf16x8*)(lds + PG8_SB(b, h) + boff + n * 2048 + k * 1024); } while (0)
; #define PG8_MMA(ai, bj, At, Bt) do { __builtin_amdgcn_s_setprio(1); _Pragma("unroll") for (int m = 0; m < 4; ++m) _Pragma("unroll") for (int n = 0; n < 2; ++n) _Pragma("unroll") for (int k = 0; k < 2; ++k) \
;         acc[ai][bj][m][n] = __builtin_amdgcn_mfma_f32_16x16x32_bf16(Bt[n][k], At[m][k], acc[ai][bj][m][n], 0, 0, 0); __builtin_amdgcn_s_setprio(0); } while (0)
; #define PG8_WAIT_V(n) asm volatile("s_waitcnt vmcnt(" #n ")" ::: "memory")
; #define PG8_WAIT_L(n) asm volatile("s_waitcnt lgkmcnt(" #n ")" ::: "memory")
; #define PG8_BAR __builtin_amdgcn_s_barrier()
; #define PG8_SCHED __builtin_amdgcn_sched_barrier(0)
; template <class EpiT, class Sched>
; __device__ __forceinline__ void gemm_phase(LAS unsigned char* lds, const Gemm g, const Sched& S, const EpiT& E, int wv) {
;     ...
;             PG8_WAIT_V(8); PG8_WAIT_L(0); PG8_BAR; PG8_MMA(1, 0, At, B0); PG8_MMA(1, 1, At, B1); PG8_BAR; PG8_SCHED;
;             PG8_LDB(B0, 1, 0); PG8_LDB(B1, 1, 1); PG8_SCHED; PG8_LDA(At, 1, 0); PG8_STAGE(PG8_SA(0, 1), a2 + hstepA, voffA);
;             PG8_WAIT_V(8); PG8_WAIT_L(0); PG8_BAR; PG8_MMA(0, 0, At, B0); PG8_MMA(0, 1, At, B1); PG8_BAR; PG8_SCHED;
	s_setprio 1
	s_waitcnt lgkmcnt(0)
	v_mfma_f32_16x16x32_bf16 v[92:95], v[128:131], v[172:175], v[92:95]
	v_mfma_f32_16x16x32_bf16 v[88:91], v[146:149], v[172:175], v[88:91]
	v_mfma_f32_16x16x32_bf16 v[84:87], v[128:131], v[180:183], v[84:87]
	v_mfma_f32_16x16x32_bf16 v[80:83], v[146:149], v[180:183], v[80:83]
	v_mfma_f32_16x16x32_bf16 v[76:79], v[128:131], v[188:191], v[76:79]
	v_mfma_f32_16x16x32_bf16 v[72:75], v[146:149], v[188:191], v[72:75]
	v_mfma_f32_16x16x32_bf16 v[68:71], v[128:131], v[208:211], v[68:71]
	v_mfma_f32_16x16x32_bf16 v[64:67], v[146:149], v[208:211], v[64:67]
	v_mfma_f32_16x16x32_bf16 v[92:95], v[142:145], v[176:179], v[92:95]
	v_mfma_f32_16x16x32_bf16 v[88:91], v[150:153], v[176:179], v[88:91]
	v_mfma_f32_16x16x32_bf16 v[84:87], v[142:145], v[184:187], v[84:87]
	v_mfma_f32_16x16x32_bf16 v[80:83], v[150:153], v[184:187], v[80:83]
	v_mfma_f32_16x16x32_bf16 v[76:79], v[142:145], v[204:207], v[76:79]
	v_mfma_f32_16x16x32_bf16 v[72:75], v[150:153], v[204:207], v[72:75]
	v_mfma_f32_16x16x32_bf16 v[68:71], v[142:145], v[212:215], v[68:71]
	v_mfma_f32_16x16x32_bf16 v[64:67], v[150:153], v[212:215], v[64:67]
	s_setprio 0
	s_setprio 1
	v_mfma_f32_16x16x32_bf16 v[28:31], v[154:157], v[172:175], v[28:31]
	v_mfma_f32_16x16x32_bf16 v[24:27], v[164:167], v[172:175], v[24:27]
	v_mfma_f32_16x16x32_bf16 v[20:23], v[154:157], v[180:183], v[20:23]
	v_mfma_f32_16x16x32_bf16 v[16:19], v[164:167], v[180:183], v[16:19]
	v_mfma_f32_16x16x32_bf16 v[12:15], v[154:157], v[188:191], v[12:15]
	v_mfma_f32_16x16x32_bf16 v[8:11], v[164:167], v[188:191], v[8:11]
	v_mfma_f32_16x16x32_bf16 v[4:7], v[154:157], v[208:211], v[4:7]
	v_mfma_f32_16x16x32_bf16 v[0:3], v[164:167], v[208:211], v[0:3]
	v_mfma_f32_16x16x32_bf16 v[28:31], v[160:163], v[176:179], v[28:31]
	v_mfma_f32_16x16x32_bf16 v[24:27], v[168:171], v[176:179], v[24:27]
	v_mfma_f32_16x16x32_bf16 v[20:23], v[160:163], v[184:187], v[20:23]
	v_mfma_f32_16x16x32_bf16 v[16:19], v[168:171], v[184:187], v[16:19]
	v_mfma_f32_16x16x32_bf16 v[12:15], v[160:163], v[204:207], v[12:15]
	v_mfma_f32_16x16x32_bf16 v[8:11], v[168:171], v[204:207], v[8:11]
	v_mfma_f32_16x16x32_bf16 v[4:7], v[160:163], v[212:215], v[4:7]
	v_mfma_f32_16x16x32_bf16 v[0:3], v[168:171], v[212:215], v[0:3]
	s_setprio 0
	s_barrier
	s_add_i32 s11, 0, 0x18000
	s_add_i32 s33, 0, 0x1c000
	ds_read_b128 v[128:131], v252
	ds_read_b128 v[142:145], v252 offset:1024
	ds_read_b128 v[146:149], v252 offset:2048
	ds_read_b128 v[150:153], v252 offset:3072
	ds_read_b128 v[154:157], v253
	ds_read_b128 v[160:163], v253 offset:1024
	ds_read_b128 v[164:167], v253 offset:2048
	ds_read_b128 v[168:171], v253 offset:3072
	s_add_u32 s4, s4, s16
	s_addc_u32 s5, s5, s17
	s_mov_b32 m0, s52
	v_lshl_add_u64 v[240:241], s[4:5], 0, v[132:133]
	ds_read_b128 v[172:175], v159 offset:32768
	ds_read_b128 v[176:179], v159 offset:33792
	ds_read_b128 v[180:183], v159 offset:34816
	ds_read_b128 v[184:187], v159 offset:35840
	ds_read_b128 v[188:191], v159 offset:36864
	ds_read_b128 v[204:207], v159 offset:37888
	ds_read_b128 v[208:211], v159 offset:38912
	ds_read_b128 v[212:215], v159 offset:39936
	global_load_lds_dwordx4 v[240:241], off
	v_lshl_add_u64 v[240:241], s[4:5], 0, v[134:135]
	s_mov_b32 m0, s53
	s_nop 0
	global_load_lds_dwordx4 v[240:241], off
	s_waitcnt vmcnt(8)
	s_waitcnt lgkmcnt(0)
	s_barrier
	s_setprio 1
	s_waitcnt lgkmcnt(0)
	v_mfma_f32_16x16x32_bf16 v[120:123], v[128:131], v[172:175], v[120:123]
	v_mfma_f32_16x16x32_bf16 v[124:127], v[146:149], v[172:175], v[124:127]
	v_mfma_f32_16x16x32_bf16 v[116:119], v[128:131], v[180:183], v[116:119]
	v_mfma_f32_16x16x32_bf16 v[112:115], v[146:149], v[180:183], v[112:115]
	v_mfma_f32_16x16x32_bf16 v[108:111], v[128:131], v[188:191], v[108:111]
	v_mfma_f32_16x16x32_bf16 v[104:107], v[146:149], v[188:191], v[104:107]
	v_mfma_f32_16x16x32_bf16 v[100:103], v[128:131], v[208:211], v[100:103]
	v_mfma_f32_16x16x32_bf16 v[96:99], v[146:149], v[208:211], v[96:99]
	v_mfma_f32_16x16x32_bf16 v[120:123], v[142:145], v[176:179], v[120:123]
	v_mfma_f32_16x16x32_bf16 v[124:127], v[150:153], v[176:179], v[124:127]
	v_mfma_f32_16x16x32_bf16 v[116:119], v[142:145], v[184:187], v[116:119]
	v_mfma_f32_16x16x32_bf16 v[112:115], v[150:153], v[184:187], v[112:115]
	v_mfma_f32_16x16x32_bf16 v[108:111], v[142:145], v[204:207], v[108:111]
	v_mfma_f32_16x16x32_bf16 v[104:107], v[150:153], v[204:207], v[104:107]
	v_mfma_f32_16x16x32_bf16 v[100:103], v[142:145], v[212:215], v[100:103]
	v_mfma_f32_16x16x32_bf16 v[96:99], v[150:153], v[212:215], v[96:99]
	s_setprio 0
	s_setprio 1
	v_mfma_f32_16x16x32_bf16 v[60:63], v[154:157], v[172:175], v[60:63]
	v_mfma_f32_16x16x32_bf16 v[56:59], v[164:167], v[172:175], v[56:59]
	v_mfma_f32_16x16x32_bf16 v[52:55], v[154:157], v[180:183], v[52:55]
	v_mfma_f32_16x16x32_bf16 v[48:51], v[164:167], v[180:183], v[48:51]
	v_mfma_f32_16x16x32_bf16 v[44:47], v[154:157], v[188:191], v[44:47]
	v_mfma_f32_16x16x32_bf16 v[40:43], v[164:167], v[188:191], v[40:43]
	v_mfma_f32_16x16x32_bf16 v[36:39], v[154:157], v[208:211], v[36:39]
	v_mfma_f32_16x16x32_bf16 v[32:35], v[164:167], v[208:211], v[32:35]
	v_mfma_f32_16x16x32_bf16 v[60:63], v[160:163], v[176:179], v[60:63]
	v_mfma_f32_16x16x32_bf16 v[56:59], v[168:171], v[176:179], v[56:59]
	v_mfma_f32_16x16x32_bf16 v[52:55], v[160:163], v[184:187], v[52:55]
	v_mfma_f32_16x16x32_bf16 v[48:51], v[168:171], v[184:187], v[48:51]
	v_mfma_f32_16x16x32_bf16 v[44:47], v[160:163], v[204:207], v[44:47]
	v_mfma_f32_16x16x32_bf16 v[40:43], v[168:171], v[204:207], v[40:43]
	v_mfma_f32_16x16x32_bf16 v[36:39], v[160:163], v[212:215], v[36:39]
	v_mfma_f32_16x16x32_bf16 v[32:35], v[168:171], v[212:215], v[32:35]
	s_setprio 0
	s_barrier
; #define PG8_STAGE(bufoff, gbase, voff) do { _Pragma("unroll") for (int _i = 0; _i < 2; ++_i) \
;         __builtin_amdgcn_global_load_lds((const unsigned*)((const char*)(gbase) + (voff)[_i]), (LAS unsigned*)(lds + (bufoff) + ldsw + _i * 8192), 16, 0, 0); } while (0)
; #define PG8_LDA(dst, b, h) do { _Pragma("unroll") for (int m = 0; m < 4; ++m) _Pragma("unroll") for (int k = 0; k < 2; ++k) dst[m][k] = *(const LAS bf16x8*)(lds + PG8_SA(b, h) + aoff + m * 2048 + k * 1024); } while (0)
; #define PG8_MMA(ai, bj, At, Bt) do { __builtin_amdgcn_s_setprio(1); _Pragma("unroll") for (int m = 0; m < 4; ++m) _Pragma("unroll") for (int n = 0; n < 2; ++n) _Pragma("unroll") for (int k = 0; k < 2; ++k) \
;         acc[ai][bj][m][n] = __builtin_amdgcn_mfma_f32_16x16x32_bf16(Bt[n][k], At[m][k], acc[ai][bj][m][n], 0, 0, 0); __builtin_amdgcn_s_setprio(0); } while (0)
; #define PG8_WAIT_V(n) asm volatile("s_waitcnt vmcnt(" #n ")" ::: "memory")
; #define PG8_WAIT_L(n) asm volatile("s_waitcnt lgkmcnt(" #n ")" ::: "memory")
; #define PG8_BAR __builtin_amdgcn_s_barrier()
; #define PG8_SCHED __builtin_amdgcn_sched_barrier(0)
; template <class EpiT, class Sched>
; __device__ __forceinline__ void gemm_phase(LAS unsigned char* lds, const Gemm g, const Sched& S, const EpiT& E, int wv) {
;     ...
;             PG8_LDA(At, 1, 1); PG8_STAGE(PG8_SB(1, 0), b3, voffB); PG8_STAGE(PG8_SB(1, 1), b3 + hstepB, voffB); PG8_STAGE(PG8_SA(1, 0), a3, voffA);
;             PG8_WAIT_V(8); PG8_WAIT_L(0); PG8_BAR; PG8_MMA(1, 0, At, B0); PG8_MMA(1, 1, At, B1); PG8_BAR; PG8_SCHED;
;         }
	s_add_i32 s4, s11, s49
	v_lshl_add_u64 v[216:217], v[216:217], 0, s[92:93]
	s_mov_b32 m0, s4
	ds_read_b128 v[172:175], v159 offset:49152
	ds_read_b128 v[176:179], v159 offset:50176
	ds_read_b128 v[180:183], v159 offset:51200
	ds_read_b128 v[184:187], v159 offset:52224
	ds_read_b128 v[188:191], v159 offset:53248
	ds_read_b128 v[204:207], v159 offset:54272
	ds_read_b128 v[208:211], v159 offset:55296
	ds_read_b128 v[212:215], v159 offset:56320
	global_load_lds_dwordx4 v[216:217], off
	v_lshl_add_u64 v[216:217], v[218:219], 0, s[92:93]
	s_add_i32 m0, s4, 0x2000
	s_add_i32 s4, s33, s49
	global_load_lds_dwordx4 v[216:217], off
	v_lshl_add_u64 v[216:217], v[220:221], 0, s[92:93]
	s_mov_b32 m0, s4
	s_nop 0
	global_load_lds_dwordx4 v[216:217], off
	v_lshl_add_u64 v[216:217], v[222:223], 0, s[92:93]
	s_add_i32 m0, s4, 0x2000
	s_nop 0
	global_load_lds_dwordx4 v[216:217], off
	v_lshl_add_u64 v[216:217], v[232:233], 0, s[92:93]
	s_mov_b32 m0, s54
	s_nop 0
	global_load_lds_dwordx4 v[216:217], off
	v_lshl_add_u64 v[216:217], v[234:235], 0, s[92:93]
	s_mov_b32 m0, s55
	s_nop 0
	global_load_lds_dwordx4 v[216:217], off
	s_waitcnt vmcnt(8)
	s_waitcnt lgkmcnt(0)
	s_barrier
	s_setprio 1
	s_waitcnt lgkmcnt(0)
	v_mfma_f32_16x16x32_bf16 v[92:95], v[128:131], v[172:175], v[92:95]
	v_mfma_f32_16x16x32_bf16 v[88:91], v[146:149], v[172:175], v[88:91]
	v_mfma_f32_16x16x32_bf16 v[84:87], v[128:131], v[180:183], v[84:87]
	v_mfma_f32_16x16x32_bf16 v[80:83], v[146:149], v[180:183], v[80:83]
	v_mfma_f32_16x16x32_bf16 v[76:79], v[128:131], v[188:191], v[76:79]
	v_mfma_f32_16x16x32_bf16 v[72:75], v[146:149], v[188:191], v[72:75]
	v_mfma_f32_16x16x32_bf16 v[68:71], v[128:131], v[208:211], v[68:71]
	v_mfma_f32_16x16x32_bf16 v[64:67], v[146:149], v[208:211], v[64:67]
	v_mfma_f32_16x16x32_bf16 v[92:95], v[142:145], v[176:179], v[92:95]
	v_mfma_f32_16x16x32_bf16 v[88:91], v[150:153], v[176:179], v[88:91]
	v_mfma_f32_16x16x32_bf16 v[84:87], v[142:145], v[184:187], v[84:87]
	v_mfma_f32_16x16x32_bf16 v[80:83], v[150:153], v[184:187], v[80:83]
	v_mfma_f32_16x16x32_bf16 v[76:79], v[142:145], v[204:207], v[76:79]
	v_mfma_f32_16x16x32_bf16 v[72:75], v[150:153], v[204:207], v[72:75]
	v_mfma_f32_16x16x32_bf16 v[68:71], v[142:145], v[212:215], v[68:71]
	v_mfma_f32_16x16x32_bf16 v[64:67], v[150:153], v[212:215], v[64:67]
	s_setprio 0
	s_setprio 1
	v_mfma_f32_16x16x32_bf16 v[28:31], v[154:157], v[172:175], v[28:31]
	v_mfma_f32_16x16x32_bf16 v[24:27], v[164:167], v[172:175], v[24:27]
	v_mfma_f32_16x16x32_bf16 v[20:23], v[154:157], v[180:183], v[20:23]
	v_mfma_f32_16x16x32_bf16 v[16:19], v[164:167], v[180:183], v[16:19]
	v_mfma_f32_16x16x32_bf16 v[12:15], v[154:157], v[188:191], v[12:15]
	v_mfma_f32_16x16x32_bf16 v[8:11], v[164:167], v[188:191], v[8:11]
	v_mfma_f32_16x16x32_bf16 v[4:7], v[154:157], v[208:211], v[4:7]
	v_mfma_f32_16x16x32_bf16 v[0:3], v[164:167], v[208:211], v[0:3]
	v_mfma_f32_16x16x32_bf16 v[28:31], v[160:163], v[176:179], v[28:31]
	v_mfma_f32_16x16x32_bf16 v[24:27], v[168:171], v[176:179], v[24:27]
	v_mfma_f32_16x16x32_bf16 v[20:23], v[160:163], v[184:187], v[20:23]
	v_mfma_f32_16x16x32_bf16 v[16:19], v[168:171], v[184:187], v[16:19]
	v_mfma_f32_16x16x32_bf16 v[12:15], v[160:163], v[204:207], v[12:15]
	v_mfma_f32_16x16x32_bf16 v[8:11], v[168:171], v[204:207], v[8:11]
	v_mfma_f32_16x16x32_bf16 v[4:7], v[160:163], v[212:215], v[4:7]
	v_mfma_f32_16x16x32_bf16 v[0:3], v[168:171], v[212:215], v[0:3]
	s_setprio 0
	s_barrier
	s_add_u32 s0, s0, 0x100
	s_addc_u32 s1, s1, 0
	s_add_u32 s6, s6, 0x100
	s_addc_u32 s7, s7, 0
	s_cmp_ge_i32 s9, s57
	s_mov_b32 s4, s9
	s_cbranch_scc0 .LBB0_472

; #define PG8_STAGE(bufoff, gbase, voff) do { _Pragma("unroll") for (int _i = 0; _i < 2; ++_i) \
;         __builtin_amdgcn_global_load_lds((const unsigned*)((const char*)(gbase) + (voff)[_i]), (LAS unsigned*)(lds + (bufoff) + ldsw + _i * 8192), 16, 0, 0); } while (0)
; #define PG8_LDA(dst, b, h) do { _Pragma("unroll") for (int m = 0; m < 4; ++m) _Pragma("unroll") for (int k = 0; k < 2; ++k) dst[m][k] = *(const LAS bf16x8*)(lds + PG8_SA(b, h) + aoff + m * 2048 + k * 1024); } while (0)
; #define PG8_LDB(dst, b, h) do { _Pragma("unroll") for (int n = 0; n < 2; ++n) _Pragma("unroll") for (int k = 0; k < 2; ++k) dst[n][k] = *(const LAS bf16x8*)(lds + PG8_SB(b, h) + boff + n * 2048 + k * 1024); } while (0)
; #define PG8_SCHED __builtin_amdgcn_sched_barrier(0)
; template <class EpiT, class Sched>
; __device__ __forceinline__ void gemm_phase(LAS unsigned char* lds, const Gemm g, const Sched& S, const EpiT& E, int wv) {
;     ...
;         for (int t = 0; t < nt; t += 2) {
;             const bool last = (t == nt - 2);
;             const char* a1 = cA + (size_t)(t + 1) * kstep;
;             const char* a2 = last ? nA : cA + (size_t)(t + 2) * kstep; const char* b2 = last ? nB : cB + (size_t)(t + 2) * kstep;
;             const char* a3 = a2 + kstep; const char* b3 = b2 + kstep;
;             PG8_LDB(B0, 0, 0); PG8_LDB(B1, 0, 1); PG8_SCHED; PG8_LDA(At, 0, 0); PG8_STAGE(PG8_SA(1, 1), a1 + hstepA, voffA);
;     ...
; #pragma unroll
;         for (int a = 0; a < 2; ++a)
; #pragma unroll
;             for (int b = 0; b < 2; ++b)
; #pragma unroll
;                 for (int m = 0; m < 4; ++m)
; #pragma unroll
;                     for (int n = 0; n < 2; ++n) acc[a][b][m][n] = (f32x4){0.f, 0.f, 0.f, 0.f};
;         cur = nxt; cA = nA; cB = nB; ++ui;
.LBB0_621:
	v_mov_b32_e32 v123, 0
	s_andn2_b64 vcc, exec, s[20:21]
	v_mov_b32_e32 v122, v123
	v_mov_b32_e32 v121, v123
	v_mov_b32_e32 v120, v123
	v_mov_b32_e32 v127, v123
	v_mov_b32_e32 v126, v123
	v_mov_b32_e32 v125, v123
	v_mov_b32_e32 v124, v123
	v_mov_b32_e32 v119, v123
	v_mov_b32_e32 v118, v123
	v_mov_b32_e32 v117, v123
	v_mov_b32_e32 v116, v123
	v_mov_b32_e32 v115, v123
	v_mov_b32_e32 v114, v123
	v_mov_b32_e32 v113, v123
	v_mov_b32_e32 v112, v123
	v_mov_b32_e32 v111, v123
	v_mov_b32_e32 v110, v123
	v_mov_b32_e32 v109, v123
	v_mov_b32_e32 v108, v123
	v_mov_b32_e32 v107, v123
	v_mov_b32_e32 v106, v123
	v_mov_b32_e32 v105, v123
	v_mov_b32_e32 v104, v123
	v_mov_b32_e32 v103, v123
	v_mov_b32_e32 v102, v123
	v_mov_b32_e32 v101, v123
	v_mov_b32_e32 v100, v123
	v_mov_b32_e32 v99, v123
	v_mov_b32_e32 v98, v123
	v_mov_b32_e32 v97, v123
	v_mov_b32_e32 v96, v123
	v_mov_b32_e32 v63, v123
	v_mov_b32_e32 v62, v123
	v_mov_b32_e32 v61, v123
	v_mov_b32_e32 v60, v123
	s_waitcnt vmcnt(0)
	v_mov_b32_e32 v59, v123
	v_mov_b32_e32 v58, v123
	v_mov_b32_e32 v57, v123
	v_mov_b32_e32 v56, v123
	v_mov_b32_e32 v55, v123
	v_mov_b32_e32 v54, v123
	v_mov_b32_e32 v53, v123
	v_mov_b32_e32 v52, v123
	v_mov_b32_e32 v51, v123
	v_mov_b32_e32 v50, v123
	v_mov_b32_e32 v49, v123
	v_mov_b32_e32 v48, v123
	v_mov_b32_e32 v47, v123
	v_mov_b32_e32 v46, v123
	v_mov_b32_e32 v45, v123
	v_mov_b32_e32 v44, v123
	v_mov_b32_e32 v43, v123
	v_mov_b32_e32 v42, v123
	v_mov_b32_e32 v41, v123
	v_mov_b32_e32 v40, v123
	v_mov_b32_e32 v39, v123
	v_mov_b32_e32 v38, v123
	v_mov_b32_e32 v37, v123
	v_mov_b32_e32 v36, v123
	v_mov_b32_e32 v35, v123
	v_mov_b32_e32 v34, v123
	v_mov_b32_e32 v33, v123
	v_mov_b32_e32 v32, v123
	v_mov_b32_e32 v95, v123
	v_mov_b32_e32 v94, v123
	v_mov_b32_e32 v93, v123
	v_mov_b32_e32 v92, v123
	v_mov_b32_e32 v91, v123
	v_mov_b32_e32 v90, v123
	v_mov_b32_e32 v89, v123
	v_mov_b32_e32 v88, v123
	v_mov_b32_e32 v87, v123
	v_mov_b32_e32 v86, v123
	v_mov_b32_e32 v85, v123
	v_mov_b32_e32 v84, v123
	v_mov_b32_e32 v83, v123
	v_mov_b32_e32 v82, v123
	v_mov_b32_e32 v81, v123
	v_mov_b32_e32 v80, v123
	v_mov_b32_e32 v79, v123
	v_mov_b32_e32 v78, v123
	v_mov_b32_e32 v77, v123
	v_mov_b32_e32 v76, v123
	v_mov_b32_e32 v75, v123
	v_mov_b32_e32 v74, v123
	v_mov_b32_e32 v73, v123
	v_mov_b32_e32 v72, v123
	v_mov_b32_e32 v71, v123
	v_mov_b32_e32 v70, v123
	v_mov_b32_e32 v69, v123
	v_mov_b32_e32 v68, v123
	v_mov_b32_e32 v67, v123
	v_mov_b32_e32 v66, v123
	v_mov_b32_e32 v65, v123
	v_mov_b32_e32 v64, v123
	v_mov_b32_e32 v31, v123
	v_mov_b32_e32 v30, v123
	v_mov_b32_e32 v29, v123
	v_mov_b32_e32 v28, v123
	v_mov_b32_e32 v27, v123
	v_mov_b32_e32 v26, v123
	v_mov_b32_e32 v25, v123
	v_mov_b32_e32 v24, v123
	v_mov_b32_e32 v23, v123
	v_mov_b32_e32 v22, v123
	v_mov_b32_e32 v21, v123
	v_mov_b32_e32 v20, v123
	v_mov_b32_e32 v19, v123
	v_mov_b32_e32 v18, v123
	v_mov_b32_e32 v17, v123
	v_mov_b32_e32 v16, v123
	v_mov_b32_e32 v15, v123
	v_mov_b32_e32 v14, v123
	v_mov_b32_e32 v13, v123
	v_mov_b32_e32 v12, v123
	v_mov_b32_e32 v11, v123
	v_mov_b32_e32 v10, v123
	v_mov_b32_e32 v9, v123
	v_mov_b32_e32 v8, v123
	v_mov_b32_e32 v7, v123
	v_mov_b32_e32 v6, v123
	v_mov_b32_e32 v5, v123
	v_mov_b32_e32 v4, v123
	v_mov_b32_e32 v3, v123
	v_mov_b32_e32 v2, v123
	v_mov_b32_e32 v1, v123
	v_mov_b32_e32 v0, v123
	s_cbranch_vccnz .LBB0_625
	s_add_u32 s0, s0, 0x80
	s_addc_u32 s1, s1, 0
	s_add_u32 s36, s36, 0x100
	v_mov_b32_e32 v0, 0
	v_mov_b32_e32 v254, 0xc00
	s_addc_u32 s37, s37, 0
	s_mov_b32 s4, 0
	v_mov_b32_e32 v1, v0
	v_mov_b32_e32 v2, v0
	v_mov_b32_e32 v3, v0
	v_mov_b32_e32 v4, v0
	v_mov_b32_e32 v5, v0
	v_mov_b32_e32 v6, v0
	v_mov_b32_e32 v7, v0
	v_mov_b32_e32 v8, v0
	v_mov_b32_e32 v9, v0
	v_mov_b32_e32 v10, v0
	v_mov_b32_e32 v11, v0
	v_mov_b32_e32 v12, v0
	v_mov_b32_e32 v13, v0
	v_mov_b32_e32 v14, v0
	v_mov_b32_e32 v15, v0
	v_mov_b32_e32 v16, v0
	v_mov_b32_e32 v17, v0
	v_mov_b32_e32 v18, v0
	v_mov_b32_e32 v19, v0
	v_mov_b32_e32 v20, v0
	v_mov_b32_e32 v21, v0
	v_mov_b32_e32 v22, v0
	v_mov_b32_e32 v23, v0
	v_mov_b32_e32 v24, v0
	v_mov_b32_e32 v25, v0
	v_mov_b32_e32 v26, v0
	v_mov_b32_e32 v27, v0
	v_mov_b32_e32 v28, v0
	v_mov_b32_e32 v29, v0
	v_mov_b32_e32 v30, v0
	v_mov_b32_e32 v31, v0
	v_mov_b32_e32 v64, v0
	v_mov_b32_e32 v65, v0
	v_mov_b32_e32 v66, v0
	v_mov_b32_e32 v67, v0
	v_mov_b32_e32 v68, v0
	v_mov_b32_e32 v69, v0
	v_mov_b32_e32 v70, v0
	v_mov_b32_e32 v71, v0
	v_mov_b32_e32 v72, v0
	v_mov_b32_e32 v73, v0
	v_mov_b32_e32 v74, v0
	v_mov_b32_e32 v75, v0
	v_mov_b32_e32 v76, v0
	v_mov_b32_e32 v77, v0
	v_mov_b32_e32 v78, v0
	v_mov_b32_e32 v79, v0
	v_mov_b32_e32 v80, v0
	v_mov_b32_e32 v81, v0
	v_mov_b32_e32 v82, v0
	v_mov_b32_e32 v83, v0
	v_mov_b32_e32 v84, v0
	v_mov_b32_e32 v85, v0
	v_mov_b32_e32 v86, v0
	v_mov_b32_e32 v87, v0
	v_mov_b32_e32 v88, v0
	v_mov_b32_e32 v89, v0
	v_mov_b32_e32 v90, v0
	v_mov_b32_e32 v91, v0
	v_mov_b32_e32 v92, v0
	v_mov_b32_e32 v93, v0
	v_mov_b32_e32 v94, v0
	v_mov_b32_e32 v95, v0
	v_mov_b32_e32 v32, v0
	v_mov_b32_e32 v33, v0
	v_mov_b32_e32 v34, v0
	v_mov_b32_e32 v35, v0
	v_mov_b32_e32 v36, v0
	v_mov_b32_e32 v37, v0
	v_mov_b32_e32 v38, v0
	v_mov_b32_e32 v39, v0
	v_mov_b32_e32 v40, v0
	v_mov_b32_e32 v41, v0
	v_mov_b32_e32 v42, v0
	v_mov_b32_e32 v43, v0
	v_mov_b32_e32 v44, v0
	v_mov_b32_e32 v45, v0
	v_mov_b32_e32 v46, v0
	v_mov_b32_e32 v47, v0
	v_mov_b32_e32 v48, v0
	v_mov_b32_e32 v49, v0
	v_mov_b32_e32 v50, v0
	v_mov_b32_e32 v51, v0
	v_mov_b32_e32 v52, v0
	v_mov_b32_e32 v53, v0
	v_mov_b32_e32 v54, v0
	v_mov_b32_e32 v55, v0
	v_mov_b32_e32 v56, v0
	v_mov_b32_e32 v57, v0
	v_mov_b32_e32 v58, v0
	v_mov_b32_e32 v59, v0
	v_mov_b32_e32 v60, v0
	v_mov_b32_e32 v61, v0
	v_mov_b32_e32 v62, v0
	v_mov_b32_e32 v63, v0
	v_mov_b32_e32 v96, v0
	v_mov_b32_e32 v97, v0
	v_mov_b32_e32 v98, v0
	v_mov_b32_e32 v99, v0
	v_mov_b32_e32 v100, v0
	v_mov_b32_e32 v101, v0
	v_mov_b32_e32 v102, v0
	v_mov_b32_e32 v103, v0
	v_mov_b32_e32 v104, v0
	v_mov_b32_e32 v105, v0
	v_mov_b32_e32 v106, v0
	v_mov_b32_e32 v107, v0
	v_mov_b32_e32 v108, v0
	v_mov_b32_e32 v109, v0
	v_mov_b32_e32 v110, v0
	v_mov_b32_e32 v111, v0
	v_mov_b32_e32 v112, v0
	v_mov_b32_e32 v113, v0
	v_mov_b32_e32 v114, v0
	v_mov_b32_e32 v115, v0
	v_mov_b32_e32 v116, v0
	v_mov_b32_e32 v117, v0
	v_mov_b32_e32 v118, v0
	v_mov_b32_e32 v119, v0
	v_mov_b32_e32 v124, v0
	v_mov_b32_e32 v125, v0
	v_mov_b32_e32 v126, v0
	v_mov_b32_e32 v127, v0
	v_mov_b32_e32 v120, v0
	v_mov_b32_e32 v121, v0
	v_mov_b32_e32 v122, v0
	v_mov_b32_e32 v123, v0
	v_add_u32_e32 v250, 0x10000, v158
	v_add_u32_e32 v251, 0x14000, v158
	v_add_u32_e32 v252, 0x18000, v158
	v_add_u32_e32 v253, 0x1c000, v158
; #define PG8_STAGE(bufoff, gbase, voff) do { _Pragma("unroll") for (int _i = 0; _i < 2; ++_i) \
;         __builtin_amdgcn_global_load_lds((const unsigned*)((const char*)(gbase) + (voff)[_i]), (LAS unsigned*)(lds + (bufoff) + ldsw + _i * 8192), 16, 0, 0); } while (0)
; #define PG8_LDA(dst, b, h) do { _Pragma("unroll") for (int m = 0; m < 4; ++m) _Pragma("unroll") for (int k = 0; k < 2; ++k) dst[m][k] = *(const LAS bf16x8*)(lds + PG8_SA(b, h) + aoff + m * 2048 + k * 1024); } while (0)
; #define PG8_LDB(dst, b, h) do { _Pragma("unroll") for (int n = 0; n < 2; ++n) _Pragma("unroll") for (int k = 0; k < 2; ++k) dst[n][k] = *(const LAS bf16x8*)(lds + PG8_SB(b, h) + boff + n * 2048 + k * 1024); } while (0)
; #define PG8_MMA(ai, bj, At, Bt) do { __builtin_amdgcn_s_setprio(1); _Pragma("unroll") for (int m = 0; m < 4; ++m) _Pragma("unroll") for (int n = 0; n < 2; ++n) _Pragma("unroll") for (int k = 0; k < 2; ++k) \
;         acc[ai][bj][m][n] = __builtin_amdgcn_mfma_f32_16x16x32_bf16(Bt[n][k], At[m][k], acc[ai][bj][m][n], 0, 0, 0); __builtin_amdgcn_s_setprio(0); } while (0)
; #define PG8_WAIT_V(n) asm volatile("s_waitcnt vmcnt(" #n ")" ::: "memory")
; #define PG8_WAIT_L(n) asm volatile("s_waitcnt lgkmcnt(" #n ")" ::: "memory")
; #define PG8_BAR __builtin_amdgcn_s_barrier()
; #define PG8_SCHED __builtin_amdgcn_sched_barrier(0)
; template <class EpiT, class Sched>
; __device__ __forceinline__ void gemm_phase(LAS unsigned char* lds, const Gemm g, const Sched& S, const EpiT& E, int wv) {
;     ...
;         for (int t = 0; t < nt; t += 2) {
;             const bool last = (t == nt - 2);
;             const char* a1 = cA + (size_t)(t + 1) * kstep;
;             const char* a2 = last ? nA : cA + (size_t)(t + 2) * kstep; const char* b2 = last ? nB : cB + (size_t)(t + 2) * kstep;
;             const char* a3 = a2 + kstep; const char* b3 = b2 + kstep;
;             PG8_LDB(B0, 0, 0); PG8_LDB(B1, 0, 1); PG8_SCHED; PG8_LDA(At, 0, 0); PG8_STAGE(PG8_SA(1, 1), a1 + hstepA, voffA);
;             PG8_WAIT_V(8); PG8_WAIT_L(0); PG8_BAR; PG8_MMA(0, 0, At, B0); PG8_MMA(0, 1, At, B1); PG8_BAR; PG8_SCHED;
;             PG8_LDA(At, 0, 1); PG8_STAGE(PG8_SB(0, 0), b2, voffB); PG8_STAGE(PG8_SB(0, 1), b2 + hstepB, voffB); PG8_STAGE(PG8_SA(0, 0), a2, voffA);
;             PG8_WAIT_V(8); PG8_WAIT_L(0); PG8_BAR; PG8_MMA(1, 0, At, B0); PG8_MMA(1, 1, At, B1); PG8_BAR; PG8_SCHED;
.LBB0_623:
	s_add_i32 s39, s4, 2
	s_add_u32 s63, s0, 0x80
	s_addc_u32 s5, s1, 0
	s_add_i32 s67, 0, 0x10000
	s_cmp_eq_u32 s53, s4
	s_cselect_b32 s5, s31, s5
	s_cselect_b32 s4, s30, s63
	s_cselect_b32 s65, s35, s37
	s_cselect_b32 s64, s34, s36
	s_add_i32 s63, 0, 0x14000
	ds_read_b128 v[128:131], v250
	ds_read_b128 v[132:135], v250 offset:1024
	ds_read_b128 v[136:139], v250 offset:2048
	ds_read_b128 v[150:153], v250 offset:3072
	ds_read_b128 v[154:157], v251
	ds_read_b128 v[160:163], v251 offset:1024
	ds_read_b128 v[164:167], v251 offset:2048
	ds_read_b128 v[168:171], v251 offset:3072
	v_lshl_add_u64 v[216:217], s[0:1], 0, v[146:147]
	s_add_i32 m0, s46, 0xc000
	ds_read_b128 v[172:175], v159
	ds_read_b128 v[176:179], v159 offset:1024
	ds_read_b128 v[180:183], v159 offset:2048
	ds_read_b128 v[184:187], v159 offset:3072
	ds_read_b128 v[188:191], v159 offset:4096
	ds_read_b128 v[204:207], v159 offset:5120
	ds_read_b128 v[208:211], v159 offset:6144
	ds_read_b128 v[212:215], v159 offset:7168
	global_load_lds_dwordx4 v[216:217], off
	v_lshl_add_u64 v[216:217], s[0:1], 0, v[148:149]
	s_add_i32 m0, s46, 0xe000
	s_nop 0
	global_load_lds_dwordx4 v[216:217], off
	s_waitcnt vmcnt(8)
	s_waitcnt lgkmcnt(0)
	s_barrier
	s_setprio 1
	s_waitcnt lgkmcnt(0)
	v_mfma_f32_16x16x32_bf16 v[120:123], v[128:131], v[172:175], v[120:123]
	v_mfma_f32_16x16x32_bf16 v[124:127], v[136:139], v[172:175], v[124:127]
	v_mfma_f32_16x16x32_bf16 v[116:119], v[128:131], v[180:183], v[116:119]
	v_mfma_f32_16x16x32_bf16 v[112:115], v[136:139], v[180:183], v[112:115]
	v_mfma_f32_16x16x32_bf16 v[108:111], v[128:131], v[188:191], v[108:111]
	v_mfma_f32_16x16x32_bf16 v[104:107], v[136:139], v[188:191], v[104:107]
	v_mfma_f32_16x16x32_bf16 v[100:103], v[128:131], v[208:211], v[100:103]
	v_mfma_f32_16x16x32_bf16 v[96:99], v[136:139], v[208:211], v[96:99]
	v_mfma_f32_16x16x32_bf16 v[120:123], v[132:135], v[176:179], v[120:123]
	v_mfma_f32_16x16x32_bf16 v[124:127], v[150:153], v[176:179], v[124:127]
	v_mfma_f32_16x16x32_bf16 v[116:119], v[132:135], v[184:187], v[116:119]
	v_mfma_f32_16x16x32_bf16 v[112:115], v[150:153], v[184:187], v[112:115]
	v_mfma_f32_16x16x32_bf16 v[108:111], v[132:135], v[204:207], v[108:111]
	v_mfma_f32_16x16x32_bf16 v[104:107], v[150:153], v[204:207], v[104:107]
	v_mfma_f32_16x16x32_bf16 v[100:103], v[132:135], v[212:215], v[100:103]
	v_mfma_f32_16x16x32_bf16 v[96:99], v[150:153], v[212:215], v[96:99]
	s_setprio 0
	s_setprio 1
	v_mfma_f32_16x16x32_bf16 v[60:63], v[154:157], v[172:175], v[60:63]
	v_mfma_f32_16x16x32_bf16 v[56:59], v[164:167], v[172:175], v[56:59]
	v_mfma_f32_16x16x32_bf16 v[52:55], v[154:157], v[180:183], v[52:55]
	v_mfma_f32_16x16x32_bf16 v[48:51], v[164:167], v[180:183], v[48:51]
	v_mfma_f32_16x16x32_bf16 v[44:47], v[154:157], v[188:191], v[44:47]
	v_mfma_f32_16x16x32_bf16 v[40:43], v[164:167], v[188:191], v[40:43]
	v_mfma_f32_16x16x32_bf16 v[36:39], v[154:157], v[208:211], v[36:39]
	v_mfma_f32_16x16x32_bf16 v[32:35], v[164:167], v[208:211], v[32:35]
	v_mfma_f32_16x16x32_bf16 v[60:63], v[160:163], v[176:179], v[60:63]
	v_mfma_f32_16x16x32_bf16 v[56:59], v[168:171], v[176:179], v[56:59]
	v_mfma_f32_16x16x32_bf16 v[52:55], v[160:163], v[184:187], v[52:55]
	v_mfma_f32_16x16x32_bf16 v[48:51], v[168:171], v[184:187], v[48:51]
	v_mfma_f32_16x16x32_bf16 v[44:47], v[160:163], v[204:207], v[44:47]
	v_mfma_f32_16x16x32_bf16 v[40:43], v[168:171], v[204:207], v[40:43]
	v_mfma_f32_16x16x32_bf16 v[36:39], v[160:163], v[212:215], v[36:39]
	v_mfma_f32_16x16x32_bf16 v[32:35], v[168:171], v[212:215], v[32:35]
	s_setprio 0
	s_barrier
	s_add_i32 s67, s67, s45
	v_lshl_add_u64 v[216:217], s[64:65], 0, v[192:193]
	s_mov_b32 m0, s67
	ds_read_b128 v[172:175], v159 offset:16384
	ds_read_b128 v[176:179], v159 offset:17408
	ds_read_b128 v[180:183], v159 offset:18432
	ds_read_b128 v[184:187], v159 offset:19456
	ds_read_b128 v[188:191], v159 offset:20480
	ds_read_b128 v[204:207], v159 offset:21504
	ds_read_b128 v[208:211], v159 offset:22528
	ds_read_b128 v[212:215], v159 offset:23552
	global_load_lds_dwordx4 v[216:217], off
	s_add_i32 m0, s67, 0x2000
	v_lshl_add_u64 v[218:219], s[64:65], 0, v[144:145]
	s_add_u32 s64, s64, s6
	s_addc_u32 s65, s65, s7
	s_add_i32 s63, s63, s45
	global_load_lds_dwordx4 v[218:219], off
	v_lshl_add_u64 v[220:221], s[64:65], 0, v[192:193]
	s_mov_b32 m0, s63
	v_lshl_add_u64 v[222:223], s[64:65], 0, v[144:145]
	global_load_lds_dwordx4 v[220:221], off
	s_add_i32 m0, s63, 0x2000
	v_lshl_add_u64 v[232:233], s[4:5], 0, v[140:141]
	global_load_lds_dwordx4 v[222:223], off
	s_mov_b32 m0, s46
	v_lshl_add_u64 v[234:235], s[4:5], 0, v[142:143]
	global_load_lds_dwordx4 v[232:233], off
	s_mov_b32 m0, s47
	s_nop 0
	global_load_lds_dwordx4 v[234:235], off
	s_waitcnt vmcnt(8)
	s_waitcnt lgkmcnt(0)
	s_barrier
; #define PG8_STAGE(bufoff, gbase, voff) do { _Pragma("unroll") for (int _i = 0; _i < 2; ++_i) \
;         __builtin_amdgcn_global_load_lds((const unsigned*)((const char*)(gbase) + (voff)[_i]), (LAS unsigned*)(lds + (bufoff) + ldsw + _i * 8192), 16, 0, 0); } while (0)
; #define PG8_LDA(dst, b, h) do { _Pragma("unroll") for (int m = 0; m < 4; ++m) _Pragma("unroll") for (int k = 0; k < 2; ++k) dst[m][k] = *(const LAS bf16x8*)(lds + PG8_SA(b, h) + aoff + m * 2048 + k * 1024); } while (0)
; #define PG8_LDB(dst, b, h) do { _Pragma("unroll") for (int n = 0; n < 2; ++n) _Pragma("unroll") for (int k = 0; k < 2; ++k) dst[n][k] = *(const LAS bf16x8*)(lds + PG8_SB(b, h) + boff + n * 2048 + k * 1024); } while (0)
; #define PG8_MMA(ai, bj, At, Bt) do { __builtin_amdgcn_s_setprio(1); _Pragma("unroll") for (int m = 0; m < 4; ++m) _Pragma("unroll") for (int n = 0; n < 2; ++n) _Pragma("unroll") for (int k = 0; k < 2; ++k) \
;         acc[ai][bj][m][n] = __builtin_amdgcn_mfma_f32_16x16x32_bf16(Bt[n][k], At[m][k], acc[ai][bj][m][n], 0, 0, 0); __builtin_amdgcn_s_setprio(0); } while (0)
; #define PG8_WAIT_V(n) asm volatile("s_waitcnt vmcnt(" #n ")" ::: "memory")
; #define PG8_WAIT_L(n) asm volatile("s_waitcnt lgkmcnt(" #n ")" ::: "memory")
; #define PG8_BAR __builtin_amdgcn_s_barrier()
; #define PG8_SCHED __builtin_amdgcn_sched_barrier(0)
; template <class EpiT, class Sched>
; __device__ __forceinline__ void gemm_phase(LAS unsigned char* lds, const Gemm g, const Sched& S, const EpiT& E, int wv) {
;     ...
;             PG8_WAIT_V(8); PG8_WAIT_L(0); PG8_BAR; PG8_MMA(1, 0, At, B0); PG8_MMA(1, 1, At, B1); PG8_BAR; PG8_SCHED;
;             PG8_LDB(B0, 1, 0); PG8_LDB(B1, 1, 1); PG8_SCHED; PG8_LDA(At, 1, 0); PG8_STAGE(PG8_SA(0, 1), a2 + hstepA, voffA);
;             PG8_WAIT_V(8); PG8_WAIT_L(0); PG8_BAR; PG8_MMA(0, 0, At, B0); PG8_MMA(0, 1, At, B1); PG8_BAR; PG8_SCHED;
	s_setprio 1
	s_waitcnt lgkmcnt(0)
	v_mfma_f32_16x16x32_bf16 v[92:95], v[128:131], v[172:175], v[92:95]
	v_mfma_f32_16x16x32_bf16 v[88:91], v[136:139], v[172:175], v[88:91]
	v_mfma_f32_16x16x32_bf16 v[84:87], v[128:131], v[180:183], v[84:87]
	v_mfma_f32_16x16x32_bf16 v[80:83], v[136:139], v[180:183], v[80:83]
	v_mfma_f32_16x16x32_bf16 v[76:79], v[128:131], v[188:191], v[76:79]
	v_mfma_f32_16x16x32_bf16 v[72:75], v[136:139], v[188:191], v[72:75]
	v_mfma_f32_16x16x32_bf16 v[68:71], v[128:131], v[208:211], v[68:71]
	v_mfma_f32_16x16x32_bf16 v[64:67], v[136:139], v[208:211], v[64:67]
	v_mfma_f32_16x16x32_bf16 v[92:95], v[132:135], v[176:179], v[92:95]
	v_mfma_f32_16x16x32_bf16 v[88:91], v[150:153], v[176:179], v[88:91]
	v_mfma_f32_16x16x32_bf16 v[84:87], v[132:135], v[184:187], v[84:87]
	v_mfma_f32_16x16x32_bf16 v[80:83], v[150:153], v[184:187], v[80:83]
	v_mfma_f32_16x16x32_bf16 v[76:79], v[132:135], v[204:207], v[76:79]
	v_mfma_f32_16x16x32_bf16 v[72:75], v[150:153], v[204:207], v[72:75]
	v_mfma_f32_16x16x32_bf16 v[68:71], v[132:135], v[212:215], v[68:71]
	v_mfma_f32_16x16x32_bf16 v[64:67], v[150:153], v[212:215], v[64:67]
	s_setprio 0
	s_setprio 1
	v_mfma_f32_16x16x32_bf16 v[28:31], v[154:157], v[172:175], v[28:31]
	v_mfma_f32_16x16x32_bf16 v[24:27], v[164:167], v[172:175], v[24:27]
	v_mfma_f32_16x16x32_bf16 v[20:23], v[154:157], v[180:183], v[20:23]
	v_mfma_f32_16x16x32_bf16 v[16:19], v[164:167], v[180:183], v[16:19]
	v_mfma_f32_16x16x32_bf16 v[12:15], v[154:157], v[188:191], v[12:15]
	v_mfma_f32_16x16x32_bf16 v[8:11], v[164:167], v[188:191], v[8:11]
	v_mfma_f32_16x16x32_bf16 v[4:7], v[154:157], v[208:211], v[4:7]
	v_mfma_f32_16x16x32_bf16 v[0:3], v[164:167], v[208:211], v[0:3]
	v_mfma_f32_16x16x32_bf16 v[28:31], v[160:163], v[176:179], v[28:31]
	v_mfma_f32_16x16x32_bf16 v[24:27], v[168:171], v[176:179], v[24:27]
	v_mfma_f32_16x16x32_bf16 v[20:23], v[160:163], v[184:187], v[20:23]
	v_mfma_f32_16x16x32_bf16 v[16:19], v[168:171], v[184:187], v[16:19]
	v_mfma_f32_16x16x32_bf16 v[12:15], v[160:163], v[204:207], v[12:15]
	v_mfma_f32_16x16x32_bf16 v[8:11], v[168:171], v[204:207], v[8:11]
	v_mfma_f32_16x16x32_bf16 v[4:7], v[160:163], v[212:215], v[4:7]
	v_mfma_f32_16x16x32_bf16 v[0:3], v[168:171], v[212:215], v[0:3]
	s_setprio 0
	s_barrier
	s_add_i32 s63, 0, 0x18000
	s_add_i32 s64, 0, 0x1c000
	ds_read_b128 v[128:131], v252
	ds_read_b128 v[132:135], v252 offset:1024
	ds_read_b128 v[136:139], v252 offset:2048
	ds_read_b128 v[150:153], v252 offset:3072
	ds_read_b128 v[154:157], v253
	ds_read_b128 v[160:163], v253 offset:1024
	ds_read_b128 v[164:167], v253 offset:2048
	ds_read_b128 v[168:171], v253 offset:3072
	s_add_u32 s4, s4, s6
	s_addc_u32 s5, s5, s7
	s_mov_b32 m0, s48
	v_lshl_add_u64 v[240:241], s[4:5], 0, v[140:141]
	ds_read_b128 v[172:175], v159 offset:32768
	ds_read_b128 v[176:179], v159 offset:33792
	ds_read_b128 v[180:183], v159 offset:34816
	ds_read_b128 v[184:187], v159 offset:35840
	ds_read_b128 v[188:191], v159 offset:36864
	ds_read_b128 v[204:207], v159 offset:37888
	ds_read_b128 v[208:211], v159 offset:38912
	ds_read_b128 v[212:215], v159 offset:39936
	global_load_lds_dwordx4 v[240:241], off
	v_lshl_add_u64 v[240:241], s[4:5], 0, v[142:143]
	s_mov_b32 m0, s49
	s_nop 0
	global_load_lds_dwordx4 v[240:241], off
	s_waitcnt vmcnt(8)
	s_waitcnt lgkmcnt(0)
	s_barrier
	s_setprio 1
	s_waitcnt lgkmcnt(0)
	v_mfma_f32_16x16x32_bf16 v[120:123], v[128:131], v[172:175], v[120:123]
	v_mfma_f32_16x16x32_bf16 v[124:127], v[136:139], v[172:175], v[124:127]
	v_mfma_f32_16x16x32_bf16 v[116:119], v[128:131], v[180:183], v[116:119]
	v_mfma_f32_16x16x32_bf16 v[112:115], v[136:139], v[180:183], v[112:115]
	v_mfma_f32_16x16x32_bf16 v[108:111], v[128:131], v[188:191], v[108:111]
	v_mfma_f32_16x16x32_bf16 v[104:107], v[136:139], v[188:191], v[104:107]
	v_mfma_f32_16x16x32_bf16 v[100:103], v[128:131], v[208:211], v[100:103]
	v_mfma_f32_16x16x32_bf16 v[96:99], v[136:139], v[208:211], v[96:99]
	v_mfma_f32_16x16x32_bf16 v[120:123], v[132:135], v[176:179], v[120:123]
	v_mfma_f32_16x16x32_bf16 v[124:127], v[150:153], v[176:179], v[124:127]
	v_mfma_f32_16x16x32_bf16 v[116:119], v[132:135], v[184:187], v[116:119]
	v_mfma_f32_16x16x32_bf16 v[112:115], v[150:153], v[184:187], v[112:115]
	v_mfma_f32_16x16x32_bf16 v[108:111], v[132:135], v[204:207], v[108:111]
	v_mfma_f32_16x16x32_bf16 v[104:107], v[150:153], v[204:207], v[104:107]
	v_mfma_f32_16x16x32_bf16 v[100:103], v[132:135], v[212:215], v[100:103]
	v_mfma_f32_16x16x32_bf16 v[96:99], v[150:153], v[212:215], v[96:99]
	s_setprio 0
	s_setprio 1
	v_mfma_f32_16x16x32_bf16 v[60:63], v[154:157], v[172:175], v[60:63]
	v_mfma_f32_16x16x32_bf16 v[56:59], v[164:167], v[172:175], v[56:59]
	v_mfma_f32_16x16x32_bf16 v[52:55], v[154:157], v[180:183], v[52:55]
	v_mfma_f32_16x16x32_bf16 v[48:51], v[164:167], v[180:183], v[48:51]
	v_mfma_f32_16x16x32_bf16 v[44:47], v[154:157], v[188:191], v[44:47]
	v_mfma_f32_16x16x32_bf16 v[40:43], v[164:167], v[188:191], v[40:43]
	v_mfma_f32_16x16x32_bf16 v[36:39], v[154:157], v[208:211], v[36:39]
	v_mfma_f32_16x16x32_bf16 v[32:35], v[164:167], v[208:211], v[32:35]
	v_mfma_f32_16x16x32_bf16 v[60:63], v[160:163], v[176:179], v[60:63]
	v_mfma_f32_16x16x32_bf16 v[56:59], v[168:171], v[176:179], v[56:59]
	v_mfma_f32_16x16x32_bf16 v[52:55], v[160:163], v[184:187], v[52:55]
	v_mfma_f32_16x16x32_bf16 v[48:51], v[168:171], v[184:187], v[48:51]
	v_mfma_f32_16x16x32_bf16 v[44:47], v[160:163], v[204:207], v[44:47]
	v_mfma_f32_16x16x32_bf16 v[40:43], v[168:171], v[204:207], v[40:43]
	v_mfma_f32_16x16x32_bf16 v[36:39], v[160:163], v[212:215], v[36:39]
	v_mfma_f32_16x16x32_bf16 v[32:35], v[168:171], v[212:215], v[32:35]
	s_setprio 0
	s_barrier
; #define PG8_STAGE(bufoff, gbase, voff) do { _Pragma("unroll") for (int _i = 0; _i < 2; ++_i) \
;         __builtin_amdgcn_global_load_lds((const unsigned*)((const char*)(gbase) + (voff)[_i]), (LAS unsigned*)(lds + (bufoff) + ldsw + _i * 8192), 16, 0, 0); } while (0)
; #define PG8_LDA(dst, b, h) do { _Pragma("unroll") for (int m = 0; m < 4; ++m) _Pragma("unroll") for (int k = 0; k < 2; ++k) dst[m][k] = *(const LAS bf16x8*)(lds + PG8_SA(b, h) + aoff + m * 2048 + k * 1024); } while (0)
; #define PG8_MMA(ai, bj, At, Bt) do { __builtin_amdgcn_s_setprio(1); _Pragma("unroll") for (int m = 0; m < 4; ++m) _Pragma("unroll") for (int n = 0; n < 2; ++n) _Pragma("unroll") for (int k = 0; k < 2; ++k) \
;         acc[ai][bj][m][n] = __builtin_amdgcn_mfma_f32_16x16x32_bf16(Bt[n][k], At[m][k], acc[ai][bj][m][n], 0, 0, 0); __builtin_amdgcn_s_setprio(0); } while (0)
; #define PG8_WAIT_V(n) asm volatile("s_waitcnt vmcnt(" #n ")" ::: "memory")
; #define PG8_WAIT_L(n) asm volatile("s_waitcnt lgkmcnt(" #n ")" ::: "memory")
; #define PG8_BAR __builtin_amdgcn_s_barrier()
; #define PG8_SCHED __builtin_amdgcn_sched_barrier(0)
; template <class EpiT, class Sched>
; __device__ __forceinline__ void gemm_phase(LAS unsigned char* lds, const Gemm g, const Sched& S, const EpiT& E, int wv) {
;     ...
;             PG8_LDA(At, 1, 1); PG8_STAGE(PG8_SB(1, 0), b3, voffB); PG8_STAGE(PG8_SB(1, 1), b3 + hstepB, voffB); PG8_STAGE(PG8_SA(1, 0), a3, voffA);
;             PG8_WAIT_V(8); PG8_WAIT_L(0); PG8_BAR; PG8_MMA(1, 0, At, B0); PG8_MMA(1, 1, At, B1); PG8_BAR; PG8_SCHED;
;         }
	s_add_i32 s4, s63, s45
	v_lshl_add_u64 v[216:217], v[216:217], 0, s[92:93]
	s_mov_b32 m0, s4
	ds_read_b128 v[172:175], v159 offset:49152
	ds_read_b128 v[176:179], v159 offset:50176
	ds_read_b128 v[180:183], v159 offset:51200
	ds_read_b128 v[184:187], v159 offset:52224
	ds_read_b128 v[188:191], v159 offset:53248
	ds_read_b128 v[204:207], v159 offset:54272
	ds_read_b128 v[208:211], v159 offset:55296
	ds_read_b128 v[212:215], v159 offset:56320
	global_load_lds_dwordx4 v[216:217], off
	v_lshl_add_u64 v[216:217], v[218:219], 0, s[92:93]
	s_add_i32 m0, s4, 0x2000
	s_add_i32 s4, s64, s45
	global_load_lds_dwordx4 v[216:217], off
	v_lshl_add_u64 v[216:217], v[220:221], 0, s[92:93]
	s_mov_b32 m0, s4
	s_nop 0
	global_load_lds_dwordx4 v[216:217], off
	v_lshl_add_u64 v[216:217], v[222:223], 0, s[92:93]
	s_add_i32 m0, s4, 0x2000
	s_nop 0
	global_load_lds_dwordx4 v[216:217], off
	v_lshl_add_u64 v[216:217], v[232:233], 0, s[92:93]
	s_mov_b32 m0, s50
	s_nop 0
	global_load_lds_dwordx4 v[216:217], off
	v_lshl_add_u64 v[216:217], v[234:235], 0, s[92:93]
	s_mov_b32 m0, s51
	s_nop 0
	global_load_lds_dwordx4 v[216:217], off
	s_waitcnt vmcnt(8)
	s_waitcnt lgkmcnt(0)
	s_barrier
	s_setprio 1
	s_waitcnt lgkmcnt(0)
	v_mfma_f32_16x16x32_bf16 v[92:95], v[128:131], v[172:175], v[92:95]
	v_mfma_f32_16x16x32_bf16 v[88:91], v[136:139], v[172:175], v[88:91]
	v_mfma_f32_16x16x32_bf16 v[84:87], v[128:131], v[180:183], v[84:87]
	v_mfma_f32_16x16x32_bf16 v[80:83], v[136:139], v[180:183], v[80:83]
	v_mfma_f32_16x16x32_bf16 v[76:79], v[128:131], v[188:191], v[76:79]
	v_mfma_f32_16x16x32_bf16 v[72:75], v[136:139], v[188:191], v[72:75]
	v_mfma_f32_16x16x32_bf16 v[68:71], v[128:131], v[208:211], v[68:71]
	v_mfma_f32_16x16x32_bf16 v[64:67], v[136:139], v[208:211], v[64:67]
	v_mfma_f32_16x16x32_bf16 v[92:95], v[132:135], v[176:179], v[92:95]
	v_mfma_f32_16x16x32_bf16 v[88:91], v[150:153], v[176:179], v[88:91]
	v_mfma_f32_16x16x32_bf16 v[84:87], v[132:135], v[184:187], v[84:87]
	v_mfma_f32_16x16x32_bf16 v[80:83], v[150:153], v[184:187], v[80:83]
	v_mfma_f32_16x16x32_bf16 v[76:79], v[132:135], v[204:207], v[76:79]
	v_mfma_f32_16x16x32_bf16 v[72:75], v[150:153], v[204:207], v[72:75]
	v_mfma_f32_16x16x32_bf16 v[68:71], v[132:135], v[212:215], v[68:71]
	v_mfma_f32_16x16x32_bf16 v[64:67], v[150:153], v[212:215], v[64:67]
	s_setprio 0
	s_setprio 1
	v_mfma_f32_16x16x32_bf16 v[28:31], v[154:157], v[172:175], v[28:31]
	v_mfma_f32_16x16x32_bf16 v[24:27], v[164:167], v[172:175], v[24:27]
	v_mfma_f32_16x16x32_bf16 v[20:23], v[154:157], v[180:183], v[20:23]
	v_mfma_f32_16x16x32_bf16 v[16:19], v[164:167], v[180:183], v[16:19]
	v_mfma_f32_16x16x32_bf16 v[12:15], v[154:157], v[188:191], v[12:15]
	v_mfma_f32_16x16x32_bf16 v[8:11], v[164:167], v[188:191], v[8:11]
	v_mfma_f32_16x16x32_bf16 v[4:7], v[154:157], v[208:211], v[4:7]
	v_mfma_f32_16x16x32_bf16 v[0:3], v[164:167], v[208:211], v[0:3]
	v_mfma_f32_16x16x32_bf16 v[28:31], v[160:163], v[176:179], v[28:31]
	v_mfma_f32_16x16x32_bf16 v[24:27], v[168:171], v[176:179], v[24:27]
	v_mfma_f32_16x16x32_bf16 v[20:23], v[160:163], v[184:187], v[20:23]
	v_mfma_f32_16x16x32_bf16 v[16:19], v[168:171], v[184:187], v[16:19]
	v_mfma_f32_16x16x32_bf16 v[12:15], v[160:163], v[204:207], v[12:15]
	v_mfma_f32_16x16x32_bf16 v[8:11], v[168:171], v[204:207], v[8:11]
	v_mfma_f32_16x16x32_bf16 v[4:7], v[160:163], v[212:215], v[4:7]
	v_mfma_f32_16x16x32_bf16 v[0:3], v[168:171], v[212:215], v[0:3]
	s_setprio 0
	s_barrier
	s_add_u32 s0, s0, 0x100
	s_addc_u32 s1, s1, 0
	s_add_u32 s36, s36, 0x100
	s_addc_u32 s37, s37, 0
	s_cmp_ge_i32 s39, s52
	s_mov_b32 s4, s39
	s_cbranch_scc0 .LBB0_623
	v_readlane_b32 s67, v255, 5

; #define PG8_STAGE(bufoff, gbase, voff) do { _Pragma("unroll") for (int _i = 0; _i < 2; ++_i) \
;         __builtin_amdgcn_global_load_lds((const unsigned*)((const char*)(gbase) + (voff)[_i]), (LAS unsigned*)(lds + (bufoff) + ldsw + _i * 8192), 16, 0, 0); } while (0)
; #define PG8_LDA(dst, b, h) do { _Pragma("unroll") for (int m = 0; m < 4; ++m) _Pragma("unroll") for (int k = 0; k < 2; ++k) dst[m][k] = *(const LAS bf16x8*)(lds + PG8_SA(b, h) + aoff + m * 2048 + k * 1024); } while (0)
; #define PG8_LDB(dst, b, h) do { _Pragma("unroll") for (int n = 0; n < 2; ++n) _Pragma("unroll") for (int k = 0; k < 2; ++k) dst[n][k] = *(const LAS bf16x8*)(lds + PG8_SB(b, h) + boff + n * 2048 + k * 1024); } while (0)
; #define PG8_MMA(ai, bj, At, Bt) do { __builtin_amdgcn_s_setprio(1); _Pragma("unroll") for (int m = 0; m < 4; ++m) _Pragma("unroll") for (int n = 0; n < 2; ++n) _Pragma("unroll") for (int k = 0; k < 2; ++k) \
;         acc[ai][bj][m][n] = __builtin_amdgcn_mfma_f32_16x16x32_bf16(Bt[n][k], At[m][k], acc[ai][bj][m][n], 0, 0, 0); __builtin_amdgcn_s_setprio(0); } while (0)
; template <class EpiT, class Sched>
; __device__ __forceinline__ void gemm_phase(LAS unsigned char* lds, const Gemm g, const Sched& S, const EpiT& E, int wv) {
;     ...
;         const bool has_next = S.next(ui + 1, nxt);
;         const char* nA = has_next ? (const char*)g.A + (size_t)nxt.pm * tstepA + (size_t)(nxt.pn >> g.zshift) * g.zA : cA; const char* nB = has_next ? (const char*)g.Bt + (size_t)nxt.pn * tstepB : cB;
;         for (int t = 0; t < nt; t += 2) {
;             const bool last = (t == nt - 2);
;             const char* a1 = cA + (size_t)(t + 1) * kstep;
;             const char* a2 = last ? nA : cA + (size_t)(t + 2) * kstep; const char* b2 = last ? nB : cB + (size_t)(t + 2) * kstep;
;             const char* a3 = a2 + kstep; const char* b3 = b2 + kstep;
;             PG8_LDB(B0, 0, 0); PG8_LDB(B1, 0, 1); PG8_SCHED; PG8_LDA(At, 0, 0); PG8_STAGE(PG8_SA(1, 1), a1 + hstepA, voffA);
;             PG8_WAIT_V(8); PG8_WAIT_L(0); PG8_BAR; PG8_MMA(0, 0, At, B0); PG8_MMA(0, 1, At, B1); PG8_BAR; PG8_SCHED;
;     ...
; #pragma unroll
;         for (int a = 0; a < 2; ++a)
; #pragma unroll
;             for (int b = 0; b < 2; ++b)
; #pragma unroll
;                 for (int m = 0; m < 4; ++m)
; #pragma unroll
;                     for (int n = 0; n < 2; ++n) acc[a][b][m][n] = (f32x4){0.f, 0.f, 0.f, 0.f};
.LBB0_1041:
	s_ashr_i32 s15, s14, 31
	s_lshl_b64 s[16:17], s[14:15], 20
	s_add_u32 s1, s29, s16
	s_addc_u32 s13, s30, s17
	s_ashr_i32 s16, s12, 2
	s_ashr_i32 s17, s16, 31
	s_lshl_b64 s[16:17], s[16:17], 10
	s_add_u32 s16, s1, s16
	s_addc_u32 s17, s13, s17
	s_and_b64 s[18:19], s[2:3], exec
	s_cselect_b32 s1, s17, s23
	s_cselect_b32 s15, s16, s22
	s_ashr_i32 s13, s12, 31
	s_lshl_b64 s[18:19], s[12:13], 18
	s_add_u32 s18, s31, s18
	s_addc_u32 s19, s38, s19
	s_and_b64 s[26:27], s[2:3], exec
	s_cselect_b32 s13, s19, s25
	s_cselect_b32 s33, s18, s24
	s_add_u32 s22, s22, 0x80080
	s_addc_u32 s23, s23, 0
	s_add_u32 s53, s24, 0x100
	v_mov_b32_e32 v0, 0
	s_addc_u32 s54, s25, 0
	s_mov_b32 s55, -2
	v_mov_b32_e32 v1, v0
	v_mov_b32_e32 v2, v0
	v_mov_b32_e32 v3, v0
	v_mov_b32_e32 v4, v0
	v_mov_b32_e32 v5, v0
	v_mov_b32_e32 v6, v0
	v_mov_b32_e32 v7, v0
	v_mov_b32_e32 v8, v0
	v_mov_b32_e32 v9, v0
	v_mov_b32_e32 v10, v0
	v_mov_b32_e32 v11, v0
	v_mov_b32_e32 v12, v0
	v_mov_b32_e32 v13, v0
	v_mov_b32_e32 v14, v0
	v_mov_b32_e32 v15, v0
	v_mov_b32_e32 v16, v0
	v_mov_b32_e32 v17, v0
	v_mov_b32_e32 v18, v0
	v_mov_b32_e32 v19, v0
	v_mov_b32_e32 v20, v0
	v_mov_b32_e32 v21, v0
	v_mov_b32_e32 v22, v0
	v_mov_b32_e32 v23, v0
	v_mov_b32_e32 v24, v0
	v_mov_b32_e32 v25, v0
	v_mov_b32_e32 v26, v0
	v_mov_b32_e32 v27, v0
	v_mov_b32_e32 v28, v0
	v_mov_b32_e32 v29, v0
	v_mov_b32_e32 v30, v0
	v_mov_b32_e32 v31, v0
	v_mov_b32_e32 v64, v0
	v_mov_b32_e32 v65, v0
	v_mov_b32_e32 v66, v0
	v_mov_b32_e32 v67, v0
	v_mov_b32_e32 v68, v0
	v_mov_b32_e32 v69, v0
	v_mov_b32_e32 v70, v0
	v_mov_b32_e32 v71, v0
	v_mov_b32_e32 v72, v0
	v_mov_b32_e32 v73, v0
	v_mov_b32_e32 v74, v0
	v_mov_b32_e32 v75, v0
	v_mov_b32_e32 v76, v0
	v_mov_b32_e32 v77, v0
	v_mov_b32_e32 v78, v0
	v_mov_b32_e32 v79, v0
	v_mov_b32_e32 v80, v0
	v_mov_b32_e32 v81, v0
	v_mov_b32_e32 v82, v0
	v_mov_b32_e32 v83, v0
	v_mov_b32_e32 v84, v0
	v_mov_b32_e32 v85, v0
	v_mov_b32_e32 v86, v0
	v_mov_b32_e32 v87, v0
	v_mov_b32_e32 v88, v0
	v_mov_b32_e32 v89, v0
	v_mov_b32_e32 v90, v0
	v_mov_b32_e32 v91, v0
	v_mov_b32_e32 v92, v0
	v_mov_b32_e32 v93, v0
	v_mov_b32_e32 v94, v0
	v_mov_b32_e32 v95, v0
	v_mov_b32_e32 v32, v0
	v_mov_b32_e32 v33, v0
	v_mov_b32_e32 v34, v0
	v_mov_b32_e32 v35, v0
	v_mov_b32_e32 v36, v0
	v_mov_b32_e32 v37, v0
	v_mov_b32_e32 v38, v0
	v_mov_b32_e32 v39, v0
	v_mov_b32_e32 v40, v0
	v_mov_b32_e32 v41, v0
	v_mov_b32_e32 v42, v0
	v_mov_b32_e32 v43, v0
	v_mov_b32_e32 v44, v0
	v_mov_b32_e32 v45, v0
	v_mov_b32_e32 v46, v0
	v_mov_b32_e32 v47, v0
	v_mov_b32_e32 v48, v0
	v_mov_b32_e32 v49, v0
	v_mov_b32_e32 v50, v0
	v_mov_b32_e32 v51, v0
	v_mov_b32_e32 v52, v0
	v_mov_b32_e32 v53, v0
	v_mov_b32_e32 v54, v0
	v_mov_b32_e32 v55, v0
	v_mov_b32_e32 v56, v0
	v_mov_b32_e32 v57, v0
	v_mov_b32_e32 v58, v0
	v_mov_b32_e32 v59, v0
	v_mov_b32_e32 v60, v0
	v_mov_b32_e32 v61, v0
	v_mov_b32_e32 v62, v0
	v_mov_b32_e32 v63, v0
	v_mov_b32_e32 v96, v0
	v_mov_b32_e32 v97, v0
	v_mov_b32_e32 v98, v0
	v_mov_b32_e32 v99, v0
	v_mov_b32_e32 v100, v0
	v_mov_b32_e32 v101, v0
	v_mov_b32_e32 v102, v0
	v_mov_b32_e32 v103, v0
	v_mov_b32_e32 v104, v0
	v_mov_b32_e32 v105, v0
	v_mov_b32_e32 v106, v0
	v_mov_b32_e32 v107, v0
	v_mov_b32_e32 v108, v0
	v_mov_b32_e32 v109, v0
	v_mov_b32_e32 v110, v0
	v_mov_b32_e32 v111, v0
	v_mov_b32_e32 v112, v0
	v_mov_b32_e32 v113, v0
	v_mov_b32_e32 v114, v0
	v_mov_b32_e32 v115, v0
	v_mov_b32_e32 v116, v0
	v_mov_b32_e32 v117, v0
	v_mov_b32_e32 v118, v0
	v_mov_b32_e32 v119, v0
	v_mov_b32_e32 v120, v0
	v_mov_b32_e32 v121, v0
	v_mov_b32_e32 v122, v0
	v_mov_b32_e32 v123, v0
	v_mov_b32_e32 v124, v0
	v_mov_b32_e32 v125, v0
	v_mov_b32_e32 v126, v0
	v_mov_b32_e32 v127, v0
	v_add_u32_e32 v250, 0x10000, v212
	v_add_u32_e32 v251, 0x14000, v212
	v_add_u32_e32 v252, 0x18000, v212
	v_add_u32_e32 v253, 0x1c000, v212
.LBB0_1042:
	s_add_u32 s24, s22, 0xfff80080
	s_addc_u32 s25, s23, -1
	s_add_i32 s56, 0, 0x10000
	s_cmp_eq_u32 s55, 4
	s_cselect_b32 s27, s1, s25
	s_cselect_b32 s26, s15, s24
	s_cselect_b32 s25, s13, s54
	s_cselect_b32 s24, s33, s53
	s_add_i32 s58, 0, 0x14000
	ds_read_b128 v[128:131], v250
	ds_read_b128 v[132:135], v250 offset:1024
	ds_read_b128 v[136:139], v250 offset:2048
	ds_read_b128 v[140:143], v250 offset:3072
	ds_read_b128 v[144:147], v251
	ds_read_b128 v[148:151], v251 offset:1024
	ds_read_b128 v[152:155], v251 offset:2048
	ds_read_b128 v[166:169], v251 offset:3072
	s_add_i32 m0, s21, 0xc000
	ds_read_b128 v[170:173], v213
	ds_read_b128 v[174:177], v213 offset:1024
	ds_read_b128 v[178:181], v213 offset:2048
	ds_read_b128 v[182:185], v213 offset:3072
	ds_read_b128 v[186:189], v213 offset:4096
	ds_read_b128 v[204:207], v213 offset:5120
	ds_read_b128 v[208:211], v213 offset:6144
	ds_read_b128 v[214:217], v213 offset:7168
	global_load_lds_dwordx4 v162, s[22:23]
	s_add_i32 m0, s21, 0xe000
	s_nop 0
	global_load_lds_dwordx4 v164, s[22:23]
	s_waitcnt vmcnt(8)
	s_waitcnt lgkmcnt(0)
	s_barrier
; #define PG8_STAGE(bufoff, gbase, voff) do { _Pragma("unroll") for (int _i = 0; _i < 2; ++_i) \
;         __builtin_amdgcn_global_load_lds((const unsigned*)((const char*)(gbase) + (voff)[_i]), (LAS unsigned*)(lds + (bufoff) + ldsw + _i * 8192), 16, 0, 0); } while (0)
; #define PG8_LDA(dst, b, h) do { _Pragma("unroll") for (int m = 0; m < 4; ++m) _Pragma("unroll") for (int k = 0; k < 2; ++k) dst[m][k] = *(const LAS bf16x8*)(lds + PG8_SA(b, h) + aoff + m * 2048 + k * 1024); } while (0)
; #define PG8_MMA(ai, bj, At, Bt) do { __builtin_amdgcn_s_setprio(1); _Pragma("unroll") for (int m = 0; m < 4; ++m) _Pragma("unroll") for (int n = 0; n < 2; ++n) _Pragma("unroll") for (int k = 0; k < 2; ++k) \
;         acc[ai][bj][m][n] = __builtin_amdgcn_mfma_f32_16x16x32_bf16(Bt[n][k], At[m][k], acc[ai][bj][m][n], 0, 0, 0); __builtin_amdgcn_s_setprio(0); } while (0)
; #define PG8_WAIT_V(n) asm volatile("s_waitcnt vmcnt(" #n ")" ::: "memory")
; #define PG8_WAIT_L(n) asm volatile("s_waitcnt lgkmcnt(" #n ")" ::: "memory")
; #define PG8_BAR __builtin_amdgcn_s_barrier()
; #define PG8_SCHED __builtin_amdgcn_sched_barrier(0)
; template <class EpiT, class Sched>
; __device__ __forceinline__ void gemm_phase(LAS unsigned char* lds, const Gemm g, const Sched& S, const EpiT& E, int wv) {
;     ...
;             PG8_WAIT_V(8); PG8_WAIT_L(0); PG8_BAR; PG8_MMA(0, 0, At, B0); PG8_MMA(0, 1, At, B1); PG8_BAR; PG8_SCHED;
;             PG8_LDA(At, 0, 1); PG8_STAGE(PG8_SB(0, 0), b2, voffB); PG8_STAGE(PG8_SB(0, 1), b2 + hstepB, voffB); PG8_STAGE(PG8_SA(0, 0), a2, voffA);
;             PG8_WAIT_V(8); PG8_WAIT_L(0); PG8_BAR; PG8_MMA(1, 0, At, B0); PG8_MMA(1, 1, At, B1); PG8_BAR; PG8_SCHED;
	s_setprio 1
	s_waitcnt lgkmcnt(0)
	v_mfma_f32_16x16x32_bf16 v[124:127], v[128:131], v[170:173], v[124:127]
	v_mfma_f32_16x16x32_bf16 v[120:123], v[136:139], v[170:173], v[120:123]
	v_mfma_f32_16x16x32_bf16 v[116:119], v[128:131], v[178:181], v[116:119]
	v_mfma_f32_16x16x32_bf16 v[112:115], v[136:139], v[178:181], v[112:115]
	v_mfma_f32_16x16x32_bf16 v[108:111], v[128:131], v[186:189], v[108:111]
	v_mfma_f32_16x16x32_bf16 v[104:107], v[136:139], v[186:189], v[104:107]
	v_mfma_f32_16x16x32_bf16 v[100:103], v[128:131], v[208:211], v[100:103]
	v_mfma_f32_16x16x32_bf16 v[96:99], v[136:139], v[208:211], v[96:99]
	v_mfma_f32_16x16x32_bf16 v[124:127], v[132:135], v[174:177], v[124:127]
	v_mfma_f32_16x16x32_bf16 v[120:123], v[140:143], v[174:177], v[120:123]
	v_mfma_f32_16x16x32_bf16 v[116:119], v[132:135], v[182:185], v[116:119]
	v_mfma_f32_16x16x32_bf16 v[112:115], v[140:143], v[182:185], v[112:115]
	v_mfma_f32_16x16x32_bf16 v[108:111], v[132:135], v[204:207], v[108:111]
	v_mfma_f32_16x16x32_bf16 v[104:107], v[140:143], v[204:207], v[104:107]
	v_mfma_f32_16x16x32_bf16 v[100:103], v[132:135], v[214:217], v[100:103]
	v_mfma_f32_16x16x32_bf16 v[96:99], v[140:143], v[214:217], v[96:99]
	s_setprio 0
	s_setprio 1
	v_mfma_f32_16x16x32_bf16 v[60:63], v[144:147], v[170:173], v[60:63]
	v_mfma_f32_16x16x32_bf16 v[56:59], v[152:155], v[170:173], v[56:59]
	v_mfma_f32_16x16x32_bf16 v[52:55], v[144:147], v[178:181], v[52:55]
	v_mfma_f32_16x16x32_bf16 v[48:51], v[152:155], v[178:181], v[48:51]
	v_mfma_f32_16x16x32_bf16 v[44:47], v[144:147], v[186:189], v[44:47]
	v_mfma_f32_16x16x32_bf16 v[40:43], v[152:155], v[186:189], v[40:43]
	v_mfma_f32_16x16x32_bf16 v[36:39], v[144:147], v[208:211], v[36:39]
	v_mfma_f32_16x16x32_bf16 v[32:35], v[152:155], v[208:211], v[32:35]
	v_mfma_f32_16x16x32_bf16 v[60:63], v[148:151], v[174:177], v[60:63]
	v_mfma_f32_16x16x32_bf16 v[56:59], v[166:169], v[174:177], v[56:59]
	v_mfma_f32_16x16x32_bf16 v[52:55], v[148:151], v[182:185], v[52:55]
	v_mfma_f32_16x16x32_bf16 v[48:51], v[166:169], v[182:185], v[48:51]
	v_mfma_f32_16x16x32_bf16 v[44:47], v[148:151], v[204:207], v[44:47]
	v_mfma_f32_16x16x32_bf16 v[40:43], v[166:169], v[204:207], v[40:43]
	v_mfma_f32_16x16x32_bf16 v[36:39], v[148:151], v[214:217], v[36:39]
	v_mfma_f32_16x16x32_bf16 v[32:35], v[166:169], v[214:217], v[32:35]
	s_setprio 0
	s_barrier
	s_add_i32 s56, s56, s39
	s_add_u32 s62, s24, s92
	s_addc_u32 s63, s25, s93
	s_mov_b32 m0, s56
	ds_read_b128 v[170:173], v213 offset:16384
	ds_read_b128 v[174:177], v213 offset:17408
	ds_read_b128 v[178:181], v213 offset:18432
	ds_read_b128 v[182:185], v213 offset:19456
	ds_read_b128 v[186:189], v213 offset:20480
	ds_read_b128 v[204:207], v213 offset:21504
	ds_read_b128 v[208:211], v213 offset:22528
	ds_read_b128 v[214:217], v213 offset:23552
	global_load_lds_dwordx4 v192, s[24:25]
	s_add_i32 m0, s56, 0x2000
	s_add_u32 s56, s24, 0x20000
	s_addc_u32 s57, s25, 0
	s_add_i32 s58, s58, s39
	global_load_lds_dwordx4 v156, s[24:25]
	s_mov_b32 m0, s58
	s_nop 0
	global_load_lds_dwordx4 v192, s[56:57]
	s_add_i32 m0, s58, 0x2000
	s_nop 0
	global_load_lds_dwordx4 v156, s[56:57]
	s_add_u32 s64, s26, s92
	s_addc_u32 s65, s27, s93
	s_mov_b32 m0, s21
	s_nop 0
	global_load_lds_dwordx4 v160, s[26:27]
	s_mov_b32 m0, s45
	s_nop 0
	global_load_lds_dwordx4 v158, s[26:27]
	s_waitcnt vmcnt(8)
	s_waitcnt lgkmcnt(0)
	s_barrier
	s_setprio 1
	s_waitcnt lgkmcnt(0)
	v_mfma_f32_16x16x32_bf16 v[92:95], v[128:131], v[170:173], v[92:95]
	v_mfma_f32_16x16x32_bf16 v[88:91], v[136:139], v[170:173], v[88:91]
	v_mfma_f32_16x16x32_bf16 v[84:87], v[128:131], v[178:181], v[84:87]
	v_mfma_f32_16x16x32_bf16 v[80:83], v[136:139], v[178:181], v[80:83]
	v_mfma_f32_16x16x32_bf16 v[76:79], v[128:131], v[186:189], v[76:79]
	v_mfma_f32_16x16x32_bf16 v[72:75], v[136:139], v[186:189], v[72:75]
	v_mfma_f32_16x16x32_bf16 v[68:71], v[128:131], v[208:211], v[68:71]
	v_mfma_f32_16x16x32_bf16 v[64:67], v[136:139], v[208:211], v[64:67]
	v_mfma_f32_16x16x32_bf16 v[92:95], v[132:135], v[174:177], v[92:95]
	v_mfma_f32_16x16x32_bf16 v[88:91], v[140:143], v[174:177], v[88:91]
	v_mfma_f32_16x16x32_bf16 v[84:87], v[132:135], v[182:185], v[84:87]
	v_mfma_f32_16x16x32_bf16 v[80:83], v[140:143], v[182:185], v[80:83]
	v_mfma_f32_16x16x32_bf16 v[76:79], v[132:135], v[204:207], v[76:79]
	v_mfma_f32_16x16x32_bf16 v[72:75], v[140:143], v[204:207], v[72:75]
	v_mfma_f32_16x16x32_bf16 v[68:71], v[132:135], v[214:217], v[68:71]
	v_mfma_f32_16x16x32_bf16 v[64:67], v[140:143], v[214:217], v[64:67]
	s_setprio 0
	s_setprio 1
	v_mfma_f32_16x16x32_bf16 v[28:31], v[144:147], v[170:173], v[28:31]
	v_mfma_f32_16x16x32_bf16 v[24:27], v[152:155], v[170:173], v[24:27]
	v_mfma_f32_16x16x32_bf16 v[20:23], v[144:147], v[178:181], v[20:23]
	v_mfma_f32_16x16x32_bf16 v[16:19], v[152:155], v[178:181], v[16:19]
	v_mfma_f32_16x16x32_bf16 v[12:15], v[144:147], v[186:189], v[12:15]
	v_mfma_f32_16x16x32_bf16 v[8:11], v[152:155], v[186:189], v[8:11]
	v_mfma_f32_16x16x32_bf16 v[4:7], v[144:147], v[208:211], v[4:7]
	v_mfma_f32_16x16x32_bf16 v[0:3], v[152:155], v[208:211], v[0:3]
	v_mfma_f32_16x16x32_bf16 v[28:31], v[148:151], v[174:177], v[28:31]
	v_mfma_f32_16x16x32_bf16 v[24:27], v[166:169], v[174:177], v[24:27]
	v_mfma_f32_16x16x32_bf16 v[20:23], v[148:151], v[182:185], v[20:23]
	v_mfma_f32_16x16x32_bf16 v[16:19], v[166:169], v[182:185], v[16:19]
	v_mfma_f32_16x16x32_bf16 v[12:15], v[148:151], v[204:207], v[12:15]
	v_mfma_f32_16x16x32_bf16 v[8:11], v[166:169], v[204:207], v[8:11]
	v_mfma_f32_16x16x32_bf16 v[4:7], v[148:151], v[214:217], v[4:7]
	v_mfma_f32_16x16x32_bf16 v[0:3], v[166:169], v[214:217], v[0:3]
	s_setprio 0
	s_barrier
; #define PG8_STAGE(bufoff, gbase, voff) do { _Pragma("unroll") for (int _i = 0; _i < 2; ++_i) \
;         __builtin_amdgcn_global_load_lds((const unsigned*)((const char*)(gbase) + (voff)[_i]), (LAS unsigned*)(lds + (bufoff) + ldsw + _i * 8192), 16, 0, 0); } while (0)
; #define PG8_LDA(dst, b, h) do { _Pragma("unroll") for (int m = 0; m < 4; ++m) _Pragma("unroll") for (int k = 0; k < 2; ++k) dst[m][k] = *(const LAS bf16x8*)(lds + PG8_SA(b, h) + aoff + m * 2048 + k * 1024); } while (0)
; #define PG8_LDB(dst, b, h) do { _Pragma("unroll") for (int n = 0; n < 2; ++n) _Pragma("unroll") for (int k = 0; k < 2; ++k) dst[n][k] = *(const LAS bf16x8*)(lds + PG8_SB(b, h) + boff + n * 2048 + k * 1024); } while (0)
; #define PG8_MMA(ai, bj, At, Bt) do { __builtin_amdgcn_s_setprio(1); _Pragma("unroll") for (int m = 0; m < 4; ++m) _Pragma("unroll") for (int n = 0; n < 2; ++n) _Pragma("unroll") for (int k = 0; k < 2; ++k) \
;         acc[ai][bj][m][n] = __builtin_amdgcn_mfma_f32_16x16x32_bf16(Bt[n][k], At[m][k], acc[ai][bj][m][n], 0, 0, 0); __builtin_amdgcn_s_setprio(0); } while (0)
; #define PG8_WAIT_V(n) asm volatile("s_waitcnt vmcnt(" #n ")" ::: "memory")
; #define PG8_WAIT_L(n) asm volatile("s_waitcnt lgkmcnt(" #n ")" ::: "memory")
; #define PG8_BAR __builtin_amdgcn_s_barrier()
; #define PG8_SCHED __builtin_amdgcn_sched_barrier(0)
; template <class EpiT, class Sched>
; __device__ __forceinline__ void gemm_phase(LAS unsigned char* lds, const Gemm g, const Sched& S, const EpiT& E, int wv) {
;     ...
;             PG8_LDB(B0, 1, 0); PG8_LDB(B1, 1, 1); PG8_SCHED; PG8_LDA(At, 1, 0); PG8_STAGE(PG8_SA(0, 1), a2 + hstepA, voffA);
;             PG8_WAIT_V(8); PG8_WAIT_L(0); PG8_BAR; PG8_MMA(0, 0, At, B0); PG8_MMA(0, 1, At, B1); PG8_BAR; PG8_SCHED;
;             PG8_LDA(At, 1, 1); PG8_STAGE(PG8_SB(1, 0), b3, voffB); PG8_STAGE(PG8_SB(1, 1), b3 + hstepB, voffB); PG8_STAGE(PG8_SA(1, 0), a3, voffA);
;             PG8_WAIT_V(8); PG8_WAIT_L(0); PG8_BAR; PG8_MMA(1, 0, At, B0); PG8_MMA(1, 1, At, B1); PG8_BAR; PG8_SCHED;
;         }
;         if (wr == 0) PG8_BAR;
	s_add_i32 s56, 0, 0x18000
	s_add_i32 s57, 0, 0x1c000
	ds_read_b128 v[128:131], v252
	ds_read_b128 v[132:135], v252 offset:1024
	ds_read_b128 v[136:139], v252 offset:2048
	ds_read_b128 v[140:143], v252 offset:3072
	ds_read_b128 v[144:147], v253
	ds_read_b128 v[148:151], v253 offset:1024
	ds_read_b128 v[152:155], v253 offset:2048
	ds_read_b128 v[166:169], v253 offset:3072
	s_add_u32 s26, s26, 0x80000
	s_addc_u32 s27, s27, 0
	s_mov_b32 m0, s46
	ds_read_b128 v[170:173], v213 offset:32768
	ds_read_b128 v[174:177], v213 offset:33792
	ds_read_b128 v[178:181], v213 offset:34816
	ds_read_b128 v[182:185], v213 offset:35840
	ds_read_b128 v[186:189], v213 offset:36864
	ds_read_b128 v[204:207], v213 offset:37888
	ds_read_b128 v[208:211], v213 offset:38912
	ds_read_b128 v[214:217], v213 offset:39936
	global_load_lds_dwordx4 v160, s[26:27]
	s_mov_b32 m0, s47
	s_nop 0
	global_load_lds_dwordx4 v158, s[26:27]
	s_waitcnt vmcnt(8)
	s_waitcnt lgkmcnt(0)
	s_barrier
	s_setprio 1
	s_waitcnt lgkmcnt(0)
	v_mfma_f32_16x16x32_bf16 v[124:127], v[128:131], v[170:173], v[124:127]
	v_mfma_f32_16x16x32_bf16 v[120:123], v[136:139], v[170:173], v[120:123]
	v_mfma_f32_16x16x32_bf16 v[116:119], v[128:131], v[178:181], v[116:119]
	v_mfma_f32_16x16x32_bf16 v[112:115], v[136:139], v[178:181], v[112:115]
	v_mfma_f32_16x16x32_bf16 v[108:111], v[128:131], v[186:189], v[108:111]
	v_mfma_f32_16x16x32_bf16 v[104:107], v[136:139], v[186:189], v[104:107]
	v_mfma_f32_16x16x32_bf16 v[100:103], v[128:131], v[208:211], v[100:103]
	v_mfma_f32_16x16x32_bf16 v[96:99], v[136:139], v[208:211], v[96:99]
	v_mfma_f32_16x16x32_bf16 v[124:127], v[132:135], v[174:177], v[124:127]
	v_mfma_f32_16x16x32_bf16 v[120:123], v[140:143], v[174:177], v[120:123]
	v_mfma_f32_16x16x32_bf16 v[116:119], v[132:135], v[182:185], v[116:119]
	v_mfma_f32_16x16x32_bf16 v[112:115], v[140:143], v[182:185], v[112:115]
	v_mfma_f32_16x16x32_bf16 v[108:111], v[132:135], v[204:207], v[108:111]
	v_mfma_f32_16x16x32_bf16 v[104:107], v[140:143], v[204:207], v[104:107]
	v_mfma_f32_16x16x32_bf16 v[100:103], v[132:135], v[214:217], v[100:103]
	v_mfma_f32_16x16x32_bf16 v[96:99], v[140:143], v[214:217], v[96:99]
	s_setprio 0
	s_setprio 1
	v_mfma_f32_16x16x32_bf16 v[60:63], v[144:147], v[170:173], v[60:63]
	v_mfma_f32_16x16x32_bf16 v[56:59], v[152:155], v[170:173], v[56:59]
	v_mfma_f32_16x16x32_bf16 v[52:55], v[144:147], v[178:181], v[52:55]
	v_mfma_f32_16x16x32_bf16 v[48:51], v[152:155], v[178:181], v[48:51]
	v_mfma_f32_16x16x32_bf16 v[44:47], v[144:147], v[186:189], v[44:47]
	v_mfma_f32_16x16x32_bf16 v[40:43], v[152:155], v[186:189], v[40:43]
	v_mfma_f32_16x16x32_bf16 v[36:39], v[144:147], v[208:211], v[36:39]
	v_mfma_f32_16x16x32_bf16 v[32:35], v[152:155], v[208:211], v[32:35]
	v_mfma_f32_16x16x32_bf16 v[60:63], v[148:151], v[174:177], v[60:63]
	v_mfma_f32_16x16x32_bf16 v[56:59], v[166:169], v[174:177], v[56:59]
	v_mfma_f32_16x16x32_bf16 v[52:55], v[148:151], v[182:185], v[52:55]
	v_mfma_f32_16x16x32_bf16 v[48:51], v[166:169], v[182:185], v[48:51]
	v_mfma_f32_16x16x32_bf16 v[44:47], v[148:151], v[204:207], v[44:47]
	v_mfma_f32_16x16x32_bf16 v[40:43], v[166:169], v[204:207], v[40:43]
	v_mfma_f32_16x16x32_bf16 v[36:39], v[148:151], v[214:217], v[36:39]
	v_mfma_f32_16x16x32_bf16 v[32:35], v[166:169], v[214:217], v[32:35]
	s_setprio 0
	s_barrier
	s_add_i32 s26, s56, s39
	s_mov_b32 m0, s26
	ds_read_b128 v[170:173], v213 offset:49152
	ds_read_b128 v[174:177], v213 offset:50176
	ds_read_b128 v[178:181], v213 offset:51200
	ds_read_b128 v[182:185], v213 offset:52224
	ds_read_b128 v[186:189], v213 offset:53248
	ds_read_b128 v[204:207], v213 offset:54272
	ds_read_b128 v[208:211], v213 offset:55296
	ds_read_b128 v[214:217], v213 offset:56320
	global_load_lds_dwordx4 v192, s[62:63]
	s_add_i32 m0, s26, 0x2000
	s_add_u32 s24, s24, 0x20080
	s_addc_u32 s25, s25, 0
	s_add_i32 s26, s57, s39
	global_load_lds_dwordx4 v156, s[62:63]
	s_mov_b32 m0, s26
	s_nop 0
	global_load_lds_dwordx4 v192, s[24:25]
	s_add_i32 m0, s26, 0x2000
	s_nop 0
	global_load_lds_dwordx4 v156, s[24:25]
	s_mov_b32 m0, s48
	s_nop 0
	global_load_lds_dwordx4 v160, s[64:65]
	s_mov_b32 m0, s49
	s_nop 0
	global_load_lds_dwordx4 v158, s[64:65]
	s_waitcnt vmcnt(8)
	s_waitcnt lgkmcnt(0)
	s_barrier
	s_setprio 1
	s_waitcnt lgkmcnt(0)
	v_mfma_f32_16x16x32_bf16 v[92:95], v[128:131], v[170:173], v[92:95]
	v_mfma_f32_16x16x32_bf16 v[88:91], v[136:139], v[170:173], v[88:91]
	v_mfma_f32_16x16x32_bf16 v[84:87], v[128:131], v[178:181], v[84:87]
	v_mfma_f32_16x16x32_bf16 v[80:83], v[136:139], v[178:181], v[80:83]
	v_mfma_f32_16x16x32_bf16 v[76:79], v[128:131], v[186:189], v[76:79]
	v_mfma_f32_16x16x32_bf16 v[72:75], v[136:139], v[186:189], v[72:75]
	v_mfma_f32_16x16x32_bf16 v[68:71], v[128:131], v[208:211], v[68:71]
	v_mfma_f32_16x16x32_bf16 v[64:67], v[136:139], v[208:211], v[64:67]
	v_mfma_f32_16x16x32_bf16 v[92:95], v[132:135], v[174:177], v[92:95]
	v_mfma_f32_16x16x32_bf16 v[88:91], v[140:143], v[174:177], v[88:91]
	v_mfma_f32_16x16x32_bf16 v[84:87], v[132:135], v[182:185], v[84:87]
	v_mfma_f32_16x16x32_bf16 v[80:83], v[140:143], v[182:185], v[80:83]
	v_mfma_f32_16x16x32_bf16 v[76:79], v[132:135], v[204:207], v[76:79]
	v_mfma_f32_16x16x32_bf16 v[72:75], v[140:143], v[204:207], v[72:75]
	v_mfma_f32_16x16x32_bf16 v[68:71], v[132:135], v[214:217], v[68:71]
	v_mfma_f32_16x16x32_bf16 v[64:67], v[140:143], v[214:217], v[64:67]
	s_setprio 0
	s_setprio 1
	v_mfma_f32_16x16x32_bf16 v[28:31], v[144:147], v[170:173], v[28:31]
	v_mfma_f32_16x16x32_bf16 v[24:27], v[152:155], v[170:173], v[24:27]
	v_mfma_f32_16x16x32_bf16 v[20:23], v[144:147], v[178:181], v[20:23]
	v_mfma_f32_16x16x32_bf16 v[16:19], v[152:155], v[178:181], v[16:19]
	v_mfma_f32_16x16x32_bf16 v[12:15], v[144:147], v[186:189], v[12:15]
	v_mfma_f32_16x16x32_bf16 v[8:11], v[152:155], v[186:189], v[8:11]
	v_mfma_f32_16x16x32_bf16 v[4:7], v[144:147], v[208:211], v[4:7]
	v_mfma_f32_16x16x32_bf16 v[0:3], v[152:155], v[208:211], v[0:3]
	v_mfma_f32_16x16x32_bf16 v[28:31], v[148:151], v[174:177], v[28:31]
	v_mfma_f32_16x16x32_bf16 v[24:27], v[166:169], v[174:177], v[24:27]
	v_mfma_f32_16x16x32_bf16 v[20:23], v[148:151], v[182:185], v[20:23]
	v_mfma_f32_16x16x32_bf16 v[16:19], v[166:169], v[182:185], v[16:19]
	v_mfma_f32_16x16x32_bf16 v[12:15], v[148:151], v[204:207], v[12:15]
	v_mfma_f32_16x16x32_bf16 v[8:11], v[166:169], v[204:207], v[8:11]
	v_mfma_f32_16x16x32_bf16 v[4:7], v[148:151], v[214:217], v[4:7]
	v_mfma_f32_16x16x32_bf16 v[0:3], v[166:169], v[214:217], v[0:3]
	s_setprio 0
	s_barrier
	s_add_i32 s55, s55, 2
	s_add_u32 s22, s22, 0x100
	s_addc_u32 s23, s23, 0
	s_add_u32 s53, s53, 0x100
	s_addc_u32 s54, s54, 0
	s_cmp_gt_u32 s55, 5
	s_cbranch_scc0 .LBB0_1042
	s_and_b64 vcc, exec, s[10:11]
	s_cbranch_vccz .LBB0_1045
	s_barrier

; #define PG8_STAGE(bufoff, gbase, voff) do { _Pragma("unroll") for (int _i = 0; _i < 2; ++_i) \
;         __builtin_amdgcn_global_load_lds((const unsigned*)((const char*)(gbase) + (voff)[_i]), (LAS unsigned*)(lds + (bufoff) + ldsw + _i * 8192), 16, 0, 0); } while (0)
; #define PG8_LDA(dst, b, h) do { _Pragma("unroll") for (int m = 0; m < 4; ++m) _Pragma("unroll") for (int k = 0; k < 2; ++k) dst[m][k] = *(const LAS bf16x8*)(lds + PG8_SA(b, h) + aoff + m * 2048 + k * 1024); } while (0)
; #define PG8_LDB(dst, b, h) do { _Pragma("unroll") for (int n = 0; n < 2; ++n) _Pragma("unroll") for (int k = 0; k < 2; ++k) dst[n][k] = *(const LAS bf16x8*)(lds + PG8_SB(b, h) + boff + n * 2048 + k * 1024); } while (0)
; #define PG8_MMA(ai, bj, At, Bt) do { __builtin_amdgcn_s_setprio(1); _Pragma("unroll") for (int m = 0; m < 4; ++m) _Pragma("unroll") for (int n = 0; n < 2; ++n) _Pragma("unroll") for (int k = 0; k < 2; ++k) \
;         acc[ai][bj][m][n] = __builtin_amdgcn_mfma_f32_16x16x32_bf16(Bt[n][k], At[m][k], acc[ai][bj][m][n], 0, 0, 0); __builtin_amdgcn_s_setprio(0); } while (0)
; template <class EpiT, class Sched>
; __device__ __forceinline__ void gemm_phase(LAS unsigned char* lds, const Gemm g, const Sched& S, const EpiT& E, int wv) {
;     ...
;         const bool has_next = S.next(ui + 1, nxt);
;         const char* nA = has_next ? (const char*)g.A + (size_t)nxt.pm * tstepA + (size_t)(nxt.pn >> g.zshift) * g.zA : cA; const char* nB = has_next ? (const char*)g.Bt + (size_t)nxt.pn * tstepB : cB;
;         for (int t = 0; t < nt; t += 2) {
;             const bool last = (t == nt - 2);
;             const char* a1 = cA + (size_t)(t + 1) * kstep;
;             const char* a2 = last ? nA : cA + (size_t)(t + 2) * kstep; const char* b2 = last ? nB : cB + (size_t)(t + 2) * kstep;
;             const char* a3 = a2 + kstep; const char* b3 = b2 + kstep;
;             PG8_LDB(B0, 0, 0); PG8_LDB(B1, 0, 1); PG8_SCHED; PG8_LDA(At, 0, 0); PG8_STAGE(PG8_SA(1, 1), a1 + hstepA, voffA);
;             PG8_WAIT_V(8); PG8_WAIT_L(0); PG8_BAR; PG8_MMA(0, 0, At, B0); PG8_MMA(0, 1, At, B1); PG8_BAR; PG8_SCHED;
;     ...
; #pragma unroll
;         for (int a = 0; a < 2; ++a)
; #pragma unroll
;             for (int b = 0; b < 2; ++b)
; #pragma unroll
;                 for (int m = 0; m < 4; ++m)
; #pragma unroll
;                     for (int n = 0; n < 2; ++n) acc[a][b][m][n] = (f32x4){0.f, 0.f, 0.f, 0.f};
.LBB0_1153:
	s_ashr_i32 s25, s24, 31
	s_lshl_b64 s[28:29], s[24:25], 19
	s_add_u32 s28, s49, s28
	s_addc_u32 s29, s50, s29
	s_and_b64 s[30:31], s[2:3], exec
	s_cselect_b32 s1, s29, s5
	s_cselect_b32 s25, s28, s4
	s_ashr_i32 s23, s22, 31
	s_lshl_b64 s[30:31], s[22:23], 21
	s_add_u32 s30, s51, s30
	s_addc_u32 s31, s52, s31
	s_and_b64 s[40:41], s[2:3], exec
	s_cselect_b32 s23, s31, s39
	s_cselect_b32 s33, s30, s38
	s_add_u32 s4, s4, 0x40080
	s_addc_u32 s5, s5, 0
	s_add_u32 s64, s38, 0x100
	v_mov_b32_e32 v0, 0
	s_addc_u32 s65, s39, 0
	s_mov_b32 s89, -2
	v_mov_b32_e32 v1, v0
	v_mov_b32_e32 v2, v0
	v_mov_b32_e32 v3, v0
	v_mov_b32_e32 v4, v0
	v_mov_b32_e32 v5, v0
	v_mov_b32_e32 v6, v0
	v_mov_b32_e32 v7, v0
	v_mov_b32_e32 v8, v0
	v_mov_b32_e32 v9, v0
	v_mov_b32_e32 v10, v0
	v_mov_b32_e32 v11, v0
	v_mov_b32_e32 v12, v0
	v_mov_b32_e32 v13, v0
	v_mov_b32_e32 v14, v0
	v_mov_b32_e32 v15, v0
	v_mov_b32_e32 v16, v0
	v_mov_b32_e32 v17, v0
	v_mov_b32_e32 v18, v0
	v_mov_b32_e32 v19, v0
	v_mov_b32_e32 v20, v0
	v_mov_b32_e32 v21, v0
	v_mov_b32_e32 v22, v0
	v_mov_b32_e32 v23, v0
	v_mov_b32_e32 v24, v0
	v_mov_b32_e32 v25, v0
	v_mov_b32_e32 v26, v0
	v_mov_b32_e32 v27, v0
	v_mov_b32_e32 v28, v0
	v_mov_b32_e32 v29, v0
	v_mov_b32_e32 v30, v0
	v_mov_b32_e32 v31, v0
	v_mov_b32_e32 v64, v0
	v_mov_b32_e32 v65, v0
	v_mov_b32_e32 v66, v0
	v_mov_b32_e32 v67, v0
	v_mov_b32_e32 v68, v0
	v_mov_b32_e32 v69, v0
	v_mov_b32_e32 v70, v0
	v_mov_b32_e32 v71, v0
	v_mov_b32_e32 v72, v0
	v_mov_b32_e32 v73, v0
	v_mov_b32_e32 v74, v0
	v_mov_b32_e32 v75, v0
	v_mov_b32_e32 v76, v0
	v_mov_b32_e32 v77, v0
	v_mov_b32_e32 v78, v0
	v_mov_b32_e32 v79, v0
	v_mov_b32_e32 v80, v0
	v_mov_b32_e32 v81, v0
	v_mov_b32_e32 v82, v0
	v_mov_b32_e32 v83, v0
	v_mov_b32_e32 v84, v0
	v_mov_b32_e32 v85, v0
	v_mov_b32_e32 v86, v0
	v_mov_b32_e32 v87, v0
	v_mov_b32_e32 v88, v0
	v_mov_b32_e32 v89, v0
	v_mov_b32_e32 v90, v0
	v_mov_b32_e32 v91, v0
	v_mov_b32_e32 v92, v0
	v_mov_b32_e32 v93, v0
	v_mov_b32_e32 v94, v0
	v_mov_b32_e32 v95, v0
	v_mov_b32_e32 v32, v0
	v_mov_b32_e32 v33, v0
	v_mov_b32_e32 v34, v0
	v_mov_b32_e32 v35, v0
	v_mov_b32_e32 v36, v0
	v_mov_b32_e32 v37, v0
	v_mov_b32_e32 v38, v0
	v_mov_b32_e32 v39, v0
	v_mov_b32_e32 v40, v0
	v_mov_b32_e32 v41, v0
	v_mov_b32_e32 v42, v0
	v_mov_b32_e32 v43, v0
	v_mov_b32_e32 v44, v0
	v_mov_b32_e32 v45, v0
	v_mov_b32_e32 v46, v0
	v_mov_b32_e32 v47, v0
	v_mov_b32_e32 v48, v0
	v_mov_b32_e32 v49, v0
	v_mov_b32_e32 v50, v0
	v_mov_b32_e32 v51, v0
	v_mov_b32_e32 v52, v0
	v_mov_b32_e32 v53, v0
	v_mov_b32_e32 v54, v0
	v_mov_b32_e32 v55, v0
	v_mov_b32_e32 v56, v0
	v_mov_b32_e32 v57, v0
	v_mov_b32_e32 v58, v0
	v_mov_b32_e32 v59, v0
	v_mov_b32_e32 v60, v0
	v_mov_b32_e32 v61, v0
	v_mov_b32_e32 v62, v0
	v_mov_b32_e32 v63, v0
	v_mov_b32_e32 v96, v0
	v_mov_b32_e32 v97, v0
	v_mov_b32_e32 v98, v0
	v_mov_b32_e32 v99, v0
	v_mov_b32_e32 v100, v0
	v_mov_b32_e32 v101, v0
	v_mov_b32_e32 v102, v0
	v_mov_b32_e32 v103, v0
	v_mov_b32_e32 v104, v0
	v_mov_b32_e32 v105, v0
	v_mov_b32_e32 v106, v0
	v_mov_b32_e32 v107, v0
	v_mov_b32_e32 v108, v0
	v_mov_b32_e32 v109, v0
	v_mov_b32_e32 v110, v0
	v_mov_b32_e32 v111, v0
	v_mov_b32_e32 v112, v0
	v_mov_b32_e32 v113, v0
	v_mov_b32_e32 v114, v0
	v_mov_b32_e32 v115, v0
	v_mov_b32_e32 v116, v0
	v_mov_b32_e32 v117, v0
	v_mov_b32_e32 v118, v0
	v_mov_b32_e32 v119, v0
	v_mov_b32_e32 v128, v0
	v_mov_b32_e32 v129, v0
	v_mov_b32_e32 v130, v0
	v_mov_b32_e32 v131, v0
	v_mov_b32_e32 v132, v0
	v_mov_b32_e32 v133, v0
	v_mov_b32_e32 v134, v0
	v_mov_b32_e32 v135, v0
	v_add_u32_e32 v250, 0x10000, v240
	v_add_u32_e32 v251, 0x14000, v240
	v_add_u32_e32 v252, 0x18000, v240
	v_add_u32_e32 v253, 0x1c000, v240
.LBB0_1154:
	s_add_u32 s38, s4, 0xfffc0080
	s_addc_u32 s39, s5, -1
	s_add_i32 s90, 0, 0x10000
	s_cmp_eq_u32 s89, 12
	s_cselect_b32 s41, s1, s39
	s_cselect_b32 s40, s25, s38
	s_cselect_b32 s39, s23, s65
	s_cselect_b32 s38, s33, s64
	s_add_i32 vcc_lo, 0, 0x14000
	ds_read_b128 v[120:123], v250
	ds_read_b128 v[124:127], v250 offset:1024
	ds_read_b128 v[136:139], v250 offset:2048
	ds_read_b128 v[140:143], v250 offset:3072
	ds_read_b128 v[144:147], v251
	ds_read_b128 v[148:151], v251 offset:1024
	ds_read_b128 v[152:155], v251 offset:2048
	ds_read_b128 v[156:159], v251 offset:3072
	s_add_i32 m0, s27, 0xc000
	ds_read_b128 v[160:163], v241
	ds_read_b128 v[164:167], v241 offset:1024
	ds_read_b128 v[178:181], v241 offset:2048
	ds_read_b128 v[182:185], v241 offset:3072
	ds_read_b128 v[186:189], v241 offset:4096
	ds_read_b128 v[204:207], v241 offset:5120
	ds_read_b128 v[208:211], v241 offset:6144
	ds_read_b128 v[212:215], v241 offset:7168
	global_load_lds_dwordx4 v174, s[4:5]
	s_add_i32 m0, s27, 0xe000
	s_nop 0
	global_load_lds_dwordx4 v176, s[4:5]
	s_waitcnt vmcnt(8)
	s_waitcnt lgkmcnt(0)
	s_barrier
; #define PG8_STAGE(bufoff, gbase, voff) do { _Pragma("unroll") for (int _i = 0; _i < 2; ++_i) \
;         __builtin_amdgcn_global_load_lds((const unsigned*)((const char*)(gbase) + (voff)[_i]), (LAS unsigned*)(lds + (bufoff) + ldsw + _i * 8192), 16, 0, 0); } while (0)
; #define PG8_LDA(dst, b, h) do { _Pragma("unroll") for (int m = 0; m < 4; ++m) _Pragma("unroll") for (int k = 0; k < 2; ++k) dst[m][k] = *(const LAS bf16x8*)(lds + PG8_SA(b, h) + aoff + m * 2048 + k * 1024); } while (0)
; #define PG8_MMA(ai, bj, At, Bt) do { __builtin_amdgcn_s_setprio(1); _Pragma("unroll") for (int m = 0; m < 4; ++m) _Pragma("unroll") for (int n = 0; n < 2; ++n) _Pragma("unroll") for (int k = 0; k < 2; ++k) \
;         acc[ai][bj][m][n] = __builtin_amdgcn_mfma_f32_16x16x32_bf16(Bt[n][k], At[m][k], acc[ai][bj][m][n], 0, 0, 0); __builtin_amdgcn_s_setprio(0); } while (0)
; #define PG8_WAIT_V(n) asm volatile("s_waitcnt vmcnt(" #n ")" ::: "memory")
; #define PG8_WAIT_L(n) asm volatile("s_waitcnt lgkmcnt(" #n ")" ::: "memory")
; #define PG8_BAR __builtin_amdgcn_s_barrier()
; #define PG8_SCHED __builtin_amdgcn_sched_barrier(0)
; template <class EpiT, class Sched>
; __device__ __forceinline__ void gemm_phase(LAS unsigned char* lds, const Gemm g, const Sched& S, const EpiT& E, int wv) {
;     ...
;             PG8_WAIT_V(8); PG8_WAIT_L(0); PG8_BAR; PG8_MMA(0, 0, At, B0); PG8_MMA(0, 1, At, B1); PG8_BAR; PG8_SCHED;
;             PG8_LDA(At, 0, 1); PG8_STAGE(PG8_SB(0, 0), b2, voffB); PG8_STAGE(PG8_SB(0, 1), b2 + hstepB, voffB); PG8_STAGE(PG8_SA(0, 0), a2, voffA);
;             PG8_WAIT_V(8); PG8_WAIT_L(0); PG8_BAR; PG8_MMA(1, 0, At, B0); PG8_MMA(1, 1, At, B1); PG8_BAR; PG8_SCHED;
	s_setprio 1
	s_waitcnt lgkmcnt(0)
	v_mfma_f32_16x16x32_bf16 v[132:135], v[120:123], v[160:163], v[132:135]
	v_mfma_f32_16x16x32_bf16 v[128:131], v[136:139], v[160:163], v[128:131]
	v_mfma_f32_16x16x32_bf16 v[116:119], v[120:123], v[178:181], v[116:119]
	v_mfma_f32_16x16x32_bf16 v[112:115], v[136:139], v[178:181], v[112:115]
	v_mfma_f32_16x16x32_bf16 v[108:111], v[120:123], v[186:189], v[108:111]
	v_mfma_f32_16x16x32_bf16 v[104:107], v[136:139], v[186:189], v[104:107]
	v_mfma_f32_16x16x32_bf16 v[100:103], v[120:123], v[208:211], v[100:103]
	v_mfma_f32_16x16x32_bf16 v[96:99], v[136:139], v[208:211], v[96:99]
	v_mfma_f32_16x16x32_bf16 v[132:135], v[124:127], v[164:167], v[132:135]
	v_mfma_f32_16x16x32_bf16 v[128:131], v[140:143], v[164:167], v[128:131]
	v_mfma_f32_16x16x32_bf16 v[116:119], v[124:127], v[182:185], v[116:119]
	v_mfma_f32_16x16x32_bf16 v[112:115], v[140:143], v[182:185], v[112:115]
	v_mfma_f32_16x16x32_bf16 v[108:111], v[124:127], v[204:207], v[108:111]
	v_mfma_f32_16x16x32_bf16 v[104:107], v[140:143], v[204:207], v[104:107]
	v_mfma_f32_16x16x32_bf16 v[100:103], v[124:127], v[212:215], v[100:103]
	v_mfma_f32_16x16x32_bf16 v[96:99], v[140:143], v[212:215], v[96:99]
	s_setprio 0
	s_setprio 1
	v_mfma_f32_16x16x32_bf16 v[60:63], v[144:147], v[160:163], v[60:63]
	v_mfma_f32_16x16x32_bf16 v[56:59], v[152:155], v[160:163], v[56:59]
	v_mfma_f32_16x16x32_bf16 v[52:55], v[144:147], v[178:181], v[52:55]
	v_mfma_f32_16x16x32_bf16 v[48:51], v[152:155], v[178:181], v[48:51]
	v_mfma_f32_16x16x32_bf16 v[44:47], v[144:147], v[186:189], v[44:47]
	v_mfma_f32_16x16x32_bf16 v[40:43], v[152:155], v[186:189], v[40:43]
	v_mfma_f32_16x16x32_bf16 v[36:39], v[144:147], v[208:211], v[36:39]
	v_mfma_f32_16x16x32_bf16 v[32:35], v[152:155], v[208:211], v[32:35]
	v_mfma_f32_16x16x32_bf16 v[60:63], v[148:151], v[164:167], v[60:63]
	v_mfma_f32_16x16x32_bf16 v[56:59], v[156:159], v[164:167], v[56:59]
	v_mfma_f32_16x16x32_bf16 v[52:55], v[148:151], v[182:185], v[52:55]
	v_mfma_f32_16x16x32_bf16 v[48:51], v[156:159], v[182:185], v[48:51]
	v_mfma_f32_16x16x32_bf16 v[44:47], v[148:151], v[204:207], v[44:47]
	v_mfma_f32_16x16x32_bf16 v[40:43], v[156:159], v[204:207], v[40:43]
	v_mfma_f32_16x16x32_bf16 v[36:39], v[148:151], v[212:215], v[36:39]
	v_mfma_f32_16x16x32_bf16 v[32:35], v[156:159], v[212:215], v[32:35]
	s_setprio 0
	s_barrier
	s_add_i32 s90, s90, s48
	s_add_u32 s36, s38, s92
	s_addc_u32 s37, s39, s93
	s_mov_b32 m0, s90
	ds_read_b128 v[160:163], v241 offset:16384
	ds_read_b128 v[164:167], v241 offset:17408
	ds_read_b128 v[178:181], v241 offset:18432
	ds_read_b128 v[182:185], v241 offset:19456
	ds_read_b128 v[186:189], v241 offset:20480
	ds_read_b128 v[204:207], v241 offset:21504
	ds_read_b128 v[208:211], v241 offset:22528
	ds_read_b128 v[212:215], v241 offset:23552
	global_load_lds_dwordx4 v192, s[38:39]
	s_add_i32 m0, s90, 0x2000
	s_add_u32 s90, s38, 0x100000
	s_addc_u32 s91, s39, 0
	s_add_i32 vcc_lo, vcc_lo, s48
	global_load_lds_dwordx4 v172, s[38:39]
	s_mov_b32 m0, vcc_lo
	s_nop 0
	global_load_lds_dwordx4 v192, s[90:91]
	s_add_i32 m0, vcc_lo, 0x2000
	s_nop 0
	global_load_lds_dwordx4 v172, s[90:91]
	s_add_u32 s98, s40, s92
	s_addc_u32 s99, s41, s93
	s_mov_b32 m0, s27
	s_nop 0
	global_load_lds_dwordx4 v168, s[40:41]
	s_mov_b32 m0, s53
	s_nop 0
	global_load_lds_dwordx4 v170, s[40:41]
	s_waitcnt vmcnt(8)
	s_waitcnt lgkmcnt(0)
	s_barrier
	s_setprio 1
	s_waitcnt lgkmcnt(0)
	v_mfma_f32_16x16x32_bf16 v[92:95], v[120:123], v[160:163], v[92:95]
	v_mfma_f32_16x16x32_bf16 v[88:91], v[136:139], v[160:163], v[88:91]
	v_mfma_f32_16x16x32_bf16 v[84:87], v[120:123], v[178:181], v[84:87]
	v_mfma_f32_16x16x32_bf16 v[80:83], v[136:139], v[178:181], v[80:83]
	v_mfma_f32_16x16x32_bf16 v[76:79], v[120:123], v[186:189], v[76:79]
	v_mfma_f32_16x16x32_bf16 v[72:75], v[136:139], v[186:189], v[72:75]
	v_mfma_f32_16x16x32_bf16 v[68:71], v[120:123], v[208:211], v[68:71]
	v_mfma_f32_16x16x32_bf16 v[64:67], v[136:139], v[208:211], v[64:67]
	v_mfma_f32_16x16x32_bf16 v[92:95], v[124:127], v[164:167], v[92:95]
	v_mfma_f32_16x16x32_bf16 v[88:91], v[140:143], v[164:167], v[88:91]
	v_mfma_f32_16x16x32_bf16 v[84:87], v[124:127], v[182:185], v[84:87]
	v_mfma_f32_16x16x32_bf16 v[80:83], v[140:143], v[182:185], v[80:83]
	v_mfma_f32_16x16x32_bf16 v[76:79], v[124:127], v[204:207], v[76:79]
	v_mfma_f32_16x16x32_bf16 v[72:75], v[140:143], v[204:207], v[72:75]
	v_mfma_f32_16x16x32_bf16 v[68:71], v[124:127], v[212:215], v[68:71]
	v_mfma_f32_16x16x32_bf16 v[64:67], v[140:143], v[212:215], v[64:67]
	s_setprio 0
	s_setprio 1
	v_mfma_f32_16x16x32_bf16 v[28:31], v[144:147], v[160:163], v[28:31]
	v_mfma_f32_16x16x32_bf16 v[24:27], v[152:155], v[160:163], v[24:27]
	v_mfma_f32_16x16x32_bf16 v[20:23], v[144:147], v[178:181], v[20:23]
	v_mfma_f32_16x16x32_bf16 v[16:19], v[152:155], v[178:181], v[16:19]
	v_mfma_f32_16x16x32_bf16 v[12:15], v[144:147], v[186:189], v[12:15]
	v_mfma_f32_16x16x32_bf16 v[8:11], v[152:155], v[186:189], v[8:11]
	v_mfma_f32_16x16x32_bf16 v[4:7], v[144:147], v[208:211], v[4:7]
	v_mfma_f32_16x16x32_bf16 v[0:3], v[152:155], v[208:211], v[0:3]
	v_mfma_f32_16x16x32_bf16 v[28:31], v[148:151], v[164:167], v[28:31]
	v_mfma_f32_16x16x32_bf16 v[24:27], v[156:159], v[164:167], v[24:27]
	v_mfma_f32_16x16x32_bf16 v[20:23], v[148:151], v[182:185], v[20:23]
	v_mfma_f32_16x16x32_bf16 v[16:19], v[156:159], v[182:185], v[16:19]
	v_mfma_f32_16x16x32_bf16 v[12:15], v[148:151], v[204:207], v[12:15]
	v_mfma_f32_16x16x32_bf16 v[8:11], v[156:159], v[204:207], v[8:11]
	v_mfma_f32_16x16x32_bf16 v[4:7], v[148:151], v[212:215], v[4:7]
	v_mfma_f32_16x16x32_bf16 v[0:3], v[156:159], v[212:215], v[0:3]
	s_setprio 0
	s_barrier
; #define PG8_STAGE(bufoff, gbase, voff) do { _Pragma("unroll") for (int _i = 0; _i < 2; ++_i) \
;         __builtin_amdgcn_global_load_lds((const unsigned*)((const char*)(gbase) + (voff)[_i]), (LAS unsigned*)(lds + (bufoff) + ldsw + _i * 8192), 16, 0, 0); } while (0)
; #define PG8_LDA(dst, b, h) do { _Pragma("unroll") for (int m = 0; m < 4; ++m) _Pragma("unroll") for (int k = 0; k < 2; ++k) dst[m][k] = *(const LAS bf16x8*)(lds + PG8_SA(b, h) + aoff + m * 2048 + k * 1024); } while (0)
; #define PG8_LDB(dst, b, h) do { _Pragma("unroll") for (int n = 0; n < 2; ++n) _Pragma("unroll") for (int k = 0; k < 2; ++k) dst[n][k] = *(const LAS bf16x8*)(lds + PG8_SB(b, h) + boff + n * 2048 + k * 1024); } while (0)
; #define PG8_MMA(ai, bj, At, Bt) do { __builtin_amdgcn_s_setprio(1); _Pragma("unroll") for (int m = 0; m < 4; ++m) _Pragma("unroll") for (int n = 0; n < 2; ++n) _Pragma("unroll") for (int k = 0; k < 2; ++k) \
;         acc[ai][bj][m][n] = __builtin_amdgcn_mfma_f32_16x16x32_bf16(Bt[n][k], At[m][k], acc[ai][bj][m][n], 0, 0, 0); __builtin_amdgcn_s_setprio(0); } while (0)
; #define PG8_WAIT_V(n) asm volatile("s_waitcnt vmcnt(" #n ")" ::: "memory")
; #define PG8_WAIT_L(n) asm volatile("s_waitcnt lgkmcnt(" #n ")" ::: "memory")
; #define PG8_BAR __builtin_amdgcn_s_barrier()
; #define PG8_SCHED __builtin_amdgcn_sched_barrier(0)
; template <class EpiT, class Sched>
; __device__ __forceinline__ void gemm_phase(LAS unsigned char* lds, const Gemm g, const Sched& S, const EpiT& E, int wv) {
;     ...
;             PG8_LDB(B0, 1, 0); PG8_LDB(B1, 1, 1); PG8_SCHED; PG8_LDA(At, 1, 0); PG8_STAGE(PG8_SA(0, 1), a2 + hstepA, voffA);
;             PG8_WAIT_V(8); PG8_WAIT_L(0); PG8_BAR; PG8_MMA(0, 0, At, B0); PG8_MMA(0, 1, At, B1); PG8_BAR; PG8_SCHED;
;             PG8_LDA(At, 1, 1); PG8_STAGE(PG8_SB(1, 0), b3, voffB); PG8_STAGE(PG8_SB(1, 1), b3 + hstepB, voffB); PG8_STAGE(PG8_SA(1, 0), a3, voffA);
;             PG8_WAIT_V(8); PG8_WAIT_L(0); PG8_BAR; PG8_MMA(1, 0, At, B0); PG8_MMA(1, 1, At, B1); PG8_BAR; PG8_SCHED;
;         }
;         if (wr == 0) PG8_BAR;
	s_add_i32 s90, 0, 0x18000
	s_add_i32 s91, 0, 0x1c000
	ds_read_b128 v[120:123], v252
	ds_read_b128 v[124:127], v252 offset:1024
	ds_read_b128 v[136:139], v252 offset:2048
	ds_read_b128 v[140:143], v252 offset:3072
	ds_read_b128 v[144:147], v253
	ds_read_b128 v[148:151], v253 offset:1024
	ds_read_b128 v[152:155], v253 offset:2048
	ds_read_b128 v[156:159], v253 offset:3072
	s_add_u32 s40, s40, 0x40000
	s_addc_u32 s41, s41, 0
	s_mov_b32 m0, s54
	ds_read_b128 v[160:163], v241 offset:32768
	ds_read_b128 v[164:167], v241 offset:33792
	ds_read_b128 v[178:181], v241 offset:34816
	ds_read_b128 v[182:185], v241 offset:35840
	ds_read_b128 v[186:189], v241 offset:36864
	ds_read_b128 v[204:207], v241 offset:37888
	ds_read_b128 v[208:211], v241 offset:38912
	ds_read_b128 v[212:215], v241 offset:39936
	global_load_lds_dwordx4 v168, s[40:41]
	s_mov_b32 m0, s55
	s_nop 0
	global_load_lds_dwordx4 v170, s[40:41]
	s_waitcnt vmcnt(8)
	s_waitcnt lgkmcnt(0)
	s_barrier
	s_setprio 1
	s_waitcnt lgkmcnt(0)
	v_mfma_f32_16x16x32_bf16 v[132:135], v[120:123], v[160:163], v[132:135]
	v_mfma_f32_16x16x32_bf16 v[128:131], v[136:139], v[160:163], v[128:131]
	v_mfma_f32_16x16x32_bf16 v[116:119], v[120:123], v[178:181], v[116:119]
	v_mfma_f32_16x16x32_bf16 v[112:115], v[136:139], v[178:181], v[112:115]
	v_mfma_f32_16x16x32_bf16 v[108:111], v[120:123], v[186:189], v[108:111]
	v_mfma_f32_16x16x32_bf16 v[104:107], v[136:139], v[186:189], v[104:107]
	v_mfma_f32_16x16x32_bf16 v[100:103], v[120:123], v[208:211], v[100:103]
	v_mfma_f32_16x16x32_bf16 v[96:99], v[136:139], v[208:211], v[96:99]
	v_mfma_f32_16x16x32_bf16 v[132:135], v[124:127], v[164:167], v[132:135]
	v_mfma_f32_16x16x32_bf16 v[128:131], v[140:143], v[164:167], v[128:131]
	v_mfma_f32_16x16x32_bf16 v[116:119], v[124:127], v[182:185], v[116:119]
	v_mfma_f32_16x16x32_bf16 v[112:115], v[140:143], v[182:185], v[112:115]
	v_mfma_f32_16x16x32_bf16 v[108:111], v[124:127], v[204:207], v[108:111]
	v_mfma_f32_16x16x32_bf16 v[104:107], v[140:143], v[204:207], v[104:107]
	v_mfma_f32_16x16x32_bf16 v[100:103], v[124:127], v[212:215], v[100:103]
	v_mfma_f32_16x16x32_bf16 v[96:99], v[140:143], v[212:215], v[96:99]
	s_setprio 0
	s_setprio 1
	v_mfma_f32_16x16x32_bf16 v[60:63], v[144:147], v[160:163], v[60:63]
	v_mfma_f32_16x16x32_bf16 v[56:59], v[152:155], v[160:163], v[56:59]
	v_mfma_f32_16x16x32_bf16 v[52:55], v[144:147], v[178:181], v[52:55]
	v_mfma_f32_16x16x32_bf16 v[48:51], v[152:155], v[178:181], v[48:51]
	v_mfma_f32_16x16x32_bf16 v[44:47], v[144:147], v[186:189], v[44:47]
	v_mfma_f32_16x16x32_bf16 v[40:43], v[152:155], v[186:189], v[40:43]
	v_mfma_f32_16x16x32_bf16 v[36:39], v[144:147], v[208:211], v[36:39]
	v_mfma_f32_16x16x32_bf16 v[32:35], v[152:155], v[208:211], v[32:35]
	v_mfma_f32_16x16x32_bf16 v[60:63], v[148:151], v[164:167], v[60:63]
	v_mfma_f32_16x16x32_bf16 v[56:59], v[156:159], v[164:167], v[56:59]
	v_mfma_f32_16x16x32_bf16 v[52:55], v[148:151], v[182:185], v[52:55]
	v_mfma_f32_16x16x32_bf16 v[48:51], v[156:159], v[182:185], v[48:51]
	v_mfma_f32_16x16x32_bf16 v[44:47], v[148:151], v[204:207], v[44:47]
	v_mfma_f32_16x16x32_bf16 v[40:43], v[156:159], v[204:207], v[40:43]
	v_mfma_f32_16x16x32_bf16 v[36:39], v[148:151], v[212:215], v[36:39]
	v_mfma_f32_16x16x32_bf16 v[32:35], v[156:159], v[212:215], v[32:35]
	s_setprio 0
	s_barrier
	s_add_i32 s40, s90, s48
	s_mov_b32 m0, s40
	ds_read_b128 v[160:163], v241 offset:49152
	ds_read_b128 v[164:167], v241 offset:50176
	ds_read_b128 v[178:181], v241 offset:51200
	ds_read_b128 v[182:185], v241 offset:52224
	ds_read_b128 v[186:189], v241 offset:53248
	ds_read_b128 v[204:207], v241 offset:54272
	ds_read_b128 v[208:211], v241 offset:55296
	ds_read_b128 v[212:215], v241 offset:56320
	global_load_lds_dwordx4 v192, s[36:37]
	s_add_i32 m0, s40, 0x2000
	s_add_u32 s38, s38, 0x100080
	s_addc_u32 s39, s39, 0
	s_add_i32 s40, s91, s48
	global_load_lds_dwordx4 v172, s[36:37]
	s_mov_b32 m0, s40
	s_nop 0
	global_load_lds_dwordx4 v192, s[38:39]
	s_add_i32 m0, s40, 0x2000
	s_nop 0
	global_load_lds_dwordx4 v172, s[38:39]
	s_mov_b32 m0, s62
	s_nop 0
	global_load_lds_dwordx4 v168, s[98:99]
	s_mov_b32 m0, s63
	s_nop 0
	global_load_lds_dwordx4 v170, s[98:99]
	s_waitcnt vmcnt(8)
	s_waitcnt lgkmcnt(0)
	s_barrier
	s_setprio 1
	s_waitcnt lgkmcnt(0)
	v_mfma_f32_16x16x32_bf16 v[92:95], v[120:123], v[160:163], v[92:95]
	v_mfma_f32_16x16x32_bf16 v[88:91], v[136:139], v[160:163], v[88:91]
	v_mfma_f32_16x16x32_bf16 v[84:87], v[120:123], v[178:181], v[84:87]
	v_mfma_f32_16x16x32_bf16 v[80:83], v[136:139], v[178:181], v[80:83]
	v_mfma_f32_16x16x32_bf16 v[76:79], v[120:123], v[186:189], v[76:79]
	v_mfma_f32_16x16x32_bf16 v[72:75], v[136:139], v[186:189], v[72:75]
	v_mfma_f32_16x16x32_bf16 v[68:71], v[120:123], v[208:211], v[68:71]
	v_mfma_f32_16x16x32_bf16 v[64:67], v[136:139], v[208:211], v[64:67]
	v_mfma_f32_16x16x32_bf16 v[92:95], v[124:127], v[164:167], v[92:95]
	v_mfma_f32_16x16x32_bf16 v[88:91], v[140:143], v[164:167], v[88:91]
	v_mfma_f32_16x16x32_bf16 v[84:87], v[124:127], v[182:185], v[84:87]
	v_mfma_f32_16x16x32_bf16 v[80:83], v[140:143], v[182:185], v[80:83]
	v_mfma_f32_16x16x32_bf16 v[76:79], v[124:127], v[204:207], v[76:79]
	v_mfma_f32_16x16x32_bf16 v[72:75], v[140:143], v[204:207], v[72:75]
	v_mfma_f32_16x16x32_bf16 v[68:71], v[124:127], v[212:215], v[68:71]
	v_mfma_f32_16x16x32_bf16 v[64:67], v[140:143], v[212:215], v[64:67]
	s_setprio 0
	s_setprio 1
	v_mfma_f32_16x16x32_bf16 v[28:31], v[144:147], v[160:163], v[28:31]
	v_mfma_f32_16x16x32_bf16 v[24:27], v[152:155], v[160:163], v[24:27]
	v_mfma_f32_16x16x32_bf16 v[20:23], v[144:147], v[178:181], v[20:23]
	v_mfma_f32_16x16x32_bf16 v[16:19], v[152:155], v[178:181], v[16:19]
	v_mfma_f32_16x16x32_bf16 v[12:15], v[144:147], v[186:189], v[12:15]
	v_mfma_f32_16x16x32_bf16 v[8:11], v[152:155], v[186:189], v[8:11]
	v_mfma_f32_16x16x32_bf16 v[4:7], v[144:147], v[208:211], v[4:7]
	v_mfma_f32_16x16x32_bf16 v[0:3], v[152:155], v[208:211], v[0:3]
	v_mfma_f32_16x16x32_bf16 v[28:31], v[148:151], v[164:167], v[28:31]
	v_mfma_f32_16x16x32_bf16 v[24:27], v[156:159], v[164:167], v[24:27]
	v_mfma_f32_16x16x32_bf16 v[20:23], v[148:151], v[182:185], v[20:23]
	v_mfma_f32_16x16x32_bf16 v[16:19], v[156:159], v[182:185], v[16:19]
	v_mfma_f32_16x16x32_bf16 v[12:15], v[148:151], v[204:207], v[12:15]
	v_mfma_f32_16x16x32_bf16 v[8:11], v[156:159], v[204:207], v[8:11]
	v_mfma_f32_16x16x32_bf16 v[4:7], v[148:151], v[212:215], v[4:7]
	v_mfma_f32_16x16x32_bf16 v[0:3], v[156:159], v[212:215], v[0:3]
	s_setprio 0
	s_barrier
	s_add_i32 s89, s89, 2
	s_add_u32 s4, s4, 0x100
	s_addc_u32 s5, s5, 0
	s_add_u32 s64, s64, 0x100
	s_addc_u32 s65, s65, 0
	s_cmp_gt_u32 s89, 13
	s_cbranch_scc0 .LBB0_1154
	s_and_b64 vcc, exec, s[20:21]
	s_cbranch_vccz .LBB0_1157
	s_barrier

; #define PG8_STAGE(bufoff, gbase, voff) do { _Pragma("unroll") for (int _i = 0; _i < 2; ++_i) \
;         __builtin_amdgcn_global_load_lds((const unsigned*)((const char*)(gbase) + (voff)[_i]), (LAS unsigned*)(lds + (bufoff) + ldsw + _i * 8192), 16, 0, 0); } while (0)
; #define PG8_LDA(dst, b, h) do { _Pragma("unroll") for (int m = 0; m < 4; ++m) _Pragma("unroll") for (int k = 0; k < 2; ++k) dst[m][k] = *(const LAS bf16x8*)(lds + PG8_SA(b, h) + aoff + m * 2048 + k * 1024); } while (0)
; #define PG8_LDB(dst, b, h) do { _Pragma("unroll") for (int n = 0; n < 2; ++n) _Pragma("unroll") for (int k = 0; k < 2; ++k) dst[n][k] = *(const LAS bf16x8*)(lds + PG8_SB(b, h) + boff + n * 2048 + k * 1024); } while (0)
; #define PG8_MMA(ai, bj, At, Bt) do { __builtin_amdgcn_s_setprio(1); _Pragma("unroll") for (int m = 0; m < 4; ++m) _Pragma("unroll") for (int n = 0; n < 2; ++n) _Pragma("unroll") for (int k = 0; k < 2; ++k) \
;         acc[ai][bj][m][n] = __builtin_amdgcn_mfma_f32_16x16x32_bf16(Bt[n][k], At[m][k], acc[ai][bj][m][n], 0, 0, 0); __builtin_amdgcn_s_setprio(0); } while (0)
; template <class EpiT, class Sched>
; __device__ __forceinline__ void gemm_phase(LAS unsigned char* lds, const Gemm g, const Sched& S, const EpiT& E, int wv) {
;     ...
;         const bool has_next = S.next(ui + 1, nxt);
;         const char* nA = has_next ? (const char*)g.A + (size_t)nxt.pm * tstepA + (size_t)(nxt.pn >> g.zshift) * g.zA : cA; const char* nB = has_next ? (const char*)g.Bt + (size_t)nxt.pn * tstepB : cB;
;         for (int t = 0; t < nt; t += 2) {
;             const bool last = (t == nt - 2);
;             const char* a1 = cA + (size_t)(t + 1) * kstep;
;             const char* a2 = last ? nA : cA + (size_t)(t + 2) * kstep; const char* b2 = last ? nB : cB + (size_t)(t + 2) * kstep;
;             const char* a3 = a2 + kstep; const char* b3 = b2 + kstep;
;             PG8_LDB(B0, 0, 0); PG8_LDB(B1, 0, 1); PG8_SCHED; PG8_LDA(At, 0, 0); PG8_STAGE(PG8_SA(1, 1), a1 + hstepA, voffA);
;             PG8_WAIT_V(8); PG8_WAIT_L(0); PG8_BAR; PG8_MMA(0, 0, At, B0); PG8_MMA(0, 1, At, B1); PG8_BAR; PG8_SCHED;
;     ...
; #pragma unroll
;         for (int a = 0; a < 2; ++a)
; #pragma unroll
;             for (int b = 0; b < 2; ++b)
; #pragma unroll
;                 for (int m = 0; m < 4; ++m)
; #pragma unroll
;                     for (int n = 0; n < 2; ++n) acc[a][b][m][n] = (f32x4){0.f, 0.f, 0.f, 0.f};
.LBB0_1270:
	s_ashr_i32 s13, s12, 31
	s_lshl_b64 s[14:15], s[12:13], 19
	s_add_u32 s14, s28, s14
	s_addc_u32 s15, s29, s15
	s_and_b64 s[16:17], s[2:3], exec
	s_cselect_b32 s13, s15, s23
	s_cselect_b32 s51, s14, s22
	s_ashr_i32 s11, s10, 31
	s_lshl_b64 s[16:17], s[10:11], 19
	s_add_u32 s16, s30, s16
	s_addc_u32 s17, s31, s17
	s_and_b64 s[26:27], s[2:3], exec
	s_cselect_b32 s11, s17, s25
	s_cselect_b32 s52, s16, s24
	s_add_u32 s22, s22, 0x40080
	s_addc_u32 s23, s23, 0
	s_add_u32 s53, s24, 0x100
	v_mov_b32_e32 v0, 0
	s_addc_u32 s54, s25, 0
	s_mov_b32 s55, -2
	v_mov_b32_e32 v1, v0
	v_mov_b32_e32 v2, v0
	v_mov_b32_e32 v3, v0
	v_mov_b32_e32 v4, v0
	v_mov_b32_e32 v5, v0
	v_mov_b32_e32 v6, v0
	v_mov_b32_e32 v7, v0
	v_mov_b32_e32 v8, v0
	v_mov_b32_e32 v9, v0
	v_mov_b32_e32 v10, v0
	v_mov_b32_e32 v11, v0
	v_mov_b32_e32 v12, v0
	v_mov_b32_e32 v13, v0
	v_mov_b32_e32 v14, v0
	v_mov_b32_e32 v15, v0
	v_mov_b32_e32 v16, v0
	v_mov_b32_e32 v17, v0
	v_mov_b32_e32 v18, v0
	v_mov_b32_e32 v19, v0
	v_mov_b32_e32 v20, v0
	v_mov_b32_e32 v21, v0
	v_mov_b32_e32 v22, v0
	v_mov_b32_e32 v23, v0
	v_mov_b32_e32 v24, v0
	v_mov_b32_e32 v25, v0
	v_mov_b32_e32 v26, v0
	v_mov_b32_e32 v27, v0
	v_mov_b32_e32 v28, v0
	v_mov_b32_e32 v29, v0
	v_mov_b32_e32 v30, v0
	v_mov_b32_e32 v31, v0
	v_mov_b32_e32 v56, v0
	v_mov_b32_e32 v57, v0
	v_mov_b32_e32 v58, v0
	v_mov_b32_e32 v59, v0
	v_mov_b32_e32 v60, v0
	v_mov_b32_e32 v61, v0
	v_mov_b32_e32 v62, v0
	v_mov_b32_e32 v63, v0
	v_mov_b32_e32 v72, v0
	v_mov_b32_e32 v73, v0
	v_mov_b32_e32 v74, v0
	v_mov_b32_e32 v75, v0
	v_mov_b32_e32 v76, v0
	v_mov_b32_e32 v77, v0
	v_mov_b32_e32 v78, v0
	v_mov_b32_e32 v79, v0
	v_mov_b32_e32 v80, v0
	v_mov_b32_e32 v81, v0
	v_mov_b32_e32 v82, v0
	v_mov_b32_e32 v83, v0
	v_mov_b32_e32 v84, v0
	v_mov_b32_e32 v85, v0
	v_mov_b32_e32 v86, v0
	v_mov_b32_e32 v87, v0
	v_mov_b32_e32 v88, v0
	v_mov_b32_e32 v89, v0
	v_mov_b32_e32 v90, v0
	v_mov_b32_e32 v91, v0
	v_mov_b32_e32 v92, v0
	v_mov_b32_e32 v93, v0
	v_mov_b32_e32 v94, v0
	v_mov_b32_e32 v95, v0
	v_mov_b32_e32 v32, v0
	v_mov_b32_e32 v33, v0
	v_mov_b32_e32 v34, v0
	v_mov_b32_e32 v35, v0
	v_mov_b32_e32 v36, v0
	v_mov_b32_e32 v37, v0
	v_mov_b32_e32 v38, v0
	v_mov_b32_e32 v39, v0
	v_mov_b32_e32 v40, v0
	v_mov_b32_e32 v41, v0
	v_mov_b32_e32 v42, v0
	v_mov_b32_e32 v43, v0
	v_mov_b32_e32 v44, v0
	v_mov_b32_e32 v45, v0
	v_mov_b32_e32 v46, v0
	v_mov_b32_e32 v47, v0
	v_mov_b32_e32 v48, v0
	v_mov_b32_e32 v49, v0
	v_mov_b32_e32 v50, v0
	v_mov_b32_e32 v51, v0
	v_mov_b32_e32 v52, v0
	v_mov_b32_e32 v53, v0
	v_mov_b32_e32 v54, v0
	v_mov_b32_e32 v55, v0
	v_mov_b32_e32 v64, v0
	v_mov_b32_e32 v65, v0
	v_mov_b32_e32 v66, v0
	v_mov_b32_e32 v67, v0
	v_mov_b32_e32 v68, v0
	v_mov_b32_e32 v69, v0
	v_mov_b32_e32 v70, v0
	v_mov_b32_e32 v71, v0
	v_mov_b32_e32 v96, v0
	v_mov_b32_e32 v97, v0
	v_mov_b32_e32 v98, v0
	v_mov_b32_e32 v99, v0
	v_mov_b32_e32 v100, v0
	v_mov_b32_e32 v101, v0
	v_mov_b32_e32 v102, v0
	v_mov_b32_e32 v103, v0
	v_mov_b32_e32 v104, v0
	v_mov_b32_e32 v105, v0
	v_mov_b32_e32 v106, v0
	v_mov_b32_e32 v107, v0
	v_mov_b32_e32 v108, v0
	v_mov_b32_e32 v109, v0
	v_mov_b32_e32 v110, v0
	v_mov_b32_e32 v111, v0
	v_mov_b32_e32 v112, v0
	v_mov_b32_e32 v113, v0
	v_mov_b32_e32 v114, v0
	v_mov_b32_e32 v115, v0
	v_mov_b32_e32 v116, v0
	v_mov_b32_e32 v117, v0
	v_mov_b32_e32 v118, v0
	v_mov_b32_e32 v119, v0
	v_mov_b32_e32 v120, v0
	v_mov_b32_e32 v121, v0
	v_mov_b32_e32 v122, v0
	v_mov_b32_e32 v123, v0
	v_mov_b32_e32 v124, v0
	v_mov_b32_e32 v125, v0
	v_mov_b32_e32 v126, v0
	v_mov_b32_e32 v127, v0
	v_add_u32_e32 v250, 0x10000, v158
	v_add_u32_e32 v251, 0x14000, v158
	v_add_u32_e32 v252, 0x18000, v158
	v_add_u32_e32 v253, 0x1c000, v158
.LBB0_1271:
	s_add_u32 s24, s22, 0xfffc0080
	s_addc_u32 s25, s23, -1
	s_add_i32 s56, 0, 0x10000
	s_cmp_eq_u32 s55, 12
	s_cselect_b32 s27, s13, s25
	s_cselect_b32 s26, s51, s24
	s_cselect_b32 s25, s11, s54
	s_cselect_b32 s24, s52, s53
	s_add_i32 s58, 0, 0x14000
	ds_read_b128 v[128:131], v250
	ds_read_b128 v[132:135], v250 offset:1024
	ds_read_b128 v[146:149], v250 offset:2048
	ds_read_b128 v[150:153], v250 offset:3072
	ds_read_b128 v[154:157], v251
	ds_read_b128 v[160:163], v251 offset:1024
	ds_read_b128 v[164:167], v251 offset:2048
	ds_read_b128 v[168:171], v251 offset:3072
	s_add_i32 m0, s19, 0xc000
	ds_read_b128 v[172:175], v159
	ds_read_b128 v[176:179], v159 offset:1024
	ds_read_b128 v[180:183], v159 offset:2048
	ds_read_b128 v[184:187], v159 offset:3072
	ds_read_b128 v[188:191], v159 offset:4096
	ds_read_b128 v[204:207], v159 offset:5120
	ds_read_b128 v[208:211], v159 offset:6144
	ds_read_b128 v[212:215], v159 offset:7168
	global_load_lds_dwordx4 v142, s[22:23]
	s_add_i32 m0, s19, 0xe000
	s_nop 0
	global_load_lds_dwordx4 v144, s[22:23]
	s_waitcnt vmcnt(8)
	s_waitcnt lgkmcnt(0)
	s_barrier
; #define PG8_STAGE(bufoff, gbase, voff) do { _Pragma("unroll") for (int _i = 0; _i < 2; ++_i) \
;         __builtin_amdgcn_global_load_lds((const unsigned*)((const char*)(gbase) + (voff)[_i]), (LAS unsigned*)(lds + (bufoff) + ldsw + _i * 8192), 16, 0, 0); } while (0)
; #define PG8_LDA(dst, b, h) do { _Pragma("unroll") for (int m = 0; m < 4; ++m) _Pragma("unroll") for (int k = 0; k < 2; ++k) dst[m][k] = *(const LAS bf16x8*)(lds + PG8_SA(b, h) + aoff + m * 2048 + k * 1024); } while (0)
; #define PG8_MMA(ai, bj, At, Bt) do { __builtin_amdgcn_s_setprio(1); _Pragma("unroll") for (int m = 0; m < 4; ++m) _Pragma("unroll") for (int n = 0; n < 2; ++n) _Pragma("unroll") for (int k = 0; k < 2; ++k) \
;         acc[ai][bj][m][n] = __builtin_amdgcn_mfma_f32_16x16x32_bf16(Bt[n][k], At[m][k], acc[ai][bj][m][n], 0, 0, 0); __builtin_amdgcn_s_setprio(0); } while (0)
; #define PG8_WAIT_V(n) asm volatile("s_waitcnt vmcnt(" #n ")" ::: "memory")
; #define PG8_WAIT_L(n) asm volatile("s_waitcnt lgkmcnt(" #n ")" ::: "memory")
; #define PG8_BAR __builtin_amdgcn_s_barrier()
; #define PG8_SCHED __builtin_amdgcn_sched_barrier(0)
; template <class EpiT, class Sched>
; __device__ __forceinline__ void gemm_phase(LAS unsigned char* lds, const Gemm g, const Sched& S, const EpiT& E, int wv) {
;     ...
;             PG8_WAIT_V(8); PG8_WAIT_L(0); PG8_BAR; PG8_MMA(0, 0, At, B0); PG8_MMA(0, 1, At, B1); PG8_BAR; PG8_SCHED;
;             PG8_LDA(At, 0, 1); PG8_STAGE(PG8_SB(0, 0), b2, voffB); PG8_STAGE(PG8_SB(0, 1), b2 + hstepB, voffB); PG8_STAGE(PG8_SA(0, 0), a2, voffA);
;             PG8_WAIT_V(8); PG8_WAIT_L(0); PG8_BAR; PG8_MMA(1, 0, At, B0); PG8_MMA(1, 1, At, B1); PG8_BAR; PG8_SCHED;
	s_setprio 1
	s_waitcnt lgkmcnt(0)
	v_mfma_f32_16x16x32_bf16 v[124:127], v[128:131], v[172:175], v[124:127]
	v_mfma_f32_16x16x32_bf16 v[120:123], v[146:149], v[172:175], v[120:123]
	v_mfma_f32_16x16x32_bf16 v[116:119], v[128:131], v[180:183], v[116:119]
	v_mfma_f32_16x16x32_bf16 v[112:115], v[146:149], v[180:183], v[112:115]
	v_mfma_f32_16x16x32_bf16 v[108:111], v[128:131], v[188:191], v[108:111]
	v_mfma_f32_16x16x32_bf16 v[104:107], v[146:149], v[188:191], v[104:107]
	v_mfma_f32_16x16x32_bf16 v[100:103], v[128:131], v[208:211], v[100:103]
	v_mfma_f32_16x16x32_bf16 v[96:99], v[146:149], v[208:211], v[96:99]
	v_mfma_f32_16x16x32_bf16 v[124:127], v[132:135], v[176:179], v[124:127]
	v_mfma_f32_16x16x32_bf16 v[120:123], v[150:153], v[176:179], v[120:123]
	v_mfma_f32_16x16x32_bf16 v[116:119], v[132:135], v[184:187], v[116:119]
	v_mfma_f32_16x16x32_bf16 v[112:115], v[150:153], v[184:187], v[112:115]
	v_mfma_f32_16x16x32_bf16 v[108:111], v[132:135], v[204:207], v[108:111]
	v_mfma_f32_16x16x32_bf16 v[104:107], v[150:153], v[204:207], v[104:107]
	v_mfma_f32_16x16x32_bf16 v[100:103], v[132:135], v[212:215], v[100:103]
	v_mfma_f32_16x16x32_bf16 v[96:99], v[150:153], v[212:215], v[96:99]
	s_setprio 0
	s_setprio 1
	v_mfma_f32_16x16x32_bf16 v[68:71], v[154:157], v[172:175], v[68:71]
	v_mfma_f32_16x16x32_bf16 v[64:67], v[164:167], v[172:175], v[64:67]
	v_mfma_f32_16x16x32_bf16 v[52:55], v[154:157], v[180:183], v[52:55]
	v_mfma_f32_16x16x32_bf16 v[48:51], v[164:167], v[180:183], v[48:51]
	v_mfma_f32_16x16x32_bf16 v[44:47], v[154:157], v[188:191], v[44:47]
	v_mfma_f32_16x16x32_bf16 v[40:43], v[164:167], v[188:191], v[40:43]
	v_mfma_f32_16x16x32_bf16 v[36:39], v[154:157], v[208:211], v[36:39]
	v_mfma_f32_16x16x32_bf16 v[32:35], v[164:167], v[208:211], v[32:35]
	v_mfma_f32_16x16x32_bf16 v[68:71], v[160:163], v[176:179], v[68:71]
	v_mfma_f32_16x16x32_bf16 v[64:67], v[168:171], v[176:179], v[64:67]
	v_mfma_f32_16x16x32_bf16 v[52:55], v[160:163], v[184:187], v[52:55]
	v_mfma_f32_16x16x32_bf16 v[48:51], v[168:171], v[184:187], v[48:51]
	v_mfma_f32_16x16x32_bf16 v[44:47], v[160:163], v[204:207], v[44:47]
	v_mfma_f32_16x16x32_bf16 v[40:43], v[168:171], v[204:207], v[40:43]
	v_mfma_f32_16x16x32_bf16 v[36:39], v[160:163], v[212:215], v[36:39]
	v_mfma_f32_16x16x32_bf16 v[32:35], v[168:171], v[212:215], v[32:35]
	s_setprio 0
	s_barrier
	s_add_i32 s56, s56, s33
	s_add_u32 s62, s24, s92
	s_addc_u32 s63, s25, s93
	s_mov_b32 m0, s56
	ds_read_b128 v[172:175], v159 offset:16384
	ds_read_b128 v[176:179], v159 offset:17408
	ds_read_b128 v[180:183], v159 offset:18432
	ds_read_b128 v[184:187], v159 offset:19456
	ds_read_b128 v[188:191], v159 offset:20480
	ds_read_b128 v[204:207], v159 offset:21504
	ds_read_b128 v[208:211], v159 offset:22528
	ds_read_b128 v[212:215], v159 offset:23552
	global_load_lds_dwordx4 v192, s[24:25]
	s_add_i32 m0, s56, 0x2000
	s_add_u32 s56, s24, 0x40000
	s_addc_u32 s57, s25, 0
	s_add_i32 s58, s58, s33
	global_load_lds_dwordx4 v140, s[24:25]
	s_mov_b32 m0, s58
	s_nop 0
	global_load_lds_dwordx4 v192, s[56:57]
	s_add_i32 m0, s58, 0x2000
	s_nop 0
	global_load_lds_dwordx4 v140, s[56:57]
	s_add_u32 s64, s26, s92
	s_addc_u32 s65, s27, s93
	s_mov_b32 m0, s19
	s_nop 0
	global_load_lds_dwordx4 v136, s[26:27]
	s_mov_b32 m0, s21
	s_nop 0
	global_load_lds_dwordx4 v138, s[26:27]
	s_waitcnt vmcnt(8)
	s_waitcnt lgkmcnt(0)
	s_barrier
	s_setprio 1
	s_waitcnt lgkmcnt(0)
	v_mfma_f32_16x16x32_bf16 v[92:95], v[128:131], v[172:175], v[92:95]
	v_mfma_f32_16x16x32_bf16 v[88:91], v[146:149], v[172:175], v[88:91]
	v_mfma_f32_16x16x32_bf16 v[84:87], v[128:131], v[180:183], v[84:87]
	v_mfma_f32_16x16x32_bf16 v[80:83], v[146:149], v[180:183], v[80:83]
	v_mfma_f32_16x16x32_bf16 v[76:79], v[128:131], v[188:191], v[76:79]
	v_mfma_f32_16x16x32_bf16 v[72:75], v[146:149], v[188:191], v[72:75]
	v_mfma_f32_16x16x32_bf16 v[60:63], v[128:131], v[208:211], v[60:63]
	v_mfma_f32_16x16x32_bf16 v[56:59], v[146:149], v[208:211], v[56:59]
	v_mfma_f32_16x16x32_bf16 v[92:95], v[132:135], v[176:179], v[92:95]
	v_mfma_f32_16x16x32_bf16 v[88:91], v[150:153], v[176:179], v[88:91]
	v_mfma_f32_16x16x32_bf16 v[84:87], v[132:135], v[184:187], v[84:87]
	v_mfma_f32_16x16x32_bf16 v[80:83], v[150:153], v[184:187], v[80:83]
	v_mfma_f32_16x16x32_bf16 v[76:79], v[132:135], v[204:207], v[76:79]
	v_mfma_f32_16x16x32_bf16 v[72:75], v[150:153], v[204:207], v[72:75]
	v_mfma_f32_16x16x32_bf16 v[60:63], v[132:135], v[212:215], v[60:63]
	v_mfma_f32_16x16x32_bf16 v[56:59], v[150:153], v[212:215], v[56:59]
	s_setprio 0
	s_setprio 1
	v_mfma_f32_16x16x32_bf16 v[28:31], v[154:157], v[172:175], v[28:31]
	v_mfma_f32_16x16x32_bf16 v[24:27], v[164:167], v[172:175], v[24:27]
	v_mfma_f32_16x16x32_bf16 v[20:23], v[154:157], v[180:183], v[20:23]
	v_mfma_f32_16x16x32_bf16 v[16:19], v[164:167], v[180:183], v[16:19]
	v_mfma_f32_16x16x32_bf16 v[12:15], v[154:157], v[188:191], v[12:15]
	v_mfma_f32_16x16x32_bf16 v[8:11], v[164:167], v[188:191], v[8:11]
	v_mfma_f32_16x16x32_bf16 v[4:7], v[154:157], v[208:211], v[4:7]
	v_mfma_f32_16x16x32_bf16 v[0:3], v[164:167], v[208:211], v[0:3]
	v_mfma_f32_16x16x32_bf16 v[28:31], v[160:163], v[176:179], v[28:31]
	v_mfma_f32_16x16x32_bf16 v[24:27], v[168:171], v[176:179], v[24:27]
	v_mfma_f32_16x16x32_bf16 v[20:23], v[160:163], v[184:187], v[20:23]
	v_mfma_f32_16x16x32_bf16 v[16:19], v[168:171], v[184:187], v[16:19]
	v_mfma_f32_16x16x32_bf16 v[12:15], v[160:163], v[204:207], v[12:15]
	v_mfma_f32_16x16x32_bf16 v[8:11], v[168:171], v[204:207], v[8:11]
	v_mfma_f32_16x16x32_bf16 v[4:7], v[160:163], v[212:215], v[4:7]
	v_mfma_f32_16x16x32_bf16 v[0:3], v[168:171], v[212:215], v[0:3]
	s_setprio 0
	s_barrier
; #define PG8_STAGE(bufoff, gbase, voff) do { _Pragma("unroll") for (int _i = 0; _i < 2; ++_i) \
;         __builtin_amdgcn_global_load_lds((const unsigned*)((const char*)(gbase) + (voff)[_i]), (LAS unsigned*)(lds + (bufoff) + ldsw + _i * 8192), 16, 0, 0); } while (0)
; #define PG8_LDA(dst, b, h) do { _Pragma("unroll") for (int m = 0; m < 4; ++m) _Pragma("unroll") for (int k = 0; k < 2; ++k) dst[m][k] = *(const LAS bf16x8*)(lds + PG8_SA(b, h) + aoff + m * 2048 + k * 1024); } while (0)
; #define PG8_LDB(dst, b, h) do { _Pragma("unroll") for (int n = 0; n < 2; ++n) _Pragma("unroll") for (int k = 0; k < 2; ++k) dst[n][k] = *(const LAS bf16x8*)(lds + PG8_SB(b, h) + boff + n * 2048 + k * 1024); } while (0)
; #define PG8_MMA(ai, bj, At, Bt) do { __builtin_amdgcn_s_setprio(1); _Pragma("unroll") for (int m = 0; m < 4; ++m) _Pragma("unroll") for (int n = 0; n < 2; ++n) _Pragma("unroll") for (int k = 0; k < 2; ++k) \
;         acc[ai][bj][m][n] = __builtin_amdgcn_mfma_f32_16x16x32_bf16(Bt[n][k], At[m][k], acc[ai][bj][m][n], 0, 0, 0); __builtin_amdgcn_s_setprio(0); } while (0)
; #define PG8_WAIT_V(n) asm volatile("s_waitcnt vmcnt(" #n ")" ::: "memory")
; #define PG8_WAIT_L(n) asm volatile("s_waitcnt lgkmcnt(" #n ")" ::: "memory")
; #define PG8_BAR __builtin_amdgcn_s_barrier()
; #define PG8_SCHED __builtin_amdgcn_sched_barrier(0)
; template <class EpiT, class Sched>
; __device__ __forceinline__ void gemm_phase(LAS unsigned char* lds, const Gemm g, const Sched& S, const EpiT& E, int wv) {
;     ...
;             PG8_LDB(B0, 1, 0); PG8_LDB(B1, 1, 1); PG8_SCHED; PG8_LDA(At, 1, 0); PG8_STAGE(PG8_SA(0, 1), a2 + hstepA, voffA);
;             PG8_WAIT_V(8); PG8_WAIT_L(0); PG8_BAR; PG8_MMA(0, 0, At, B0); PG8_MMA(0, 1, At, B1); PG8_BAR; PG8_SCHED;
;             PG8_LDA(At, 1, 1); PG8_STAGE(PG8_SB(1, 0), b3, voffB); PG8_STAGE(PG8_SB(1, 1), b3 + hstepB, voffB); PG8_STAGE(PG8_SA(1, 0), a3, voffA);
;             PG8_WAIT_V(8); PG8_WAIT_L(0); PG8_BAR; PG8_MMA(1, 0, At, B0); PG8_MMA(1, 1, At, B1); PG8_BAR; PG8_SCHED;
;         }
;         if (wr == 0) PG8_BAR;
	s_add_i32 s56, 0, 0x18000
	s_add_i32 s57, 0, 0x1c000
	ds_read_b128 v[128:131], v252
	ds_read_b128 v[132:135], v252 offset:1024
	ds_read_b128 v[146:149], v252 offset:2048
	ds_read_b128 v[150:153], v252 offset:3072
	ds_read_b128 v[154:157], v253
	ds_read_b128 v[160:163], v253 offset:1024
	ds_read_b128 v[164:167], v253 offset:2048
	ds_read_b128 v[168:171], v253 offset:3072
	s_add_u32 s26, s26, 0x40000
	s_addc_u32 s27, s27, 0
	s_mov_b32 m0, s38
	ds_read_b128 v[172:175], v159 offset:32768
	ds_read_b128 v[176:179], v159 offset:33792
	ds_read_b128 v[180:183], v159 offset:34816
	ds_read_b128 v[184:187], v159 offset:35840
	ds_read_b128 v[188:191], v159 offset:36864
	ds_read_b128 v[204:207], v159 offset:37888
	ds_read_b128 v[208:211], v159 offset:38912
	ds_read_b128 v[212:215], v159 offset:39936
	global_load_lds_dwordx4 v136, s[26:27]
	s_mov_b32 m0, s39
	s_nop 0
	global_load_lds_dwordx4 v138, s[26:27]
	s_waitcnt vmcnt(8)
	s_waitcnt lgkmcnt(0)
	s_barrier
	s_setprio 1
	s_waitcnt lgkmcnt(0)
	v_mfma_f32_16x16x32_bf16 v[124:127], v[128:131], v[172:175], v[124:127]
	v_mfma_f32_16x16x32_bf16 v[120:123], v[146:149], v[172:175], v[120:123]
	v_mfma_f32_16x16x32_bf16 v[116:119], v[128:131], v[180:183], v[116:119]
	v_mfma_f32_16x16x32_bf16 v[112:115], v[146:149], v[180:183], v[112:115]
	v_mfma_f32_16x16x32_bf16 v[108:111], v[128:131], v[188:191], v[108:111]
	v_mfma_f32_16x16x32_bf16 v[104:107], v[146:149], v[188:191], v[104:107]
	v_mfma_f32_16x16x32_bf16 v[100:103], v[128:131], v[208:211], v[100:103]
	v_mfma_f32_16x16x32_bf16 v[96:99], v[146:149], v[208:211], v[96:99]
	v_mfma_f32_16x16x32_bf16 v[124:127], v[132:135], v[176:179], v[124:127]
	v_mfma_f32_16x16x32_bf16 v[120:123], v[150:153], v[176:179], v[120:123]
	v_mfma_f32_16x16x32_bf16 v[116:119], v[132:135], v[184:187], v[116:119]
	v_mfma_f32_16x16x32_bf16 v[112:115], v[150:153], v[184:187], v[112:115]
	v_mfma_f32_16x16x32_bf16 v[108:111], v[132:135], v[204:207], v[108:111]
	v_mfma_f32_16x16x32_bf16 v[104:107], v[150:153], v[204:207], v[104:107]
	v_mfma_f32_16x16x32_bf16 v[100:103], v[132:135], v[212:215], v[100:103]
	v_mfma_f32_16x16x32_bf16 v[96:99], v[150:153], v[212:215], v[96:99]
	s_setprio 0
	s_setprio 1
	v_mfma_f32_16x16x32_bf16 v[68:71], v[154:157], v[172:175], v[68:71]
	v_mfma_f32_16x16x32_bf16 v[64:67], v[164:167], v[172:175], v[64:67]
	v_mfma_f32_16x16x32_bf16 v[52:55], v[154:157], v[180:183], v[52:55]
	v_mfma_f32_16x16x32_bf16 v[48:51], v[164:167], v[180:183], v[48:51]
	v_mfma_f32_16x16x32_bf16 v[44:47], v[154:157], v[188:191], v[44:47]
	v_mfma_f32_16x16x32_bf16 v[40:43], v[164:167], v[188:191], v[40:43]
	v_mfma_f32_16x16x32_bf16 v[36:39], v[154:157], v[208:211], v[36:39]
	v_mfma_f32_16x16x32_bf16 v[32:35], v[164:167], v[208:211], v[32:35]
	v_mfma_f32_16x16x32_bf16 v[68:71], v[160:163], v[176:179], v[68:71]
	v_mfma_f32_16x16x32_bf16 v[64:67], v[168:171], v[176:179], v[64:67]
	v_mfma_f32_16x16x32_bf16 v[52:55], v[160:163], v[184:187], v[52:55]
	v_mfma_f32_16x16x32_bf16 v[48:51], v[168:171], v[184:187], v[48:51]
	v_mfma_f32_16x16x32_bf16 v[44:47], v[160:163], v[204:207], v[44:47]
	v_mfma_f32_16x16x32_bf16 v[40:43], v[168:171], v[204:207], v[40:43]
	v_mfma_f32_16x16x32_bf16 v[36:39], v[160:163], v[212:215], v[36:39]
	v_mfma_f32_16x16x32_bf16 v[32:35], v[168:171], v[212:215], v[32:35]
	s_setprio 0
	s_barrier
	s_add_i32 s26, s56, s33
	s_mov_b32 m0, s26
	ds_read_b128 v[172:175], v159 offset:49152
	ds_read_b128 v[176:179], v159 offset:50176
	ds_read_b128 v[180:183], v159 offset:51200
	ds_read_b128 v[184:187], v159 offset:52224
	ds_read_b128 v[188:191], v159 offset:53248
	ds_read_b128 v[204:207], v159 offset:54272
	ds_read_b128 v[208:211], v159 offset:55296
	ds_read_b128 v[212:215], v159 offset:56320
	global_load_lds_dwordx4 v192, s[62:63]
	s_add_i32 m0, s26, 0x2000
	s_add_u32 s24, s24, 0x40080
	s_addc_u32 s25, s25, 0
	s_add_i32 s26, s57, s33
	global_load_lds_dwordx4 v140, s[62:63]
	s_mov_b32 m0, s26
	s_nop 0
	global_load_lds_dwordx4 v192, s[24:25]
	s_add_i32 m0, s26, 0x2000
	s_nop 0
	global_load_lds_dwordx4 v140, s[24:25]
	s_mov_b32 m0, s40
	s_nop 0
	global_load_lds_dwordx4 v136, s[64:65]
	s_mov_b32 m0, s41
	s_nop 0
	global_load_lds_dwordx4 v138, s[64:65]
	s_waitcnt vmcnt(8)
	s_waitcnt lgkmcnt(0)
	s_barrier
	s_setprio 1
	s_waitcnt lgkmcnt(0)
	v_mfma_f32_16x16x32_bf16 v[92:95], v[128:131], v[172:175], v[92:95]
	v_mfma_f32_16x16x32_bf16 v[88:91], v[146:149], v[172:175], v[88:91]
	v_mfma_f32_16x16x32_bf16 v[84:87], v[128:131], v[180:183], v[84:87]
	v_mfma_f32_16x16x32_bf16 v[80:83], v[146:149], v[180:183], v[80:83]
	v_mfma_f32_16x16x32_bf16 v[76:79], v[128:131], v[188:191], v[76:79]
	v_mfma_f32_16x16x32_bf16 v[72:75], v[146:149], v[188:191], v[72:75]
	v_mfma_f32_16x16x32_bf16 v[60:63], v[128:131], v[208:211], v[60:63]
	v_mfma_f32_16x16x32_bf16 v[56:59], v[146:149], v[208:211], v[56:59]
	v_mfma_f32_16x16x32_bf16 v[92:95], v[132:135], v[176:179], v[92:95]
	v_mfma_f32_16x16x32_bf16 v[88:91], v[150:153], v[176:179], v[88:91]
	v_mfma_f32_16x16x32_bf16 v[84:87], v[132:135], v[184:187], v[84:87]
	v_mfma_f32_16x16x32_bf16 v[80:83], v[150:153], v[184:187], v[80:83]
	v_mfma_f32_16x16x32_bf16 v[76:79], v[132:135], v[204:207], v[76:79]
	v_mfma_f32_16x16x32_bf16 v[72:75], v[150:153], v[204:207], v[72:75]
	v_mfma_f32_16x16x32_bf16 v[60:63], v[132:135], v[212:215], v[60:63]
	v_mfma_f32_16x16x32_bf16 v[56:59], v[150:153], v[212:215], v[56:59]
	s_setprio 0
	s_setprio 1
	v_mfma_f32_16x16x32_bf16 v[28:31], v[154:157], v[172:175], v[28:31]
	v_mfma_f32_16x16x32_bf16 v[24:27], v[164:167], v[172:175], v[24:27]
	v_mfma_f32_16x16x32_bf16 v[20:23], v[154:157], v[180:183], v[20:23]
	v_mfma_f32_16x16x32_bf16 v[16:19], v[164:167], v[180:183], v[16:19]
	v_mfma_f32_16x16x32_bf16 v[12:15], v[154:157], v[188:191], v[12:15]
	v_mfma_f32_16x16x32_bf16 v[8:11], v[164:167], v[188:191], v[8:11]
	v_mfma_f32_16x16x32_bf16 v[4:7], v[154:157], v[208:211], v[4:7]
	v_mfma_f32_16x16x32_bf16 v[0:3], v[164:167], v[208:211], v[0:3]
	v_mfma_f32_16x16x32_bf16 v[28:31], v[160:163], v[176:179], v[28:31]
	v_mfma_f32_16x16x32_bf16 v[24:27], v[168:171], v[176:179], v[24:27]
	v_mfma_f32_16x16x32_bf16 v[20:23], v[160:163], v[184:187], v[20:23]
	v_mfma_f32_16x16x32_bf16 v[16:19], v[168:171], v[184:187], v[16:19]
	v_mfma_f32_16x16x32_bf16 v[12:15], v[160:163], v[204:207], v[12:15]
	v_mfma_f32_16x16x32_bf16 v[8:11], v[168:171], v[204:207], v[8:11]
	v_mfma_f32_16x16x32_bf16 v[4:7], v[160:163], v[212:215], v[4:7]
	v_mfma_f32_16x16x32_bf16 v[0:3], v[168:171], v[212:215], v[0:3]
	s_setprio 0
	s_barrier
	s_add_i32 s55, s55, 2
	s_add_u32 s22, s22, 0x100
	s_addc_u32 s23, s23, 0
	s_add_u32 s53, s53, 0x100
	s_addc_u32 s54, s54, 0
	s_cmp_gt_u32 s55, 13
	s_cbranch_scc0 .LBB0_1271
	s_and_b64 vcc, exec, s[8:9]
	s_cbranch_vccz .LBB0_1274
	s_barrier

; #define PG8_STAGE(bufoff, gbase, voff) do { _Pragma("unroll") for (int _i = 0; _i < 2; ++_i) \
;         __builtin_amdgcn_global_load_lds((const unsigned*)((const char*)(gbase) + (voff)[_i]), (LAS unsigned*)(lds + (bufoff) + ldsw + _i * 8192), 16, 0, 0); } while (0)
; #define PG8_LDA(dst, b, h) do { _Pragma("unroll") for (int m = 0; m < 4; ++m) _Pragma("unroll") for (int k = 0; k < 2; ++k) dst[m][k] = *(const LAS bf16x8*)(lds + PG8_SA(b, h) + aoff + m * 2048 + k * 1024); } while (0)
; #define PG8_LDB(dst, b, h) do { _Pragma("unroll") for (int n = 0; n < 2; ++n) _Pragma("unroll") for (int k = 0; k < 2; ++k) dst[n][k] = *(const LAS bf16x8*)(lds + PG8_SB(b, h) + boff + n * 2048 + k * 1024); } while (0)
; #define PG8_MMA(ai, bj, At, Bt) do { __builtin_amdgcn_s_setprio(1); _Pragma("unroll") for (int m = 0; m < 4; ++m) _Pragma("unroll") for (int n = 0; n < 2; ++n) _Pragma("unroll") for (int k = 0; k < 2; ++k) \
;         acc[ai][bj][m][n] = __builtin_amdgcn_mfma_f32_16x16x32_bf16(Bt[n][k], At[m][k], acc[ai][bj][m][n], 0, 0, 0); __builtin_amdgcn_s_setprio(0); } while (0)
; template <class EpiT, class Sched>
; __device__ __forceinline__ void gemm_phase(LAS unsigned char* lds, const Gemm g, const Sched& S, const EpiT& E, int wv) {
;     ...
;         const bool has_next = S.next(ui + 1, nxt);
;         const char* nA = has_next ? (const char*)g.A + (size_t)nxt.pm * tstepA + (size_t)(nxt.pn >> g.zshift) * g.zA : cA; const char* nB = has_next ? (const char*)g.Bt + (size_t)nxt.pn * tstepB : cB;
;         for (int t = 0; t < nt; t += 2) {
;             const bool last = (t == nt - 2);
;             const char* a1 = cA + (size_t)(t + 1) * kstep;
;             const char* a2 = last ? nA : cA + (size_t)(t + 2) * kstep; const char* b2 = last ? nB : cB + (size_t)(t + 2) * kstep;
;             const char* a3 = a2 + kstep; const char* b3 = b2 + kstep;
;             PG8_LDB(B0, 0, 0); PG8_LDB(B1, 0, 1); PG8_SCHED; PG8_LDA(At, 0, 0); PG8_STAGE(PG8_SA(1, 1), a1 + hstepA, voffA);
;             PG8_WAIT_V(8); PG8_WAIT_L(0); PG8_BAR; PG8_MMA(0, 0, At, B0); PG8_MMA(0, 1, At, B1); PG8_BAR; PG8_SCHED;
;     ...
; #pragma unroll
;         for (int a = 0; a < 2; ++a)
; #pragma unroll
;             for (int b = 0; b < 2; ++b)
; #pragma unroll
;                 for (int m = 0; m < 4; ++m)
; #pragma unroll
;                     for (int n = 0; n < 2; ++n) acc[a][b][m][n] = (f32x4){0.f, 0.f, 0.f, 0.f};
.Lffn_m_done_b:
.LBB0_1334:
	s_ashr_i32 s17, s16, 31
	s_lshl_b64 s[0:1], s[16:17], 21
	s_add_u32 s0, s29, s0
	s_addc_u32 s1, s30, s1
	s_and_b64 s[20:21], s[2:3], exec
	s_cselect_b32 s17, s1, s5
	s_cselect_b32 s19, s0, s4
	s_ashr_i32 s11, s10, 31
	s_lshl_b64 s[20:21], s[10:11], 21
	s_add_u32 s20, s31, s20
	s_addc_u32 s21, s36, s21
	s_and_b64 s[26:27], s[2:3], exec
	s_cselect_b32 s11, s21, s25
	s_cselect_b32 s23, s20, s24
	s_add_u32 s4, s4, 0x100080
	s_addc_u32 s5, s5, 0
	s_add_u32 s33, s24, 0x100
	v_mov_b32_e32 v0, 0
	s_addc_u32 s58, s25, 0
	s_mov_b32 s59, -2
	v_mov_b32_e32 v1, v0
	v_mov_b32_e32 v2, v0
	v_mov_b32_e32 v3, v0
	v_mov_b32_e32 v4, v0
	v_mov_b32_e32 v5, v0
	v_mov_b32_e32 v6, v0
	v_mov_b32_e32 v7, v0
	v_mov_b32_e32 v8, v0
	v_mov_b32_e32 v9, v0
	v_mov_b32_e32 v10, v0
	v_mov_b32_e32 v11, v0
	v_mov_b32_e32 v12, v0
	v_mov_b32_e32 v13, v0
	v_mov_b32_e32 v14, v0
	v_mov_b32_e32 v15, v0
	v_mov_b32_e32 v16, v0
	v_mov_b32_e32 v17, v0
	v_mov_b32_e32 v18, v0
	v_mov_b32_e32 v19, v0
	v_mov_b32_e32 v20, v0
	v_mov_b32_e32 v21, v0
	v_mov_b32_e32 v22, v0
	v_mov_b32_e32 v23, v0
	v_mov_b32_e32 v24, v0
	v_mov_b32_e32 v25, v0
	v_mov_b32_e32 v26, v0
	v_mov_b32_e32 v27, v0
	v_mov_b32_e32 v28, v0
	v_mov_b32_e32 v29, v0
	v_mov_b32_e32 v30, v0
	v_mov_b32_e32 v31, v0
	v_mov_b32_e32 v64, v0
	v_mov_b32_e32 v65, v0
	v_mov_b32_e32 v66, v0
	v_mov_b32_e32 v67, v0
	v_mov_b32_e32 v68, v0
	v_mov_b32_e32 v69, v0
	v_mov_b32_e32 v70, v0
	v_mov_b32_e32 v71, v0
	v_mov_b32_e32 v72, v0
	v_mov_b32_e32 v73, v0
	v_mov_b32_e32 v74, v0
	v_mov_b32_e32 v75, v0
	v_mov_b32_e32 v76, v0
	v_mov_b32_e32 v77, v0
	v_mov_b32_e32 v78, v0
	v_mov_b32_e32 v79, v0
	v_mov_b32_e32 v80, v0
	v_mov_b32_e32 v81, v0
	v_mov_b32_e32 v82, v0
	v_mov_b32_e32 v83, v0
	v_mov_b32_e32 v84, v0
	v_mov_b32_e32 v85, v0
	v_mov_b32_e32 v86, v0
	v_mov_b32_e32 v87, v0
	v_mov_b32_e32 v88, v0
	v_mov_b32_e32 v89, v0
	v_mov_b32_e32 v90, v0
	v_mov_b32_e32 v91, v0
	v_mov_b32_e32 v92, v0
	v_mov_b32_e32 v93, v0
	v_mov_b32_e32 v94, v0
	v_mov_b32_e32 v95, v0
	v_mov_b32_e32 v32, v0
	v_mov_b32_e32 v33, v0
	v_mov_b32_e32 v34, v0
	v_mov_b32_e32 v35, v0
	v_mov_b32_e32 v36, v0
	v_mov_b32_e32 v37, v0
	v_mov_b32_e32 v38, v0
	v_mov_b32_e32 v39, v0
	v_mov_b32_e32 v40, v0
	v_mov_b32_e32 v41, v0
	v_mov_b32_e32 v42, v0
	v_mov_b32_e32 v43, v0
	v_mov_b32_e32 v44, v0
	v_mov_b32_e32 v45, v0
	v_mov_b32_e32 v46, v0
	v_mov_b32_e32 v47, v0
	v_mov_b32_e32 v48, v0
	v_mov_b32_e32 v49, v0
	v_mov_b32_e32 v50, v0
	v_mov_b32_e32 v51, v0
	v_mov_b32_e32 v52, v0
	v_mov_b32_e32 v53, v0
	v_mov_b32_e32 v54, v0
	v_mov_b32_e32 v55, v0
	v_mov_b32_e32 v56, v0
	v_mov_b32_e32 v57, v0
	v_mov_b32_e32 v58, v0
	v_mov_b32_e32 v59, v0
	v_mov_b32_e32 v60, v0
	v_mov_b32_e32 v61, v0
	v_mov_b32_e32 v62, v0
	v_mov_b32_e32 v63, v0
	v_mov_b32_e32 v96, v0
	v_mov_b32_e32 v97, v0
	v_mov_b32_e32 v98, v0
	v_mov_b32_e32 v99, v0
	v_mov_b32_e32 v100, v0
	v_mov_b32_e32 v101, v0
	v_mov_b32_e32 v102, v0
	v_mov_b32_e32 v103, v0
	v_mov_b32_e32 v104, v0
	v_mov_b32_e32 v105, v0
	v_mov_b32_e32 v106, v0
	v_mov_b32_e32 v107, v0
	v_mov_b32_e32 v108, v0
	v_mov_b32_e32 v109, v0
	v_mov_b32_e32 v110, v0
	v_mov_b32_e32 v111, v0
	v_mov_b32_e32 v112, v0
	v_mov_b32_e32 v113, v0
	v_mov_b32_e32 v114, v0
	v_mov_b32_e32 v115, v0
	v_mov_b32_e32 v116, v0
	v_mov_b32_e32 v117, v0
	v_mov_b32_e32 v118, v0
	v_mov_b32_e32 v119, v0
	v_mov_b32_e32 v120, v0
	v_mov_b32_e32 v121, v0
	v_mov_b32_e32 v122, v0
	v_mov_b32_e32 v123, v0
	v_mov_b32_e32 v124, v0
	v_mov_b32_e32 v125, v0
	v_mov_b32_e32 v126, v0
	v_mov_b32_e32 v127, v0
	v_add_u32_e32 v250, 0x10000, v214
	v_add_u32_e32 v251, 0x14000, v214
	v_add_u32_e32 v252, 0x18000, v214
	v_add_u32_e32 v253, 0x1c000, v214
.LBB0_1335:
	s_add_u32 s24, s4, 0xfff00080
	s_addc_u32 s25, s5, -1
	s_add_i32 s62, 0, 0x10000
	s_cmp_eq_u32 s59, 60
	s_cselect_b32 s27, s17, s25
	s_cselect_b32 s26, s19, s24
	s_cselect_b32 s25, s11, s58
	s_cselect_b32 s24, s23, s33
	s_add_i32 s64, 0, 0x14000
	ds_read_b128 v[128:131], v250
	ds_read_b128 v[132:135], v250 offset:1024
	ds_read_b128 v[136:139], v250 offset:2048
	ds_read_b128 v[140:143], v250 offset:3072
	ds_read_b128 v[144:147], v251
	ds_read_b128 v[148:151], v251 offset:1024
	ds_read_b128 v[152:155], v251 offset:2048
	ds_read_b128 v[156:159], v251 offset:3072
	s_add_i32 m0, s38, 0xc000
	ds_read_b128 v[160:163], v215
	ds_read_b128 v[164:167], v215 offset:1024
	ds_read_b128 v[178:181], v215 offset:2048
	ds_read_b128 v[182:185], v215 offset:3072
	ds_read_b128 v[186:189], v215 offset:4096
	ds_read_b128 v[204:207], v215 offset:5120
	ds_read_b128 v[208:211], v215 offset:6144
	ds_read_b128 v[216:219], v215 offset:7168
	global_load_lds_dwordx4 v174, s[4:5]
	s_add_i32 m0, s38, 0xe000
	s_nop 0
	global_load_lds_dwordx4 v176, s[4:5]
	s_waitcnt vmcnt(8)
	s_waitcnt lgkmcnt(0)
	s_barrier
; #define PG8_STAGE(bufoff, gbase, voff) do { _Pragma("unroll") for (int _i = 0; _i < 2; ++_i) \
;         __builtin_amdgcn_global_load_lds((const unsigned*)((const char*)(gbase) + (voff)[_i]), (LAS unsigned*)(lds + (bufoff) + ldsw + _i * 8192), 16, 0, 0); } while (0)
; #define PG8_LDA(dst, b, h) do { _Pragma("unroll") for (int m = 0; m < 4; ++m) _Pragma("unroll") for (int k = 0; k < 2; ++k) dst[m][k] = *(const LAS bf16x8*)(lds + PG8_SA(b, h) + aoff + m * 2048 + k * 1024); } while (0)
; #define PG8_MMA(ai, bj, At, Bt) do { __builtin_amdgcn_s_setprio(1); _Pragma("unroll") for (int m = 0; m < 4; ++m) _Pragma("unroll") for (int n = 0; n < 2; ++n) _Pragma("unroll") for (int k = 0; k < 2; ++k) \
;         acc[ai][bj][m][n] = __builtin_amdgcn_mfma_f32_16x16x32_bf16(Bt[n][k], At[m][k], acc[ai][bj][m][n], 0, 0, 0); __builtin_amdgcn_s_setprio(0); } while (0)
; #define PG8_WAIT_V(n) asm volatile("s_waitcnt vmcnt(" #n ")" ::: "memory")
; #define PG8_WAIT_L(n) asm volatile("s_waitcnt lgkmcnt(" #n ")" ::: "memory")
; #define PG8_BAR __builtin_amdgcn_s_barrier()
; #define PG8_SCHED __builtin_amdgcn_sched_barrier(0)
; template <class EpiT, class Sched>
; __device__ __forceinline__ void gemm_phase(LAS unsigned char* lds, const Gemm g, const Sched& S, const EpiT& E, int wv) {
;     ...
;             PG8_WAIT_V(8); PG8_WAIT_L(0); PG8_BAR; PG8_MMA(0, 0, At, B0); PG8_MMA(0, 1, At, B1); PG8_BAR; PG8_SCHED;
;             PG8_LDA(At, 0, 1); PG8_STAGE(PG8_SB(0, 0), b2, voffB); PG8_STAGE(PG8_SB(0, 1), b2 + hstepB, voffB); PG8_STAGE(PG8_SA(0, 0), a2, voffA);
;             PG8_WAIT_V(8); PG8_WAIT_L(0); PG8_BAR; PG8_MMA(1, 0, At, B0); PG8_MMA(1, 1, At, B1); PG8_BAR; PG8_SCHED;
	s_setprio 1
	s_waitcnt lgkmcnt(0)
	v_mfma_f32_16x16x32_bf16 v[124:127], v[128:131], v[160:163], v[124:127]
	v_mfma_f32_16x16x32_bf16 v[120:123], v[136:139], v[160:163], v[120:123]
	v_mfma_f32_16x16x32_bf16 v[116:119], v[128:131], v[178:181], v[116:119]
	v_mfma_f32_16x16x32_bf16 v[112:115], v[136:139], v[178:181], v[112:115]
	v_mfma_f32_16x16x32_bf16 v[108:111], v[128:131], v[186:189], v[108:111]
	v_mfma_f32_16x16x32_bf16 v[104:107], v[136:139], v[186:189], v[104:107]
	v_mfma_f32_16x16x32_bf16 v[100:103], v[128:131], v[208:211], v[100:103]
	v_mfma_f32_16x16x32_bf16 v[96:99], v[136:139], v[208:211], v[96:99]
	v_mfma_f32_16x16x32_bf16 v[124:127], v[132:135], v[164:167], v[124:127]
	v_mfma_f32_16x16x32_bf16 v[120:123], v[140:143], v[164:167], v[120:123]
	v_mfma_f32_16x16x32_bf16 v[116:119], v[132:135], v[182:185], v[116:119]
	v_mfma_f32_16x16x32_bf16 v[112:115], v[140:143], v[182:185], v[112:115]
	v_mfma_f32_16x16x32_bf16 v[108:111], v[132:135], v[204:207], v[108:111]
	v_mfma_f32_16x16x32_bf16 v[104:107], v[140:143], v[204:207], v[104:107]
	v_mfma_f32_16x16x32_bf16 v[100:103], v[132:135], v[216:219], v[100:103]
	v_mfma_f32_16x16x32_bf16 v[96:99], v[140:143], v[216:219], v[96:99]
	s_setprio 0
	s_setprio 1
	v_mfma_f32_16x16x32_bf16 v[60:63], v[144:147], v[160:163], v[60:63]
	v_mfma_f32_16x16x32_bf16 v[56:59], v[152:155], v[160:163], v[56:59]
	v_mfma_f32_16x16x32_bf16 v[52:55], v[144:147], v[178:181], v[52:55]
	v_mfma_f32_16x16x32_bf16 v[48:51], v[152:155], v[178:181], v[48:51]
	v_mfma_f32_16x16x32_bf16 v[44:47], v[144:147], v[186:189], v[44:47]
	v_mfma_f32_16x16x32_bf16 v[40:43], v[152:155], v[186:189], v[40:43]
	v_mfma_f32_16x16x32_bf16 v[36:39], v[144:147], v[208:211], v[36:39]
	v_mfma_f32_16x16x32_bf16 v[32:35], v[152:155], v[208:211], v[32:35]
	v_mfma_f32_16x16x32_bf16 v[60:63], v[148:151], v[164:167], v[60:63]
	v_mfma_f32_16x16x32_bf16 v[56:59], v[156:159], v[164:167], v[56:59]
	v_mfma_f32_16x16x32_bf16 v[52:55], v[148:151], v[182:185], v[52:55]
	v_mfma_f32_16x16x32_bf16 v[48:51], v[156:159], v[182:185], v[48:51]
	v_mfma_f32_16x16x32_bf16 v[44:47], v[148:151], v[204:207], v[44:47]
	v_mfma_f32_16x16x32_bf16 v[40:43], v[156:159], v[204:207], v[40:43]
	v_mfma_f32_16x16x32_bf16 v[36:39], v[148:151], v[216:219], v[36:39]
	v_mfma_f32_16x16x32_bf16 v[32:35], v[156:159], v[216:219], v[32:35]
	s_setprio 0
	s_barrier
	s_add_i32 s62, s62, s37
	s_add_u32 s72, s24, s92
	s_addc_u32 s73, s25, s93
	s_mov_b32 m0, s62
	ds_read_b128 v[160:163], v215 offset:16384
	ds_read_b128 v[164:167], v215 offset:17408
	ds_read_b128 v[178:181], v215 offset:18432
	ds_read_b128 v[182:185], v215 offset:19456
	ds_read_b128 v[186:189], v215 offset:20480
	ds_read_b128 v[204:207], v215 offset:21504
	ds_read_b128 v[208:211], v215 offset:22528
	ds_read_b128 v[216:219], v215 offset:23552
	global_load_lds_dwordx4 v192, s[24:25]
	s_add_i32 m0, s62, 0x2000
	s_add_u32 s62, s24, 0x100000
	s_addc_u32 s63, s25, 0
	s_add_i32 s64, s64, s37
	global_load_lds_dwordx4 v172, s[24:25]
	s_mov_b32 m0, s64
	s_nop 0
	global_load_lds_dwordx4 v192, s[62:63]
	s_add_i32 m0, s64, 0x2000
	s_nop 0
	global_load_lds_dwordx4 v172, s[62:63]
	s_add_u32 s98, s26, s92
	s_addc_u32 s99, s27, s93
	s_mov_b32 m0, s38
	s_nop 0
	global_load_lds_dwordx4 v168, s[26:27]
	s_mov_b32 m0, s39
	s_nop 0
	global_load_lds_dwordx4 v170, s[26:27]
	s_waitcnt vmcnt(8)
	s_waitcnt lgkmcnt(0)
	s_barrier
	s_setprio 1
	s_waitcnt lgkmcnt(0)
	v_mfma_f32_16x16x32_bf16 v[92:95], v[128:131], v[160:163], v[92:95]
	v_mfma_f32_16x16x32_bf16 v[88:91], v[136:139], v[160:163], v[88:91]
	v_mfma_f32_16x16x32_bf16 v[84:87], v[128:131], v[178:181], v[84:87]
	v_mfma_f32_16x16x32_bf16 v[80:83], v[136:139], v[178:181], v[80:83]
	v_mfma_f32_16x16x32_bf16 v[76:79], v[128:131], v[186:189], v[76:79]
	v_mfma_f32_16x16x32_bf16 v[72:75], v[136:139], v[186:189], v[72:75]
	v_mfma_f32_16x16x32_bf16 v[68:71], v[128:131], v[208:211], v[68:71]
	v_mfma_f32_16x16x32_bf16 v[64:67], v[136:139], v[208:211], v[64:67]
	v_mfma_f32_16x16x32_bf16 v[92:95], v[132:135], v[164:167], v[92:95]
	v_mfma_f32_16x16x32_bf16 v[88:91], v[140:143], v[164:167], v[88:91]
	v_mfma_f32_16x16x32_bf16 v[84:87], v[132:135], v[182:185], v[84:87]
	v_mfma_f32_16x16x32_bf16 v[80:83], v[140:143], v[182:185], v[80:83]
	v_mfma_f32_16x16x32_bf16 v[76:79], v[132:135], v[204:207], v[76:79]
	v_mfma_f32_16x16x32_bf16 v[72:75], v[140:143], v[204:207], v[72:75]
	v_mfma_f32_16x16x32_bf16 v[68:71], v[132:135], v[216:219], v[68:71]
	v_mfma_f32_16x16x32_bf16 v[64:67], v[140:143], v[216:219], v[64:67]
	s_setprio 0
	s_setprio 1
	v_mfma_f32_16x16x32_bf16 v[28:31], v[144:147], v[160:163], v[28:31]
	v_mfma_f32_16x16x32_bf16 v[24:27], v[152:155], v[160:163], v[24:27]
	v_mfma_f32_16x16x32_bf16 v[20:23], v[144:147], v[178:181], v[20:23]
	v_mfma_f32_16x16x32_bf16 v[16:19], v[152:155], v[178:181], v[16:19]
	v_mfma_f32_16x16x32_bf16 v[12:15], v[144:147], v[186:189], v[12:15]
	v_mfma_f32_16x16x32_bf16 v[8:11], v[152:155], v[186:189], v[8:11]
	v_mfma_f32_16x16x32_bf16 v[4:7], v[144:147], v[208:211], v[4:7]
	v_mfma_f32_16x16x32_bf16 v[0:3], v[152:155], v[208:211], v[0:3]
	v_mfma_f32_16x16x32_bf16 v[28:31], v[148:151], v[164:167], v[28:31]
	v_mfma_f32_16x16x32_bf16 v[24:27], v[156:159], v[164:167], v[24:27]
	v_mfma_f32_16x16x32_bf16 v[20:23], v[148:151], v[182:185], v[20:23]
	v_mfma_f32_16x16x32_bf16 v[16:19], v[156:159], v[182:185], v[16:19]
	v_mfma_f32_16x16x32_bf16 v[12:15], v[148:151], v[204:207], v[12:15]
	v_mfma_f32_16x16x32_bf16 v[8:11], v[156:159], v[204:207], v[8:11]
	v_mfma_f32_16x16x32_bf16 v[4:7], v[148:151], v[216:219], v[4:7]
	v_mfma_f32_16x16x32_bf16 v[0:3], v[156:159], v[216:219], v[0:3]
	s_setprio 0
	s_barrier
; #define PG8_STAGE(bufoff, gbase, voff) do { _Pragma("unroll") for (int _i = 0; _i < 2; ++_i) \
;         __builtin_amdgcn_global_load_lds((const unsigned*)((const char*)(gbase) + (voff)[_i]), (LAS unsigned*)(lds + (bufoff) + ldsw + _i * 8192), 16, 0, 0); } while (0)
; #define PG8_LDA(dst, b, h) do { _Pragma("unroll") for (int m = 0; m < 4; ++m) _Pragma("unroll") for (int k = 0; k < 2; ++k) dst[m][k] = *(const LAS bf16x8*)(lds + PG8_SA(b, h) + aoff + m * 2048 + k * 1024); } while (0)
; #define PG8_LDB(dst, b, h) do { _Pragma("unroll") for (int n = 0; n < 2; ++n) _Pragma("unroll") for (int k = 0; k < 2; ++k) dst[n][k] = *(const LAS bf16x8*)(lds + PG8_SB(b, h) + boff + n * 2048 + k * 1024); } while (0)
; #define PG8_MMA(ai, bj, At, Bt) do { __builtin_amdgcn_s_setprio(1); _Pragma("unroll") for (int m = 0; m < 4; ++m) _Pragma("unroll") for (int n = 0; n < 2; ++n) _Pragma("unroll") for (int k = 0; k < 2; ++k) \
;         acc[ai][bj][m][n] = __builtin_amdgcn_mfma_f32_16x16x32_bf16(Bt[n][k], At[m][k], acc[ai][bj][m][n], 0, 0, 0); __builtin_amdgcn_s_setprio(0); } while (0)
; #define PG8_WAIT_V(n) asm volatile("s_waitcnt vmcnt(" #n ")" ::: "memory")
; #define PG8_WAIT_L(n) asm volatile("s_waitcnt lgkmcnt(" #n ")" ::: "memory")
; #define PG8_BAR __builtin_amdgcn_s_barrier()
; #define PG8_SCHED __builtin_amdgcn_sched_barrier(0)
; template <class EpiT, class Sched>
; __device__ __forceinline__ void gemm_phase(LAS unsigned char* lds, const Gemm g, const Sched& S, const EpiT& E, int wv) {
;     ...
;             PG8_LDB(B0, 1, 0); PG8_LDB(B1, 1, 1); PG8_SCHED; PG8_LDA(At, 1, 0); PG8_STAGE(PG8_SA(0, 1), a2 + hstepA, voffA);
;             PG8_WAIT_V(8); PG8_WAIT_L(0); PG8_BAR; PG8_MMA(0, 0, At, B0); PG8_MMA(0, 1, At, B1); PG8_BAR; PG8_SCHED;
;             PG8_LDA(At, 1, 1); PG8_STAGE(PG8_SB(1, 0), b3, voffB); PG8_STAGE(PG8_SB(1, 1), b3 + hstepB, voffB); PG8_STAGE(PG8_SA(1, 0), a3, voffA);
;             PG8_WAIT_V(8); PG8_WAIT_L(0); PG8_BAR; PG8_MMA(1, 0, At, B0); PG8_MMA(1, 1, At, B1); PG8_BAR; PG8_SCHED;
;         }
;         if (wr == 0) PG8_BAR;
	s_add_i32 s62, 0, 0x18000
	s_add_i32 s63, 0, 0x1c000
	ds_read_b128 v[128:131], v252
	ds_read_b128 v[132:135], v252 offset:1024
	ds_read_b128 v[136:139], v252 offset:2048
	ds_read_b128 v[140:143], v252 offset:3072
	ds_read_b128 v[144:147], v253
	ds_read_b128 v[148:151], v253 offset:1024
	ds_read_b128 v[152:155], v253 offset:2048
	ds_read_b128 v[156:159], v253 offset:3072
	s_add_u32 s26, s26, 0x100000
	s_addc_u32 s27, s27, 0
	s_mov_b32 m0, s40
	ds_read_b128 v[160:163], v215 offset:32768
	ds_read_b128 v[164:167], v215 offset:33792
	ds_read_b128 v[178:181], v215 offset:34816
	ds_read_b128 v[182:185], v215 offset:35840
	ds_read_b128 v[186:189], v215 offset:36864
	ds_read_b128 v[204:207], v215 offset:37888
	ds_read_b128 v[208:211], v215 offset:38912
	ds_read_b128 v[216:219], v215 offset:39936
	global_load_lds_dwordx4 v168, s[26:27]
	s_mov_b32 m0, s41
	s_nop 0
	global_load_lds_dwordx4 v170, s[26:27]
	s_waitcnt vmcnt(8)
	s_waitcnt lgkmcnt(0)
	s_barrier
	s_setprio 1
	s_waitcnt lgkmcnt(0)
	v_mfma_f32_16x16x32_bf16 v[124:127], v[128:131], v[160:163], v[124:127]
	v_mfma_f32_16x16x32_bf16 v[120:123], v[136:139], v[160:163], v[120:123]
	v_mfma_f32_16x16x32_bf16 v[116:119], v[128:131], v[178:181], v[116:119]
	v_mfma_f32_16x16x32_bf16 v[112:115], v[136:139], v[178:181], v[112:115]
	v_mfma_f32_16x16x32_bf16 v[108:111], v[128:131], v[186:189], v[108:111]
	v_mfma_f32_16x16x32_bf16 v[104:107], v[136:139], v[186:189], v[104:107]
	v_mfma_f32_16x16x32_bf16 v[100:103], v[128:131], v[208:211], v[100:103]
	v_mfma_f32_16x16x32_bf16 v[96:99], v[136:139], v[208:211], v[96:99]
	v_mfma_f32_16x16x32_bf16 v[124:127], v[132:135], v[164:167], v[124:127]
	v_mfma_f32_16x16x32_bf16 v[120:123], v[140:143], v[164:167], v[120:123]
	v_mfma_f32_16x16x32_bf16 v[116:119], v[132:135], v[182:185], v[116:119]
	v_mfma_f32_16x16x32_bf16 v[112:115], v[140:143], v[182:185], v[112:115]
	v_mfma_f32_16x16x32_bf16 v[108:111], v[132:135], v[204:207], v[108:111]
	v_mfma_f32_16x16x32_bf16 v[104:107], v[140:143], v[204:207], v[104:107]
	v_mfma_f32_16x16x32_bf16 v[100:103], v[132:135], v[216:219], v[100:103]
	v_mfma_f32_16x16x32_bf16 v[96:99], v[140:143], v[216:219], v[96:99]
	s_setprio 0
	s_setprio 1
	v_mfma_f32_16x16x32_bf16 v[60:63], v[144:147], v[160:163], v[60:63]
	v_mfma_f32_16x16x32_bf16 v[56:59], v[152:155], v[160:163], v[56:59]
	v_mfma_f32_16x16x32_bf16 v[52:55], v[144:147], v[178:181], v[52:55]
	v_mfma_f32_16x16x32_bf16 v[48:51], v[152:155], v[178:181], v[48:51]
	v_mfma_f32_16x16x32_bf16 v[44:47], v[144:147], v[186:189], v[44:47]
	v_mfma_f32_16x16x32_bf16 v[40:43], v[152:155], v[186:189], v[40:43]
	v_mfma_f32_16x16x32_bf16 v[36:39], v[144:147], v[208:211], v[36:39]
	v_mfma_f32_16x16x32_bf16 v[32:35], v[152:155], v[208:211], v[32:35]
	v_mfma_f32_16x16x32_bf16 v[60:63], v[148:151], v[164:167], v[60:63]
	v_mfma_f32_16x16x32_bf16 v[56:59], v[156:159], v[164:167], v[56:59]
	v_mfma_f32_16x16x32_bf16 v[52:55], v[148:151], v[182:185], v[52:55]
	v_mfma_f32_16x16x32_bf16 v[48:51], v[156:159], v[182:185], v[48:51]
	v_mfma_f32_16x16x32_bf16 v[44:47], v[148:151], v[204:207], v[44:47]
	v_mfma_f32_16x16x32_bf16 v[40:43], v[156:159], v[204:207], v[40:43]
	v_mfma_f32_16x16x32_bf16 v[36:39], v[148:151], v[216:219], v[36:39]
	v_mfma_f32_16x16x32_bf16 v[32:35], v[156:159], v[216:219], v[32:35]
	s_setprio 0
	s_barrier
	s_add_i32 s26, s62, s37
	s_mov_b32 m0, s26
	ds_read_b128 v[160:163], v215 offset:49152
	ds_read_b128 v[164:167], v215 offset:50176
	ds_read_b128 v[178:181], v215 offset:51200
	ds_read_b128 v[182:185], v215 offset:52224
	ds_read_b128 v[186:189], v215 offset:53248
	ds_read_b128 v[204:207], v215 offset:54272
	ds_read_b128 v[208:211], v215 offset:55296
	ds_read_b128 v[216:219], v215 offset:56320
	global_load_lds_dwordx4 v192, s[72:73]
	s_add_i32 m0, s26, 0x2000
	s_add_u32 s24, s24, 0x100080
	s_addc_u32 s25, s25, 0
	s_add_i32 s26, s63, s37
	global_load_lds_dwordx4 v172, s[72:73]
	s_mov_b32 m0, s26
	s_nop 0
	global_load_lds_dwordx4 v192, s[24:25]
	s_add_i32 m0, s26, 0x2000
	s_nop 0
	global_load_lds_dwordx4 v172, s[24:25]
	s_mov_b32 m0, s50
	s_nop 0
	global_load_lds_dwordx4 v168, s[98:99]
	s_mov_b32 m0, s51
	s_nop 0
	global_load_lds_dwordx4 v170, s[98:99]
	s_waitcnt vmcnt(8)
	s_waitcnt lgkmcnt(0)
	s_barrier
	s_setprio 1
	s_waitcnt lgkmcnt(0)
	v_mfma_f32_16x16x32_bf16 v[92:95], v[128:131], v[160:163], v[92:95]
	v_mfma_f32_16x16x32_bf16 v[88:91], v[136:139], v[160:163], v[88:91]
	v_mfma_f32_16x16x32_bf16 v[84:87], v[128:131], v[178:181], v[84:87]
	v_mfma_f32_16x16x32_bf16 v[80:83], v[136:139], v[178:181], v[80:83]
	v_mfma_f32_16x16x32_bf16 v[76:79], v[128:131], v[186:189], v[76:79]
	v_mfma_f32_16x16x32_bf16 v[72:75], v[136:139], v[186:189], v[72:75]
	v_mfma_f32_16x16x32_bf16 v[68:71], v[128:131], v[208:211], v[68:71]
	v_mfma_f32_16x16x32_bf16 v[64:67], v[136:139], v[208:211], v[64:67]
	v_mfma_f32_16x16x32_bf16 v[92:95], v[132:135], v[164:167], v[92:95]
	v_mfma_f32_16x16x32_bf16 v[88:91], v[140:143], v[164:167], v[88:91]
	v_mfma_f32_16x16x32_bf16 v[84:87], v[132:135], v[182:185], v[84:87]
	v_mfma_f32_16x16x32_bf16 v[80:83], v[140:143], v[182:185], v[80:83]
	v_mfma_f32_16x16x32_bf16 v[76:79], v[132:135], v[204:207], v[76:79]
	v_mfma_f32_16x16x32_bf16 v[72:75], v[140:143], v[204:207], v[72:75]
	v_mfma_f32_16x16x32_bf16 v[68:71], v[132:135], v[216:219], v[68:71]
	v_mfma_f32_16x16x32_bf16 v[64:67], v[140:143], v[216:219], v[64:67]
	s_setprio 0
	s_setprio 1
	v_mfma_f32_16x16x32_bf16 v[28:31], v[144:147], v[160:163], v[28:31]
	v_mfma_f32_16x16x32_bf16 v[24:27], v[152:155], v[160:163], v[24:27]
	v_mfma_f32_16x16x32_bf16 v[20:23], v[144:147], v[178:181], v[20:23]
	v_mfma_f32_16x16x32_bf16 v[16:19], v[152:155], v[178:181], v[16:19]
	v_mfma_f32_16x16x32_bf16 v[12:15], v[144:147], v[186:189], v[12:15]
	v_mfma_f32_16x16x32_bf16 v[8:11], v[152:155], v[186:189], v[8:11]
	v_mfma_f32_16x16x32_bf16 v[4:7], v[144:147], v[208:211], v[4:7]
	v_mfma_f32_16x16x32_bf16 v[0:3], v[152:155], v[208:211], v[0:3]
	v_mfma_f32_16x16x32_bf16 v[28:31], v[148:151], v[164:167], v[28:31]
	v_mfma_f32_16x16x32_bf16 v[24:27], v[156:159], v[164:167], v[24:27]
	v_mfma_f32_16x16x32_bf16 v[20:23], v[148:151], v[182:185], v[20:23]
	v_mfma_f32_16x16x32_bf16 v[16:19], v[156:159], v[182:185], v[16:19]
	v_mfma_f32_16x16x32_bf16 v[12:15], v[148:151], v[204:207], v[12:15]
	v_mfma_f32_16x16x32_bf16 v[8:11], v[156:159], v[204:207], v[8:11]
	v_mfma_f32_16x16x32_bf16 v[4:7], v[148:151], v[216:219], v[4:7]
	v_mfma_f32_16x16x32_bf16 v[0:3], v[156:159], v[216:219], v[0:3]
	s_setprio 0
	s_barrier
	s_add_i32 s59, s59, 2
	s_add_u32 s4, s4, 0x100
	s_addc_u32 s5, s5, 0
	s_add_u32 s33, s33, 0x100
	s_addc_u32 s58, s58, 0
	s_cmp_gt_u32 s59, 61
	s_cbranch_scc0 .LBB0_1335
	s_and_b64 vcc, exec, s[14:15]
	s_cbranch_vccz .LBB0_1338
	s_barrier
